# prio_young
# speedup vs baseline: 1.0056x; 1.0056x over previous
; __device__ __forceinline__ unsigned xb_ld(unsigned* p) { return __hip_atomic_load(p, __ATOMIC_RELAXED, __HIP_MEMORY_SCOPE_AGENT); }
; __device__ __forceinline__ unsigned xb_add(unsigned* p, unsigned v) { return __hip_atomic_fetch_add(p, v, __ATOMIC_RELAXED, __HIP_MEMORY_SCOPE_AGENT); }
; __device__ __forceinline__ unsigned xb_xcc_id() { return (unsigned)__builtin_amdgcn_s_getreg((3 << 11) | 20) & 0xFu; }
; #define XB_SPIN(cond, bar) do { unsigned _sp = 0; while (cond) { __builtin_amdgcn_s_sleep(1); \
;     if ((++_sp & 255u) == 0u) { if (xb_ld(&(bar)[XB_TMO])) break; if (_sp > XB_SPIN_CAP) { atomicAdd(&(bar)[XB_TMO], 1u); break; } } } } while (0)
;   __shared__ uint4 sh;
;   if (tid == 0) {
;     const unsigned x = xb_xcc_id();
;     xb_add(&bar[XB_XCNT(x)], 1u);
;     __threadfence();
;     const unsigned G = gridDim.x;
;     const unsigned old = xb_add(&bar[XB_CNT], 1u), gen = old / G;
;     if (old + 1u == (gen + 1u) * G) xb_add(&bar[XB_GEN], 1u); else XB_SPIN(xb_ld(&bar[XB_GEN]) == gen, bar);
.LBB0_2:
	s_or_b64 exec, exec, s[2:3]
	s_add_u32 s2, s96, 0x2f001000
	v_readlane_b32 s4, v252, 14
	s_addc_u32 s3, s97, 0
	v_mbcnt_lo_u32_b32 v1, -1, 0
	v_mbcnt_hi_u32_b32 v1, -1, v1
	s_and_b32 s33, s4, 0xffffffc0
	s_cmp_lt_u32 s33, 0x100
	s_cbranch_scc1 .Lprio_skip
	s_setprio 1
.Lprio_skip:
	v_or_b32_e32 v1, s33, v1
	v_cmp_eq_u32_e32 vcc, 0, v1
	s_and_saveexec_b64 s[4:5], vcc
	s_cbranch_execz .LBB0_22
	s_getreg_b32 s6, hwreg(HW_REG_XCC_ID, 0, 4)
	s_mov_b64 s[8:9], exec
	s_and_b32 s26, s6, 15
	s_lshl_b32 s6, s26, 8
	v_mbcnt_lo_u32_b32 v1, s8, 0
	s_add_u32 s6, s2, s6
	v_mbcnt_hi_u32_b32 v1, s9, v1
	s_addc_u32 s7, s3, 0
	v_cmp_eq_u32_e32 vcc, 0, v1
	s_and_saveexec_b64 s[10:11], vcc
	s_cbranch_execz .LBB0_5
	s_bcnt1_i32_b64 s8, s[8:9]
	v_mov_b32_e32 v1, 0
	v_mov_b32_e32 v2, s8
	global_atomic_add v1, v2, s[6:7] offset:1024

; #define WAIT_L(n) asm volatile("s_waitcnt lgkmcnt(" #n ")" ::: "memory")
; #define BAR __builtin_amdgcn_s_barrier()
; #define SCHED __builtin_amdgcn_sched_barrier(0)
; __device__ __forceinline__ void mainloop_8phase(const u16* __restrict__ A, const u16* __restrict__ Bt, int K,
;                                                 f32x4 (&acc)[2][2][4][2], int wid_s, int ld) {
;     ...
;   for (int t = 0; t < nt - 2; t += 2) {
;     LDB(B0, 0, 0); SCHED; LDA(At, 0, 0); STAGE(SA(1, 1), A, brow + G_HALF, t + 1);
;     WAIT_L(8); BAR; WAIT_L(0); MMA(0, 0, At, B0); BAR; SCHED;
;     LDB(B1, 0, 1); STAGE(SB(0, 0), Bt, bcol, t + 2);
;     BAR; WAIT_L(0); MMA(0, 1, At, B1); BAR;
;     LDA(At, 0, 1); STAGE(SA(0, 0), A, brow, t + 2);
;     BAR; WAIT_L(0); MMA(1, 0, At, B0); BAR; SCHED;
.LBB0_58:
	ds_read_b128 v[156:159], v155
	ds_read_b128 v[160:163], v155 offset:1024
	ds_read_b128 v[164:167], v155 offset:2048
	ds_read_b128 v[168:171], v155 offset:3072
	v_readfirstlane_b32 s7, v145
	s_add_i32 s6, s1, 0xffffff00
	s_mov_b32 m0, s7
	v_readfirstlane_b32 s7, v144
	ds_read_b128 v[172:175], v133
	ds_read_b128 v[176:179], v133 offset:1024
	ds_read_b128 v[180:183], v132
	ds_read_b128 v[184:187], v132 offset:1024
	ds_read_b128 v[188:191], v131
	ds_read_b128 v[192:195], v131 offset:1024
	ds_read_b128 v[196:199], v130
	ds_read_b128 v[200:203], v130 offset:1024
	buffer_load_dwordx4 v137, s[88:91], s6 offen lds
	s_mov_b32 m0, s7
	s_nop 0
	buffer_load_dwordx4 v136, s[88:91], s6 offen lds
	s_waitcnt lgkmcnt(8)
	s_barrier
	s_waitcnt lgkmcnt(0)
	s_waitcnt lgkmcnt(7)
	v_mfma_f32_16x16x32_bf16 v[126:129], v[172:175], v[156:159], v[126:129]
	v_mfma_f32_16x16x32_bf16 v[122:125], v[172:175], v[164:167], v[122:125]
	s_waitcnt lgkmcnt(5)
	v_mfma_f32_16x16x32_bf16 v[118:121], v[180:183], v[156:159], v[118:121]
	v_mfma_f32_16x16x32_bf16 v[114:117], v[180:183], v[164:167], v[114:117]
	s_waitcnt lgkmcnt(3)
	v_mfma_f32_16x16x32_bf16 v[110:113], v[188:191], v[156:159], v[110:113]
	v_mfma_f32_16x16x32_bf16 v[106:109], v[188:191], v[164:167], v[106:109]
	s_waitcnt lgkmcnt(1)
	v_mfma_f32_16x16x32_bf16 v[102:105], v[196:199], v[156:159], v[102:105]
	v_mfma_f32_16x16x32_bf16 v[98:101], v[196:199], v[164:167], v[98:101]
	v_mfma_f32_16x16x32_bf16 v[126:129], v[176:179], v[160:163], v[126:129]
	v_mfma_f32_16x16x32_bf16 v[122:125], v[176:179], v[168:171], v[122:125]
	v_mfma_f32_16x16x32_bf16 v[118:121], v[184:187], v[160:163], v[118:121]
	v_mfma_f32_16x16x32_bf16 v[114:117], v[184:187], v[168:171], v[114:117]
	v_mfma_f32_16x16x32_bf16 v[110:113], v[192:195], v[160:163], v[110:113]
	v_mfma_f32_16x16x32_bf16 v[106:109], v[192:195], v[168:171], v[106:109]
	s_waitcnt lgkmcnt(0)
	v_mfma_f32_16x16x32_bf16 v[102:105], v[200:203], v[160:163], v[102:105]
	v_mfma_f32_16x16x32_bf16 v[98:101], v[200:203], v[168:171], v[98:101]
	s_barrier
	v_readfirstlane_b32 s16, v148
	s_add_i32 s15, s1, 0xfff7ff80
	s_mov_b32 s6, s90
	s_mov_b32 s7, s91
	s_mov_b32 m0, s16
	v_readfirstlane_b32 s16, v149
	ds_read_b128 v[204:207], v147
	ds_read_b128 v[208:211], v147 offset:1024
	ds_read_b128 v[212:215], v147 offset:2048
	ds_read_b128 v[216:219], v147 offset:3072
	buffer_load_dwordx4 v137, s[4:7], s15 offen lds
	s_mov_b32 m0, s16
	s_nop 0
	buffer_load_dwordx4 v136, s[4:7], s15 offen lds
	s_barrier
	s_waitcnt lgkmcnt(0)
	s_waitcnt lgkmcnt(3)
	v_mfma_f32_16x16x32_bf16 v[94:97], v[172:175], v[204:207], v[94:97]
	s_waitcnt lgkmcnt(1)
	v_mfma_f32_16x16x32_bf16 v[90:93], v[172:175], v[212:215], v[90:93]
	v_mfma_f32_16x16x32_bf16 v[86:89], v[180:183], v[204:207], v[86:89]
	v_mfma_f32_16x16x32_bf16 v[82:85], v[180:183], v[212:215], v[82:85]
	v_mfma_f32_16x16x32_bf16 v[78:81], v[188:191], v[204:207], v[78:81]
	v_mfma_f32_16x16x32_bf16 v[74:77], v[188:191], v[212:215], v[74:77]
	v_mfma_f32_16x16x32_bf16 v[70:73], v[196:199], v[204:207], v[70:73]
	v_mfma_f32_16x16x32_bf16 v[66:69], v[196:199], v[212:215], v[66:69]
	v_mfma_f32_16x16x32_bf16 v[94:97], v[176:179], v[208:211], v[94:97]
	s_waitcnt lgkmcnt(0)
	v_mfma_f32_16x16x32_bf16 v[90:93], v[176:179], v[216:219], v[90:93]
	v_mfma_f32_16x16x32_bf16 v[86:89], v[184:187], v[208:211], v[86:89]
	v_mfma_f32_16x16x32_bf16 v[82:85], v[184:187], v[216:219], v[82:85]
	v_mfma_f32_16x16x32_bf16 v[78:81], v[192:195], v[208:211], v[78:81]
	v_mfma_f32_16x16x32_bf16 v[74:77], v[192:195], v[216:219], v[74:77]
	v_mfma_f32_16x16x32_bf16 v[70:73], v[200:203], v[208:211], v[70:73]
	v_mfma_f32_16x16x32_bf16 v[66:69], v[200:203], v[216:219], v[66:69]
	v_readfirstlane_b32 s16, v140
	s_mov_b32 m0, s16
	v_readfirstlane_b32 s16, v150
	s_barrier
	ds_read_b128 v[172:175], v133 offset:16384
	ds_read_b128 v[176:179], v133 offset:17408
	ds_read_b128 v[180:183], v132 offset:16384
	ds_read_b128 v[184:187], v132 offset:17408
	ds_read_b128 v[188:191], v131 offset:16384
	ds_read_b128 v[192:195], v131 offset:17408
	ds_read_b128 v[196:199], v130 offset:16384
	ds_read_b128 v[200:203], v130 offset:17408
	buffer_load_dwordx4 v137, s[88:91], s15 offen lds
	s_mov_b32 m0, s16
	s_nop 0
	buffer_load_dwordx4 v136, s[88:91], s15 offen lds
	s_barrier
	s_waitcnt lgkmcnt(0)
	s_waitcnt lgkmcnt(7)
	v_mfma_f32_16x16x32_bf16 v[62:65], v[172:175], v[156:159], v[62:65]
	v_mfma_f32_16x16x32_bf16 v[58:61], v[172:175], v[164:167], v[58:61]
	s_waitcnt lgkmcnt(5)
	v_mfma_f32_16x16x32_bf16 v[54:57], v[180:183], v[156:159], v[54:57]
	v_mfma_f32_16x16x32_bf16 v[50:53], v[180:183], v[164:167], v[50:53]
	s_waitcnt lgkmcnt(3)
	v_mfma_f32_16x16x32_bf16 v[46:49], v[188:191], v[156:159], v[46:49]
	v_mfma_f32_16x16x32_bf16 v[42:45], v[188:191], v[164:167], v[42:45]
	s_waitcnt lgkmcnt(1)
	v_mfma_f32_16x16x32_bf16 v[38:41], v[196:199], v[156:159], v[38:41]
	v_mfma_f32_16x16x32_bf16 v[34:37], v[196:199], v[164:167], v[34:37]
	v_mfma_f32_16x16x32_bf16 v[62:65], v[176:179], v[160:163], v[62:65]
	v_mfma_f32_16x16x32_bf16 v[58:61], v[176:179], v[168:171], v[58:61]
	v_mfma_f32_16x16x32_bf16 v[54:57], v[184:187], v[160:163], v[54:57]
	v_mfma_f32_16x16x32_bf16 v[50:53], v[184:187], v[168:171], v[50:53]
	v_mfma_f32_16x16x32_bf16 v[46:49], v[192:195], v[160:163], v[46:49]
	v_mfma_f32_16x16x32_bf16 v[42:45], v[192:195], v[168:171], v[42:45]
	s_waitcnt lgkmcnt(0)
	v_mfma_f32_16x16x32_bf16 v[38:41], v[200:203], v[160:163], v[38:41]
	v_mfma_f32_16x16x32_bf16 v[34:37], v[200:203], v[168:171], v[34:37]
	s_barrier
; #define WAIT_V(n) asm volatile("s_waitcnt vmcnt(" #n ")" ::: "memory")
; #define WAIT_L(n) asm volatile("s_waitcnt lgkmcnt(" #n ")" ::: "memory")
; #define BAR __builtin_amdgcn_s_barrier()
; #define SCHED __builtin_amdgcn_sched_barrier(0)
; __device__ __forceinline__ void mainloop_8phase(const u16* __restrict__ A, const u16* __restrict__ Bt, int K,
;                                                 f32x4 (&acc)[2][2][4][2], int wid_s, int ld) {
;     ...
;     STAGE(SB(0, 1), Bt, bcol + G_HALF, t + 2);
;     WAIT_V(6); BAR; MMA(1, 1, At, B1); BAR;
;     LDB(B0, 1, 0); SCHED; LDA(At, 1, 0); STAGE(SA(0, 1), A, brow + G_HALF, t + 2);
;     WAIT_L(8); BAR; WAIT_L(0); MMA(0, 0, At, B0); BAR; SCHED;
;     LDB(B1, 1, 1); STAGE(SB(1, 0), Bt, bcol, t + 3);
;     BAR; WAIT_L(0); MMA(0, 1, At, B1); BAR;
;     LDA(At, 1, 1); STAGE(SA(1, 0), A, brow, t + 3);
	v_readfirstlane_b32 s16, v151
	s_add_i32 s15, s1, 0xffffff80
	s_mov_b32 m0, s16
	v_readfirstlane_b32 s16, v152
	buffer_load_dwordx4 v137, s[4:7], s15 offen lds
	s_mov_b32 m0, s16
	s_nop 0
	buffer_load_dwordx4 v136, s[4:7], s15 offen lds
	s_waitcnt vmcnt(6)
	s_barrier
	v_mfma_f32_16x16x32_bf16 v[30:33], v[172:175], v[204:207], v[30:33]
	v_mfma_f32_16x16x32_bf16 v[26:29], v[172:175], v[212:215], v[26:29]
	v_mfma_f32_16x16x32_bf16 v[22:25], v[180:183], v[204:207], v[22:25]
	v_mfma_f32_16x16x32_bf16 v[18:21], v[180:183], v[212:215], v[18:21]
	v_mfma_f32_16x16x32_bf16 v[14:17], v[188:191], v[204:207], v[14:17]
	v_mfma_f32_16x16x32_bf16 v[10:13], v[188:191], v[212:215], v[10:13]
	v_mfma_f32_16x16x32_bf16 v[6:9], v[196:199], v[204:207], v[6:9]
	v_mfma_f32_16x16x32_bf16 v[2:5], v[196:199], v[212:215], v[2:5]
	v_mfma_f32_16x16x32_bf16 v[30:33], v[176:179], v[208:211], v[30:33]
	v_mfma_f32_16x16x32_bf16 v[26:29], v[176:179], v[216:219], v[26:29]
	v_mfma_f32_16x16x32_bf16 v[22:25], v[184:187], v[208:211], v[22:25]
	v_mfma_f32_16x16x32_bf16 v[18:21], v[184:187], v[216:219], v[18:21]
	v_mfma_f32_16x16x32_bf16 v[14:17], v[192:195], v[208:211], v[14:17]
	v_mfma_f32_16x16x32_bf16 v[10:13], v[192:195], v[216:219], v[10:13]
	v_mfma_f32_16x16x32_bf16 v[6:9], v[200:203], v[208:211], v[6:9]
	v_mfma_f32_16x16x32_bf16 v[2:5], v[200:203], v[216:219], v[2:5]
	s_barrier
	ds_read_b128 v[156:159], v135
	ds_read_b128 v[160:163], v135 offset:1024
	ds_read_b128 v[164:167], v135 offset:2048
	ds_read_b128 v[168:171], v135 offset:3072
	v_readfirstlane_b32 s16, v153
	s_mov_b32 m0, s16
	v_readfirstlane_b32 s16, v154
	ds_read_b128 v[172:175], v133 offset:32768
	ds_read_b128 v[176:179], v133 offset:33792
	ds_read_b128 v[180:183], v132 offset:32768
	ds_read_b128 v[184:187], v132 offset:33792
	ds_read_b128 v[188:191], v131 offset:32768
	ds_read_b128 v[192:195], v131 offset:33792
	ds_read_b128 v[196:199], v130 offset:32768
	ds_read_b128 v[200:203], v130 offset:33792
	buffer_load_dwordx4 v137, s[88:91], s15 offen lds
	s_mov_b32 m0, s16
	s_nop 0
	buffer_load_dwordx4 v136, s[88:91], s15 offen lds
	s_waitcnt lgkmcnt(8)
	s_barrier
	s_waitcnt lgkmcnt(0)
	s_waitcnt lgkmcnt(7)
	v_mfma_f32_16x16x32_bf16 v[126:129], v[172:175], v[156:159], v[126:129]
	v_mfma_f32_16x16x32_bf16 v[122:125], v[172:175], v[164:167], v[122:125]
	s_waitcnt lgkmcnt(5)
	v_mfma_f32_16x16x32_bf16 v[118:121], v[180:183], v[156:159], v[118:121]
	v_mfma_f32_16x16x32_bf16 v[114:117], v[180:183], v[164:167], v[114:117]
	s_waitcnt lgkmcnt(3)
	v_mfma_f32_16x16x32_bf16 v[110:113], v[188:191], v[156:159], v[110:113]
	v_mfma_f32_16x16x32_bf16 v[106:109], v[188:191], v[164:167], v[106:109]
	s_waitcnt lgkmcnt(1)
	v_mfma_f32_16x16x32_bf16 v[102:105], v[196:199], v[156:159], v[102:105]
	v_mfma_f32_16x16x32_bf16 v[98:101], v[196:199], v[164:167], v[98:101]
	v_mfma_f32_16x16x32_bf16 v[126:129], v[176:179], v[160:163], v[126:129]
	v_mfma_f32_16x16x32_bf16 v[122:125], v[176:179], v[168:171], v[122:125]
	v_mfma_f32_16x16x32_bf16 v[118:121], v[184:187], v[160:163], v[118:121]
	v_mfma_f32_16x16x32_bf16 v[114:117], v[184:187], v[168:171], v[114:117]
	v_mfma_f32_16x16x32_bf16 v[110:113], v[192:195], v[160:163], v[110:113]
	v_mfma_f32_16x16x32_bf16 v[106:109], v[192:195], v[168:171], v[106:109]
	s_waitcnt lgkmcnt(0)
	v_mfma_f32_16x16x32_bf16 v[102:105], v[200:203], v[160:163], v[102:105]
	v_mfma_f32_16x16x32_bf16 v[98:101], v[200:203], v[168:171], v[98:101]
	s_barrier
	v_readfirstlane_b32 s16, v138
	s_add_i32 s15, s1, 0xfff80000
	s_mov_b32 m0, s16
	v_readfirstlane_b32 s16, v139
	ds_read_b128 v[204:207], v134
	ds_read_b128 v[208:211], v134 offset:1024
	ds_read_b128 v[212:215], v134 offset:2048
	ds_read_b128 v[216:219], v134 offset:3072
	buffer_load_dwordx4 v137, s[4:7], s15 offen lds
	s_mov_b32 m0, s16
	s_nop 0
	buffer_load_dwordx4 v136, s[4:7], s15 offen lds
	s_barrier
	s_waitcnt lgkmcnt(0)
	s_waitcnt lgkmcnt(3)
	v_mfma_f32_16x16x32_bf16 v[94:97], v[172:175], v[204:207], v[94:97]
	s_waitcnt lgkmcnt(1)
	v_mfma_f32_16x16x32_bf16 v[90:93], v[172:175], v[212:215], v[90:93]
	v_mfma_f32_16x16x32_bf16 v[86:89], v[180:183], v[204:207], v[86:89]
	v_mfma_f32_16x16x32_bf16 v[82:85], v[180:183], v[212:215], v[82:85]
	v_mfma_f32_16x16x32_bf16 v[78:81], v[188:191], v[204:207], v[78:81]
	v_mfma_f32_16x16x32_bf16 v[74:77], v[188:191], v[212:215], v[74:77]
	v_mfma_f32_16x16x32_bf16 v[70:73], v[196:199], v[204:207], v[70:73]
	v_mfma_f32_16x16x32_bf16 v[66:69], v[196:199], v[212:215], v[66:69]
	v_mfma_f32_16x16x32_bf16 v[94:97], v[176:179], v[208:211], v[94:97]
	s_waitcnt lgkmcnt(0)
	v_mfma_f32_16x16x32_bf16 v[90:93], v[176:179], v[216:219], v[90:93]
	v_mfma_f32_16x16x32_bf16 v[86:89], v[184:187], v[208:211], v[86:89]
	v_mfma_f32_16x16x32_bf16 v[82:85], v[184:187], v[216:219], v[82:85]
	v_mfma_f32_16x16x32_bf16 v[78:81], v[192:195], v[208:211], v[78:81]
	v_mfma_f32_16x16x32_bf16 v[74:77], v[192:195], v[216:219], v[74:77]
	v_mfma_f32_16x16x32_bf16 v[70:73], v[200:203], v[208:211], v[70:73]
	v_mfma_f32_16x16x32_bf16 v[66:69], v[200:203], v[216:219], v[66:69]
	v_readfirstlane_b32 s16, v141
	s_mov_b32 m0, s16
	v_readfirstlane_b32 s16, v142
	s_barrier
	ds_read_b128 v[172:175], v133 offset:49152
	ds_read_b128 v[176:179], v133 offset:50176
	ds_read_b128 v[180:183], v132 offset:49152
	ds_read_b128 v[184:187], v132 offset:50176
	ds_read_b128 v[188:191], v131 offset:49152
	ds_read_b128 v[192:195], v131 offset:50176
	ds_read_b128 v[196:199], v130 offset:49152
	ds_read_b128 v[200:203], v130 offset:50176
	buffer_load_dwordx4 v137, s[88:91], s15 offen lds
	s_mov_b32 m0, s16
	s_nop 0
	buffer_load_dwordx4 v136, s[88:91], s15 offen lds
	s_barrier
; #define WAIT_V(n) asm volatile("s_waitcnt vmcnt(" #n ")" ::: "memory")
; #define WAIT_L(n) asm volatile("s_waitcnt lgkmcnt(" #n ")" ::: "memory")
; #define BAR __builtin_amdgcn_s_barrier()
; #define SCHED __builtin_amdgcn_sched_barrier(0)
; __device__ __forceinline__ void mainloop_8phase(const u16* __restrict__ A, const u16* __restrict__ Bt, int K,
;                                                 f32x4 (&acc)[2][2][4][2], int wid_s, int ld) {
;     ...
;     BAR; WAIT_L(0); MMA(1, 0, At, B0); BAR; SCHED;
;     STAGE(SB(1, 1), Bt, bcol + G_HALF, t + 3);
;     WAIT_V(6); BAR; MMA(1, 1, At, B1); BAR;
;   }
;   { LDB(B0, 0, 0); LDA(At, 0, 0); STAGE(SA(1, 1), A, brow + G_HALF, nt - 1);
;     BAR; WAIT_L(0); MMA(0, 0, At, B0); BAR;
;     LDB(B1, 0, 1); BAR; WAIT_L(0); MMA(0, 1, At, B1); BAR;
	s_waitcnt lgkmcnt(0)
	s_waitcnt lgkmcnt(7)
	v_mfma_f32_16x16x32_bf16 v[62:65], v[172:175], v[156:159], v[62:65]
	v_mfma_f32_16x16x32_bf16 v[58:61], v[172:175], v[164:167], v[58:61]
	s_waitcnt lgkmcnt(5)
	v_mfma_f32_16x16x32_bf16 v[54:57], v[180:183], v[156:159], v[54:57]
	v_mfma_f32_16x16x32_bf16 v[50:53], v[180:183], v[164:167], v[50:53]
	s_waitcnt lgkmcnt(3)
	v_mfma_f32_16x16x32_bf16 v[46:49], v[188:191], v[156:159], v[46:49]
	v_mfma_f32_16x16x32_bf16 v[42:45], v[188:191], v[164:167], v[42:45]
	s_waitcnt lgkmcnt(1)
	v_mfma_f32_16x16x32_bf16 v[38:41], v[196:199], v[156:159], v[38:41]
	v_mfma_f32_16x16x32_bf16 v[34:37], v[196:199], v[164:167], v[34:37]
	v_mfma_f32_16x16x32_bf16 v[62:65], v[176:179], v[160:163], v[62:65]
	v_mfma_f32_16x16x32_bf16 v[58:61], v[176:179], v[168:171], v[58:61]
	v_mfma_f32_16x16x32_bf16 v[54:57], v[184:187], v[160:163], v[54:57]
	v_mfma_f32_16x16x32_bf16 v[50:53], v[184:187], v[168:171], v[50:53]
	v_mfma_f32_16x16x32_bf16 v[46:49], v[192:195], v[160:163], v[46:49]
	v_mfma_f32_16x16x32_bf16 v[42:45], v[192:195], v[168:171], v[42:45]
	s_waitcnt lgkmcnt(0)
	v_mfma_f32_16x16x32_bf16 v[38:41], v[200:203], v[160:163], v[38:41]
	v_mfma_f32_16x16x32_bf16 v[34:37], v[200:203], v[168:171], v[34:37]
	s_barrier
	v_readfirstlane_b32 s15, v143
	s_mov_b32 m0, s15
	v_readfirstlane_b32 s15, v146
	buffer_load_dwordx4 v137, s[4:7], s1 offen lds
	s_mov_b32 m0, s15
	s_nop 0
	buffer_load_dwordx4 v136, s[4:7], s1 offen lds
	s_waitcnt vmcnt(6)
	s_barrier
	v_mfma_f32_16x16x32_bf16 v[30:33], v[172:175], v[204:207], v[30:33]
	v_mfma_f32_16x16x32_bf16 v[26:29], v[172:175], v[212:215], v[26:29]
	v_mfma_f32_16x16x32_bf16 v[22:25], v[180:183], v[204:207], v[22:25]
	v_mfma_f32_16x16x32_bf16 v[18:21], v[180:183], v[212:215], v[18:21]
	v_mfma_f32_16x16x32_bf16 v[14:17], v[188:191], v[204:207], v[14:17]
	v_mfma_f32_16x16x32_bf16 v[10:13], v[188:191], v[212:215], v[10:13]
	v_mfma_f32_16x16x32_bf16 v[6:9], v[196:199], v[204:207], v[6:9]
	v_mfma_f32_16x16x32_bf16 v[2:5], v[196:199], v[212:215], v[2:5]
	v_mfma_f32_16x16x32_bf16 v[30:33], v[176:179], v[208:211], v[30:33]
	v_mfma_f32_16x16x32_bf16 v[26:29], v[176:179], v[216:219], v[26:29]
	v_mfma_f32_16x16x32_bf16 v[22:25], v[184:187], v[208:211], v[22:25]
	v_mfma_f32_16x16x32_bf16 v[18:21], v[184:187], v[216:219], v[18:21]
	v_mfma_f32_16x16x32_bf16 v[14:17], v[192:195], v[208:211], v[14:17]
	v_mfma_f32_16x16x32_bf16 v[10:13], v[192:195], v[216:219], v[10:13]
	v_mfma_f32_16x16x32_bf16 v[6:9], v[200:203], v[208:211], v[6:9]
	v_mfma_f32_16x16x32_bf16 v[2:5], v[200:203], v[216:219], v[2:5]
	s_add_i32 s0, s0, 2
	s_addk_i32 s1, 0x100
	s_cmp_lt_u32 s0, 28
	s_barrier
	s_cbranch_scc1 .LBB0_58
	v_readfirstlane_b32 s0, v145
	s_mov_b32 m0, s0
	s_mov_b32 s1, 0x80f80
	v_readfirstlane_b32 s0, v144
	ds_read_b128 v[138:141], v155
	ds_read_b128 v[148:151], v155 offset:1024
	ds_read_b128 v[156:159], v155 offset:2048
	ds_read_b128 v[152:155], v155 offset:3072
	ds_read_b128 v[160:163], v133
	ds_read_b128 v[164:167], v133 offset:1024
	ds_read_b128 v[168:171], v132
	ds_read_b128 v[172:175], v132 offset:1024
	ds_read_b128 v[176:179], v131
	ds_read_b128 v[180:183], v131 offset:1024
	ds_read_b128 v[184:187], v130
	ds_read_b128 v[188:191], v130 offset:1024
	buffer_load_dwordx4 v137, s[88:91], s1 offen lds
	s_mov_b32 m0, s0
	s_nop 0
	buffer_load_dwordx4 v136, s[88:91], s1 offen lds
	s_barrier
	s_waitcnt lgkmcnt(0)
	s_waitcnt lgkmcnt(7)
	v_mfma_f32_16x16x32_bf16 v[126:129], v[160:163], v[138:141], v[126:129]
	v_mfma_f32_16x16x32_bf16 v[122:125], v[160:163], v[156:159], v[122:125]
	s_waitcnt lgkmcnt(5)
	v_mfma_f32_16x16x32_bf16 v[118:121], v[168:171], v[138:141], v[118:121]
	v_mfma_f32_16x16x32_bf16 v[114:117], v[168:171], v[156:159], v[114:117]
	s_waitcnt lgkmcnt(1)
	v_mfma_f32_16x16x32_bf16 v[102:105], v[184:187], v[138:141], v[102:105]
	v_mfma_f32_16x16x32_bf16 v[98:101], v[184:187], v[156:159], v[98:101]
	v_mfma_f32_16x16x32_bf16 v[126:129], v[164:167], v[148:151], v[126:129]
	v_mfma_f32_16x16x32_bf16 v[122:125], v[164:167], v[152:155], v[122:125]
	v_mfma_f32_16x16x32_bf16 v[118:121], v[172:175], v[148:151], v[118:121]
	v_mfma_f32_16x16x32_bf16 v[114:117], v[172:175], v[152:155], v[114:117]
	v_mfma_f32_16x16x32_bf16 v[110:113], v[176:179], v[138:141], v[110:113]
	v_mfma_f32_16x16x32_bf16 v[106:109], v[176:179], v[156:159], v[106:109]
	s_waitcnt lgkmcnt(0)
	v_mfma_f32_16x16x32_bf16 v[102:105], v[188:191], v[148:151], v[102:105]
	v_mfma_f32_16x16x32_bf16 v[98:101], v[188:191], v[152:155], v[98:101]
	v_mfma_f32_16x16x32_bf16 v[142:145], v[180:183], v[148:151], v[110:113]
	v_mfma_f32_16x16x32_bf16 v[192:195], v[180:183], v[152:155], v[106:109]
	s_barrier
	s_nop 0
	ds_read_b128 v[106:109], v147
	ds_read_b128 v[110:113], v147 offset:1024
	ds_read_b128 v[196:199], v147 offset:2048
	ds_read_b128 v[200:203], v147 offset:3072
	s_barrier
	s_waitcnt lgkmcnt(0)
	s_waitcnt lgkmcnt(3)
	v_mfma_f32_16x16x32_bf16 v[86:89], v[168:171], v[106:109], v[86:89]
	s_waitcnt lgkmcnt(1)
	v_mfma_f32_16x16x32_bf16 v[82:85], v[168:171], v[196:199], v[82:85]
	v_mfma_f32_16x16x32_bf16 v[70:73], v[184:187], v[106:109], v[70:73]
	v_mfma_f32_16x16x32_bf16 v[66:69], v[184:187], v[196:199], v[66:69]
	v_mfma_f32_16x16x32_bf16 v[94:97], v[160:163], v[106:109], v[94:97]
	v_mfma_f32_16x16x32_bf16 v[90:93], v[160:163], v[196:199], v[90:93]
	v_mfma_f32_16x16x32_bf16 v[86:89], v[172:175], v[110:113], v[86:89]
	s_waitcnt lgkmcnt(0)
	v_mfma_f32_16x16x32_bf16 v[82:85], v[172:175], v[200:203], v[82:85]
	v_mfma_f32_16x16x32_bf16 v[78:81], v[176:179], v[106:109], v[78:81]
	v_mfma_f32_16x16x32_bf16 v[74:77], v[176:179], v[196:199], v[74:77]
	v_mfma_f32_16x16x32_bf16 v[70:73], v[188:191], v[110:113], v[70:73]
	v_mfma_f32_16x16x32_bf16 v[66:69], v[188:191], v[200:203], v[66:69]
	v_mfma_f32_16x16x32_bf16 v[204:207], v[164:167], v[110:113], v[94:97]
	v_mfma_f32_16x16x32_bf16 v[160:163], v[164:167], v[200:203], v[90:93]
	v_mfma_f32_16x16x32_bf16 v[164:167], v[180:183], v[110:113], v[78:81]
	v_mfma_f32_16x16x32_bf16 v[168:171], v[180:183], v[200:203], v[74:77]
	s_barrier
; #define WAIT_V(n) asm volatile("s_waitcnt vmcnt(" #n ")" ::: "memory")
; #define WAIT_L(n) asm volatile("s_waitcnt lgkmcnt(" #n ")" ::: "memory")
; #define BAR __builtin_amdgcn_s_barrier()
; __device__ __forceinline__ void mainloop_8phase(const u16* __restrict__ A, const u16* __restrict__ Bt, int K,
;                                                 f32x4 (&acc)[2][2][4][2], int wid_s, int ld) {
;     ...
;     LDA(At, 0, 1); WAIT_V(4); BAR; WAIT_L(0); MMA(1, 0, At, B0); MMA(1, 1, At, B1); BAR; }
;   { LDB(B0, 1, 0); LDA(At, 1, 0); WAIT_V(2); BAR; WAIT_L(0); MMA(0, 0, At, B0); BAR;
	s_nop 0
	ds_read_b128 v[74:77], v133 offset:16384
	ds_read_b128 v[78:81], v133 offset:17408
	ds_read_b128 v[90:93], v132 offset:16384
	ds_read_b128 v[94:97], v132 offset:17408
	ds_read_b128 v[172:175], v131 offset:16384
	ds_read_b128 v[176:179], v131 offset:17408
	ds_read_b128 v[180:183], v130 offset:16384
	ds_read_b128 v[184:187], v130 offset:17408
	s_waitcnt vmcnt(4)
	s_barrier
	s_waitcnt lgkmcnt(0)
	s_waitcnt lgkmcnt(7)
	v_mfma_f32_16x16x32_bf16 v[62:65], v[74:77], v[138:141], v[62:65]
	v_mfma_f32_16x16x32_bf16 v[58:61], v[74:77], v[156:159], v[58:61]
	s_waitcnt lgkmcnt(5)
	v_mfma_f32_16x16x32_bf16 v[54:57], v[90:93], v[138:141], v[54:57]
	v_mfma_f32_16x16x32_bf16 v[50:53], v[90:93], v[156:159], v[50:53]
	s_waitcnt lgkmcnt(1)
	v_mfma_f32_16x16x32_bf16 v[38:41], v[180:183], v[138:141], v[38:41]
	v_mfma_f32_16x16x32_bf16 v[34:37], v[180:183], v[156:159], v[34:37]
	v_mfma_f32_16x16x32_bf16 v[62:65], v[78:81], v[148:151], v[62:65]
	v_mfma_f32_16x16x32_bf16 v[58:61], v[78:81], v[152:155], v[58:61]
	v_mfma_f32_16x16x32_bf16 v[54:57], v[94:97], v[148:151], v[54:57]
	v_mfma_f32_16x16x32_bf16 v[50:53], v[94:97], v[152:155], v[50:53]
	v_mfma_f32_16x16x32_bf16 v[46:49], v[172:175], v[138:141], v[46:49]
	v_mfma_f32_16x16x32_bf16 v[42:45], v[172:175], v[156:159], v[42:45]
	s_waitcnt lgkmcnt(0)
	v_mfma_f32_16x16x32_bf16 v[38:41], v[184:187], v[148:151], v[38:41]
	v_mfma_f32_16x16x32_bf16 v[34:37], v[184:187], v[152:155], v[34:37]
	v_mfma_f32_16x16x32_bf16 v[188:191], v[176:179], v[148:151], v[46:49]
	v_mfma_f32_16x16x32_bf16 v[208:211], v[176:179], v[152:155], v[42:45]
	v_mfma_f32_16x16x32_bf16 v[22:25], v[90:93], v[106:109], v[22:25]
	v_mfma_f32_16x16x32_bf16 v[18:21], v[90:93], v[196:199], v[18:21]
	v_mfma_f32_16x16x32_bf16 v[6:9], v[180:183], v[106:109], v[6:9]
	v_mfma_f32_16x16x32_bf16 v[2:5], v[180:183], v[196:199], v[2:5]
	v_mfma_f32_16x16x32_bf16 v[30:33], v[74:77], v[106:109], v[30:33]
	v_mfma_f32_16x16x32_bf16 v[26:29], v[74:77], v[196:199], v[26:29]
	v_mfma_f32_16x16x32_bf16 v[22:25], v[94:97], v[110:113], v[22:25]
	v_mfma_f32_16x16x32_bf16 v[18:21], v[94:97], v[200:203], v[18:21]
	v_mfma_f32_16x16x32_bf16 v[14:17], v[172:175], v[106:109], v[14:17]
	v_mfma_f32_16x16x32_bf16 v[10:13], v[172:175], v[196:199], v[10:13]
	v_mfma_f32_16x16x32_bf16 v[6:9], v[184:187], v[110:113], v[6:9]
	v_mfma_f32_16x16x32_bf16 v[2:5], v[184:187], v[200:203], v[2:5]
	v_mfma_f32_16x16x32_bf16 v[136:139], v[78:81], v[110:113], v[30:33]
	v_mfma_f32_16x16x32_bf16 v[146:149], v[78:81], v[200:203], v[26:29]
	v_mfma_f32_16x16x32_bf16 v[150:153], v[176:179], v[110:113], v[14:17]
	v_mfma_f32_16x16x32_bf16 v[154:157], v[176:179], v[200:203], v[10:13]
	s_barrier
	s_nop 0
	ds_read_b128 v[10:13], v135
	ds_read_b128 v[14:17], v135 offset:1024
	ds_read_b128 v[172:175], v135 offset:2048
	ds_read_b128 v[176:179], v135 offset:3072
	ds_read_b128 v[26:29], v133 offset:32768
	ds_read_b128 v[30:33], v133 offset:33792
	ds_read_b128 v[42:45], v132 offset:32768
	ds_read_b128 v[46:49], v132 offset:33792
	ds_read_b128 v[180:183], v131 offset:32768
	ds_read_b128 v[184:187], v131 offset:33792
	ds_read_b128 v[196:199], v130 offset:32768
	ds_read_b128 v[200:203], v130 offset:33792
	s_waitcnt vmcnt(2)
	s_barrier
	s_waitcnt lgkmcnt(0)
	s_waitcnt lgkmcnt(7)
	v_mfma_f32_16x16x32_bf16 v[74:77], v[26:29], v[10:13], v[126:129]
	s_waitcnt lgkmcnt(6)
	v_mfma_f32_16x16x32_bf16 v[126:129], v[30:33], v[14:17], v[74:77]
	v_mfma_f32_16x16x32_bf16 v[74:77], v[26:29], v[172:175], v[122:125]
	v_mfma_f32_16x16x32_bf16 v[122:125], v[30:33], v[176:179], v[74:77]
	s_waitcnt lgkmcnt(5)
	v_mfma_f32_16x16x32_bf16 v[74:77], v[42:45], v[10:13], v[118:121]
	s_waitcnt lgkmcnt(4)
	v_mfma_f32_16x16x32_bf16 v[110:113], v[46:49], v[14:17], v[74:77]
	v_mfma_f32_16x16x32_bf16 v[74:77], v[42:45], v[172:175], v[114:117]
	v_mfma_f32_16x16x32_bf16 v[106:109], v[46:49], v[176:179], v[74:77]
	s_waitcnt lgkmcnt(3)
	v_mfma_f32_16x16x32_bf16 v[74:77], v[180:183], v[10:13], v[142:145]
	s_waitcnt lgkmcnt(2)
	v_mfma_f32_16x16x32_bf16 v[94:97], v[184:187], v[14:17], v[74:77]
	v_mfma_f32_16x16x32_bf16 v[74:77], v[180:183], v[172:175], v[192:195]
	v_mfma_f32_16x16x32_bf16 v[90:93], v[184:187], v[176:179], v[74:77]
	s_waitcnt lgkmcnt(1)
	v_mfma_f32_16x16x32_bf16 v[74:77], v[196:199], v[10:13], v[102:105]
	s_waitcnt lgkmcnt(0)
	v_mfma_f32_16x16x32_bf16 v[78:81], v[200:203], v[14:17], v[74:77]
	v_mfma_f32_16x16x32_bf16 v[74:77], v[196:199], v[172:175], v[98:101]
	v_mfma_f32_16x16x32_bf16 v[74:77], v[200:203], v[176:179], v[74:77]
	s_barrier
; #define WAIT_V(n) asm volatile("s_waitcnt vmcnt(" #n ")" ::: "memory")
; #define WAIT_L(n) asm volatile("s_waitcnt lgkmcnt(" #n ")" ::: "memory")
; #define BAR __builtin_amdgcn_s_barrier()
; __device__ __forceinline__ void mainloop_8phase(const u16* __restrict__ A, const u16* __restrict__ Bt, int K,
;                                                 f32x4 (&acc)[2][2][4][2], int wid_s, int ld) {
;     ...
;   { LDB(B0, 1, 0); LDA(At, 1, 0); WAIT_V(2); BAR; WAIT_L(0); MMA(0, 0, At, B0); BAR;
;     LDB(B1, 1, 1); WAIT_V(0); BAR; WAIT_L(0); MMA(0, 1, At, B1); BAR;
;     LDA(At, 1, 1); BAR; WAIT_L(0); MMA(1, 0, At, B0); MMA(1, 1, At, B1); BAR; }
;   if (wr == 0) BAR;
	ds_read_b128 v[140:143], v134
	ds_read_b128 v[192:195], v134 offset:1024
	ds_read_b128 v[212:215], v134 offset:2048
	ds_read_b128 v[216:219], v134 offset:3072
	s_waitcnt vmcnt(0)
	s_barrier
	s_waitcnt lgkmcnt(0)
	s_waitcnt lgkmcnt(3)
	v_mfma_f32_16x16x32_bf16 v[98:101], v[26:29], v[140:143], v[204:207]
	s_waitcnt lgkmcnt(1)
	v_mfma_f32_16x16x32_bf16 v[26:29], v[26:29], v[212:215], v[160:163]
	s_waitcnt lgkmcnt(0)
	v_mfma_f32_16x16x32_bf16 v[114:117], v[30:33], v[216:219], v[26:29]
	v_mfma_f32_16x16x32_bf16 v[26:29], v[42:45], v[140:143], v[86:89]
	v_mfma_f32_16x16x32_bf16 v[102:105], v[46:49], v[192:195], v[26:29]
	v_mfma_f32_16x16x32_bf16 v[26:29], v[42:45], v[212:215], v[82:85]
	v_mfma_f32_16x16x32_bf16 v[118:121], v[30:33], v[192:195], v[98:101]
	v_mfma_f32_16x16x32_bf16 v[98:101], v[46:49], v[216:219], v[26:29]
	v_mfma_f32_16x16x32_bf16 v[26:29], v[180:183], v[140:143], v[164:167]
	v_mfma_f32_16x16x32_bf16 v[86:89], v[184:187], v[192:195], v[26:29]
	v_mfma_f32_16x16x32_bf16 v[26:29], v[180:183], v[212:215], v[168:171]
	v_mfma_f32_16x16x32_bf16 v[82:85], v[184:187], v[216:219], v[26:29]
	v_mfma_f32_16x16x32_bf16 v[26:29], v[196:199], v[140:143], v[70:73]
	v_mfma_f32_16x16x32_bf16 v[70:73], v[200:203], v[192:195], v[26:29]
	v_mfma_f32_16x16x32_bf16 v[26:29], v[196:199], v[212:215], v[66:69]
	v_mfma_f32_16x16x32_bf16 v[66:69], v[200:203], v[216:219], v[26:29]
	s_barrier
	ds_read_b128 v[158:161], v133 offset:49152
	ds_read_b128 v[162:165], v133 offset:50176
	ds_read_b128 v[166:169], v132 offset:49152
	ds_read_b128 v[132:135], v132 offset:50176
	ds_read_b128 v[180:183], v131 offset:49152
	ds_read_b128 v[184:187], v131 offset:50176
	ds_read_b128 v[196:199], v130 offset:49152
	ds_read_b128 v[200:203], v130 offset:50176
	s_barrier
	s_waitcnt lgkmcnt(0)
	s_waitcnt lgkmcnt(7)
	v_mfma_f32_16x16x32_bf16 v[26:29], v[158:161], v[10:13], v[62:65]
	s_waitcnt lgkmcnt(6)
	v_mfma_f32_16x16x32_bf16 v[62:65], v[162:165], v[14:17], v[26:29]
	v_mfma_f32_16x16x32_bf16 v[26:29], v[158:161], v[172:175], v[58:61]
	v_mfma_f32_16x16x32_bf16 v[58:61], v[162:165], v[176:179], v[26:29]
	s_waitcnt lgkmcnt(5)
	v_mfma_f32_16x16x32_bf16 v[26:29], v[166:169], v[10:13], v[54:57]
	s_waitcnt lgkmcnt(4)
	v_mfma_f32_16x16x32_bf16 v[46:49], v[132:135], v[14:17], v[26:29]
	v_mfma_f32_16x16x32_bf16 v[26:29], v[166:169], v[172:175], v[50:53]
	v_mfma_f32_16x16x32_bf16 v[42:45], v[132:135], v[176:179], v[26:29]
	s_waitcnt lgkmcnt(3)
	v_mfma_f32_16x16x32_bf16 v[26:29], v[180:183], v[10:13], v[188:191]
	s_waitcnt lgkmcnt(1)
	v_mfma_f32_16x16x32_bf16 v[10:13], v[196:199], v[10:13], v[38:41]
	v_mfma_f32_16x16x32_bf16 v[30:33], v[184:187], v[14:17], v[26:29]
	v_mfma_f32_16x16x32_bf16 v[26:29], v[180:183], v[172:175], v[208:211]
	s_waitcnt lgkmcnt(0)
	v_mfma_f32_16x16x32_bf16 v[14:17], v[200:203], v[14:17], v[10:13]
	v_mfma_f32_16x16x32_bf16 v[10:13], v[196:199], v[172:175], v[34:37]
	v_mfma_f32_16x16x32_bf16 v[26:29], v[184:187], v[176:179], v[26:29]
	v_mfma_f32_16x16x32_bf16 v[10:13], v[200:203], v[176:179], v[10:13]
	v_mfma_f32_16x16x32_bf16 v[34:37], v[158:161], v[140:143], v[136:139]
	v_mfma_f32_16x16x32_bf16 v[54:57], v[162:165], v[192:195], v[34:37]
	v_mfma_f32_16x16x32_bf16 v[34:37], v[158:161], v[212:215], v[146:149]
	v_mfma_f32_16x16x32_bf16 v[18:21], v[166:169], v[212:215], v[18:21]
	v_mfma_f32_16x16x32_bf16 v[50:53], v[162:165], v[216:219], v[34:37]
	v_mfma_f32_16x16x32_bf16 v[22:25], v[166:169], v[140:143], v[22:25]
	v_mfma_f32_16x16x32_bf16 v[34:37], v[132:135], v[216:219], v[18:21]
	v_mfma_f32_16x16x32_bf16 v[18:21], v[180:183], v[140:143], v[150:153]
	v_mfma_f32_16x16x32_bf16 v[38:41], v[132:135], v[192:195], v[22:25]
	v_mfma_f32_16x16x32_bf16 v[22:25], v[184:187], v[192:195], v[18:21]
	v_mfma_f32_16x16x32_bf16 v[18:21], v[180:183], v[212:215], v[154:157]
	v_mfma_f32_16x16x32_bf16 v[6:9], v[196:199], v[140:143], v[6:9]
	v_mfma_f32_16x16x32_bf16 v[2:5], v[196:199], v[212:215], v[2:5]
	v_mfma_f32_16x16x32_bf16 v[18:21], v[184:187], v[216:219], v[18:21]
	v_mfma_f32_16x16x32_bf16 v[6:9], v[200:203], v[192:195], v[6:9]
	v_mfma_f32_16x16x32_bf16 v[2:5], v[200:203], v[216:219], v[2:5]
	s_movk_i32 s0, 0x100
	v_cmp_gt_u32_e32 vcc, s0, v0
	s_barrier
	s_and_saveexec_b64 s[0:1], vcc
	s_cbranch_execz .LBB0_61
	s_barrier

; #define WAIT_V(n) asm volatile("s_waitcnt vmcnt(" #n ")" ::: "memory")
; #define SB0 __builtin_amdgcn_sched_barrier(0)
; template <bool FWD>
; __device__ __forceinline__ void ret_sweep(const Params& p, int gs, int s, int g, int h, int sl, int nsegps, float lf, float lb) {
;     ...
; #pragma unroll
;     for (int mb = 0; mb < 2; ++mb)
; #pragma unroll
;       for (int nb = 0; nb < 8; ++nb) {
;         f32x4 a = T[mb][nb];
;         *(uint2*)(Ts + (nb * 16 + fr) * 264 + 32 * w + mb * 16 + fq * 4) = make_uint2(pack2(a[0], a[1]), pack2(a[2], a[3]));
;       }
;     ret_store_vt(vp, VTs, tid);
;     SB0;
;     u32x4* ypriv = (u32x4*)((char*)(Y + (long)t0 * YS + h * 512 + sl * 128) + (unsigned)(((tid >> 2) * YS + (tid & 3) * 32) * 2));
;     SB0;
;     WAIT_V(0);
;     __syncthreads();
;     f32x4 O[2][4];
; #pragma unroll
;     for (int mb = 0; mb < 2; ++mb)
; #pragma unroll
;       for (int nb = 0; nb < 4; ++nb) O[mb][nb] = f32x4{0.f, 0.f, 0.f, 0.f};
; #pragma unroll
;     for (int ks = 0; ks < 8; ++ks)
; #pragma unroll
;       for (int nb = 0; nb < 4; ++nb) {
;         bf16x8 b = *(const bf16x8*)(Ts + (64 * wv + nb * 16 + fr) * 264 + ks * 32 + fq * 8);
; #pragma unroll
;         for (int mb = 0; mb < 2; ++mb) O[mb][nb] = mfma16(qa[mb][ks], b, O[mb][nb]);
;       }
.LBB0_126:
	v_mov_b32_e32 v2, s33
	v_mbcnt_lo_u32_b32 v183, -1, 0
	v_mbcnt_hi_u32_b32 v183, -1, v183
	v_cvt_pk_bf16_f32 v148, v24, v25
	v_and_b32_e32 v181, 15, v183
	v_bfe_u32 v185, v183, 4, 2
	v_bitop3_b32 v2, v183, s57, v2 bitop3:0xc8
	v_add_u32_e32 v2, 16, v2
	v_lshlrev_b32_e32 v150, 3, v185
	v_mul_u32_u24_e32 v151, 0x210, v181
	v_cvt_pk_bf16_f32 v149, v26, v27
	v_add3_u32 v2, v2, v150, v151
	v_cvt_pk_bf16_f32 v164, v4, v5
	v_cvt_pk_bf16_f32 v165, v6, v7
	v_cvt_pk_bf16_f32 v150, v28, v29
	v_cvt_pk_bf16_f32 v151, v30, v31
	ds_write2_b64 v2, v[148:149], v[164:165] offset1:4
	v_cvt_pk_bf16_f32 v148, v8, v9
	v_cvt_pk_bf16_f32 v149, v10, v11
	v_add_u32_e32 v164, 0x2000, v2
	v_cvt_pk_bf16_f32 v152, v36, v37
	v_cvt_pk_bf16_f32 v153, v38, v39
	ds_write2_b64 v164, v[150:151], v[148:149] offset0:32 offset1:36
	v_cvt_pk_bf16_f32 v148, v12, v13
	v_cvt_pk_bf16_f32 v149, v14, v15
	v_add_u32_e32 v150, 0x4000, v2
	v_cvt_pk_bf16_f32 v154, v48, v49
	v_cvt_pk_bf16_f32 v155, v50, v51
	ds_write2_b64 v150, v[152:153], v[148:149] offset0:64 offset1:68
	v_cvt_pk_bf16_f32 v148, v16, v17
	v_cvt_pk_bf16_f32 v149, v18, v19
	v_add_u32_e32 v150, 0x6000, v2
	v_cvt_pk_bf16_f32 v156, v52, v53
	v_cvt_pk_bf16_f32 v157, v54, v55
	ds_write2_b64 v150, v[154:155], v[148:149] offset0:96 offset1:100
	v_cvt_pk_bf16_f32 v148, v20, v21
	v_cvt_pk_bf16_f32 v149, v22, v23
	v_add_u32_e32 v150, 0x8000, v2
	v_cvt_pk_bf16_f32 v158, v56, v57
	v_cvt_pk_bf16_f32 v159, v58, v59
	ds_write2_b64 v150, v[156:157], v[148:149] offset0:128 offset1:132
	v_cvt_pk_bf16_f32 v148, v32, v33
	v_cvt_pk_bf16_f32 v149, v34, v35
	v_add_u32_e32 v150, 0xa000, v2
	v_cvt_pk_bf16_f32 v160, v60, v61
	v_cvt_pk_bf16_f32 v161, v62, v63
	ds_write2_b64 v150, v[158:159], v[148:149] offset0:160 offset1:164
	v_cvt_pk_bf16_f32 v148, v40, v41
	v_cvt_pk_bf16_f32 v149, v42, v43
	v_add_u32_e32 v150, 0xc000, v2
	v_cvt_pk_bf16_f32 v162, v64, v65
	v_cvt_pk_bf16_f32 v163, v66, v67
	ds_write2_b64 v150, v[160:161], v[148:149] offset0:192 offset1:196
	v_cvt_pk_bf16_f32 v148, v44, v45
	v_cvt_pk_bf16_f32 v149, v46, v47
	v_add_u32_e32 v2, 0xe000, v2
	ds_write2_b64 v2, v[162:163], v[148:149] offset0:224 offset1:228
	v_lshlrev_b32_e32 v2, 4, v183
	v_or_b32_e32 v3, s33, v183
	v_and_b32_e32 v2, 0xf0, v2
	v_add_u32_e32 v2, s93, v2
	v_lshrrev_b32_e32 v148, 4, v3
	v_mad_u64_u32 v[148:149], s[52:53], v148, s36, v[2:3]
	s_waitcnt vmcnt(18)
	ds_write_b128 v148, v[124:127]
	v_add_u32_e32 v124, 0x200, v3
	v_lshrrev_b32_e32 v124, 4, v124
	v_mad_u64_u32 v[124:125], s[52:53], v124, s36, v[2:3]
	s_waitcnt vmcnt(18)
	ds_write_b128 v124, v[128:131]
	v_add_u32_e32 v124, 0x400, v3
	v_lshrrev_b32_e32 v124, 4, v124
	s_cmp_lg_u32 s12, 0xfff10000
	v_mad_u64_u32 v[124:125], s[52:53], v124, s36, v[2:3]
	s_cselect_b32 s16, s50, 0
	s_waitcnt vmcnt(17)
	ds_write_b128 v124, v[132:135]
	v_add_u32_e32 v124, 0x600, v3
	s_add_i32 s16, s16, s14
	v_ashrrev_i32_e32 v184, 2, v3
	v_lshrrev_b32_e32 v124, 4, v124
	s_ashr_i32 s17, s16, 31
	v_and_b32_e32 v186, 0xffffffe0, v184
	v_mad_u64_u32 v[124:125], s[52:53], v124, s36, v[2:3]
	s_lshl_b64 s[18:19], s[16:17], 19
	v_or_b32_e32 v0, v186, v181
	v_lshlrev_b32_e32 v182, 4, v185
	s_waitcnt vmcnt(9)
	ds_write_b128 v124, v[144:147]
	v_and_or_b32 v2, v3, 64, v181
	v_mul_u32_u24_e32 v2, 0x210, v2
	v_add3_u32 v2, 16, v182, v2
	s_waitcnt vmcnt(0)
	s_waitcnt lgkmcnt(0)
	s_barrier
	ds_read_b128 v[124:127], v2
	ds_read_b128 v[132:135], v2 offset:8448
	ds_read_b128 v[148:151], v2 offset:16896
	ds_read_b128 v[156:159], v2 offset:25344
	s_waitcnt vmcnt(1) lgkmcnt(3)
	v_mfma_f32_16x16x32_bf16 v[128:131], v[136:139], v[124:127], 0
	s_add_u32 s18, s28, s18
	s_addc_u32 s19, s29, s19
	v_mfma_f32_16x16x32_bf16 v[124:127], v[140:143], v[124:127], 0
	s_waitcnt lgkmcnt(2)
	v_mfma_f32_16x16x32_bf16 v[144:147], v[136:139], v[132:135], 0
	v_mfma_f32_16x16x32_bf16 v[132:135], v[140:143], v[132:135], 0
	s_waitcnt lgkmcnt(1)
	v_mfma_f32_16x16x32_bf16 v[152:155], v[136:139], v[148:151], 0
	v_mfma_f32_16x16x32_bf16 v[148:151], v[140:143], v[148:151], 0
	s_waitcnt lgkmcnt(0)
	v_mfma_f32_16x16x32_bf16 v[136:139], v[136:139], v[156:159], 0
	v_mfma_f32_16x16x32_bf16 v[140:143], v[140:143], v[156:159], 0
	ds_read_b128 v[156:159], v2 offset:64
	s_waitcnt lgkmcnt(0)
	v_mfma_f32_16x16x32_bf16 v[128:131], v[112:115], v[156:159], v[128:131]
	v_mfma_f32_16x16x32_bf16 v[124:127], v[120:123], v[156:159], v[124:127]
	ds_read_b128 v[156:159], v2 offset:8512
	s_waitcnt lgkmcnt(0)
	v_mfma_f32_16x16x32_bf16 v[144:147], v[112:115], v[156:159], v[144:147]
	v_mfma_f32_16x16x32_bf16 v[132:135], v[120:123], v[156:159], v[132:135]
	ds_read_b128 v[156:159], v2 offset:16960
	s_waitcnt lgkmcnt(0)
	v_mfma_f32_16x16x32_bf16 v[152:155], v[112:115], v[156:159], v[152:155]
	v_mfma_f32_16x16x32_bf16 v[148:151], v[120:123], v[156:159], v[148:151]
	ds_read_b128 v[156:159], v2 offset:25408
	s_waitcnt lgkmcnt(0)
	v_mfma_f32_16x16x32_bf16 v[112:115], v[112:115], v[156:159], v[136:139]
	s_nop 2
	ds_read_b128 v[136:139], v2 offset:128
	s_waitcnt lgkmcnt(0)
	v_mfma_f32_16x16x32_bf16 v[128:131], v[108:111], v[136:139], v[128:131]
	v_mfma_f32_16x16x32_bf16 v[124:127], v[116:119], v[136:139], v[124:127]
	ds_read_b128 v[136:139], v2 offset:8576
	v_mfma_f32_16x16x32_bf16 v[120:123], v[120:123], v[156:159], v[140:143]
	s_waitcnt lgkmcnt(0)
	v_mfma_f32_16x16x32_bf16 v[140:143], v[108:111], v[136:139], v[144:147]
	v_mfma_f32_16x16x32_bf16 v[132:135], v[116:119], v[136:139], v[132:135]
	ds_read_b128 v[136:139], v2 offset:17024
	s_waitcnt lgkmcnt(0)
	v_mfma_f32_16x16x32_bf16 v[144:147], v[108:111], v[136:139], v[152:155]
	v_mfma_f32_16x16x32_bf16 v[136:139], v[116:119], v[136:139], v[148:151]
	s_nop 2
	ds_read_b128 v[148:151], v2 offset:25472
	s_waitcnt lgkmcnt(0)
; template <bool FWD>
; __device__ __forceinline__ void ret_sweep(const Params& p, int gs, int s, int g, int h, int sl, int nsegps, float lf, float lb) {
;     ...
; #pragma unroll
;     for (int ks = 0; ks < 8; ++ks)
; #pragma unroll
;       for (int nb = 0; nb < 4; ++nb) {
;         bf16x8 b = *(const bf16x8*)(Ts + (64 * wv + nb * 16 + fr) * 264 + ks * 32 + fq * 8);
; #pragma unroll
;         for (int mb = 0; mb < 2; ++mb) O[mb][nb] = mfma16(qa[mb][ks], b, O[mb][nb]);
;       }
	v_mfma_f32_16x16x32_bf16 v[108:111], v[108:111], v[148:151], v[112:115]
	v_mfma_f32_16x16x32_bf16 v[112:115], v[116:119], v[148:151], v[120:123]
	ds_read_b128 v[116:119], v2 offset:192
	s_waitcnt lgkmcnt(0)
	v_mfma_f32_16x16x32_bf16 v[120:123], v[96:99], v[116:119], v[128:131]
	v_mfma_f32_16x16x32_bf16 v[116:119], v[104:107], v[116:119], v[124:127]
	s_nop 2
	ds_read_b128 v[124:127], v2 offset:8640
	s_waitcnt lgkmcnt(0)
	v_mfma_f32_16x16x32_bf16 v[128:131], v[96:99], v[124:127], v[140:143]
	v_mfma_f32_16x16x32_bf16 v[124:127], v[104:107], v[124:127], v[132:135]
	s_nop 2
	ds_read_b128 v[132:135], v2 offset:17088
	s_waitcnt lgkmcnt(0)
	v_mfma_f32_16x16x32_bf16 v[140:143], v[96:99], v[132:135], v[144:147]
	v_mfma_f32_16x16x32_bf16 v[132:135], v[104:107], v[132:135], v[136:139]
	s_nop 2
	ds_read_b128 v[136:139], v2 offset:25536
	s_waitcnt lgkmcnt(0)
	v_mfma_f32_16x16x32_bf16 v[96:99], v[96:99], v[136:139], v[108:111]
	s_nop 2
	ds_read_b128 v[108:111], v2 offset:256
	v_mfma_f32_16x16x32_bf16 v[104:107], v[104:107], v[136:139], v[112:115]
	s_waitcnt lgkmcnt(0)
	v_mfma_f32_16x16x32_bf16 v[112:115], v[92:95], v[108:111], v[120:123]
	v_mfma_f32_16x16x32_bf16 v[108:111], v[100:103], v[108:111], v[116:119]
	s_nop 2
	ds_read_b128 v[116:119], v2 offset:8704
	s_waitcnt lgkmcnt(0)
	v_mfma_f32_16x16x32_bf16 v[120:123], v[92:95], v[116:119], v[128:131]
	v_mfma_f32_16x16x32_bf16 v[116:119], v[100:103], v[116:119], v[124:127]
	s_nop 2
	ds_read_b128 v[124:127], v2 offset:17152
	s_waitcnt lgkmcnt(0)
	v_mfma_f32_16x16x32_bf16 v[128:131], v[92:95], v[124:127], v[140:143]
	v_mfma_f32_16x16x32_bf16 v[124:127], v[100:103], v[124:127], v[132:135]
	s_nop 2
	ds_read_b128 v[132:135], v2 offset:25600
	s_waitcnt lgkmcnt(0)
	v_mfma_f32_16x16x32_bf16 v[92:95], v[92:95], v[132:135], v[96:99]
	v_mfma_f32_16x16x32_bf16 v[96:99], v[100:103], v[132:135], v[104:107]
	ds_read_b128 v[100:103], v2 offset:320
	s_waitcnt lgkmcnt(0)
	v_mfma_f32_16x16x32_bf16 v[104:107], v[80:83], v[100:103], v[112:115]
	v_mfma_f32_16x16x32_bf16 v[100:103], v[88:91], v[100:103], v[108:111]
	s_nop 2
	ds_read_b128 v[108:111], v2 offset:8768
	s_waitcnt lgkmcnt(0)
	v_mfma_f32_16x16x32_bf16 v[112:115], v[80:83], v[108:111], v[120:123]
	v_mfma_f32_16x16x32_bf16 v[108:111], v[88:91], v[108:111], v[116:119]
	s_nop 2
	ds_read_b128 v[116:119], v2 offset:17216
	s_waitcnt lgkmcnt(0)
	v_mfma_f32_16x16x32_bf16 v[120:123], v[80:83], v[116:119], v[128:131]
	v_mfma_f32_16x16x32_bf16 v[116:119], v[88:91], v[116:119], v[124:127]
	s_nop 2
	ds_read_b128 v[124:127], v2 offset:25664
	s_waitcnt lgkmcnt(0)
	v_mfma_f32_16x16x32_bf16 v[80:83], v[80:83], v[124:127], v[92:95]
	s_nop 2
	ds_read_b128 v[92:95], v2 offset:384
	v_mfma_f32_16x16x32_bf16 v[88:91], v[88:91], v[124:127], v[96:99]
	s_waitcnt lgkmcnt(0)
	v_mfma_f32_16x16x32_bf16 v[96:99], v[76:79], v[92:95], v[104:107]
	v_mfma_f32_16x16x32_bf16 v[92:95], v[84:87], v[92:95], v[100:103]
	s_nop 2
	ds_read_b128 v[100:103], v2 offset:8832
	s_waitcnt lgkmcnt(0)
	v_mfma_f32_16x16x32_bf16 v[104:107], v[76:79], v[100:103], v[112:115]
	v_mfma_f32_16x16x32_bf16 v[100:103], v[84:87], v[100:103], v[108:111]
	s_nop 2
	ds_read_b128 v[108:111], v2 offset:17280
	s_waitcnt lgkmcnt(0)
	v_mfma_f32_16x16x32_bf16 v[112:115], v[76:79], v[108:111], v[120:123]
	v_mfma_f32_16x16x32_bf16 v[108:111], v[84:87], v[108:111], v[116:119]
	s_nop 2
	ds_read_b128 v[116:119], v2 offset:25728
	s_waitcnt lgkmcnt(0)
	v_mfma_f32_16x16x32_bf16 v[120:123], v[76:79], v[116:119], v[80:83]
	ds_read_b128 v[76:79], v2 offset:448
	s_nop 1
	ds_read_b128 v[80:83], v2 offset:8896
	v_mfma_f32_16x16x32_bf16 v[116:119], v[84:87], v[116:119], v[88:91]
	ds_read_b128 v[84:87], v2 offset:17344
	s_waitcnt lgkmcnt(2)
	v_mfma_f32_16x16x32_bf16 v[88:91], v[68:71], v[76:79], v[96:99]
	s_waitcnt vmcnt(0)
	v_mfma_f32_16x16x32_bf16 v[76:79], v[72:75], v[76:79], v[92:95]
	s_waitcnt lgkmcnt(1)
	v_mfma_f32_16x16x32_bf16 v[92:95], v[68:71], v[80:83], v[104:107]
	v_mfma_f32_16x16x32_bf16 v[80:83], v[72:75], v[80:83], v[100:103]
	s_nop 2
	ds_read_b128 v[100:103], v2 offset:25792
	s_waitcnt lgkmcnt(1)
	v_mfma_f32_16x16x32_bf16 v[96:99], v[68:71], v[84:87], v[112:115]
	v_lshl_or_b32 v2, v0, 12, v182
	v_mfma_f32_16x16x32_bf16 v[84:87], v[72:75], v[84:87], v[108:111]
	s_waitcnt lgkmcnt(0)
; __device__ __forceinline__ float ex2(float x) { return __builtin_amdgcn_exp2f(x); }
; #define SB0 __builtin_amdgcn_sched_barrier(0)
; template <bool FWD>
; __device__ __forceinline__ void ret_sweep(const Params& p, int gs, int s, int g, int h, int sl, int nsegps, float lf, float lb) {
;     ...
;     bf16x8 kt[2][4];
;     ret_load_kt(kt, KT + (long)(h * 128 + chunk) * 256 * 128, w, fr, fq);
;     SB0;
;     int ibase = 32 * wi + fq * 4;
;     asm volatile("" : "+v"(ibase));
; #pragma unroll
;     for (int mb = 0; mb < 2; ++mb)
; #pragma unroll
;       for (int jj = 0; jj < 4; ++jj) {
;         int i = ibase + mb * 16 + jj;
;         float sc = FWD ? ex2(lf * (float)(i + 128)) : ex2(lb * (float)(255 - i));
; #pragma unroll
;         for (int nb = 0; nb < 4; ++nb) O[mb][nb][jj] *= sc;
;       }
;     if constexpr (FWD) {
; #pragma unroll
;       for (int ks = 0; ks < 4; ++ks) {
; #pragma unroll
;         for (int nb = 0; nb < 4; ++nb) {
;           bf16x8 b = *(const bf16x8*)(VTs + (64 * wv + nb * 16 + fr) * 136 + ks * 32 + fq * 8);
; #pragma unroll
;           for (int mb = 0; mb < 2; ++mb) O[mb][nb] = mfma16(pa[mb][ks], b, O[mb][nb]);
;         }
;       }
;     }
;     SB0;
;     if constexpr (!FWD) {
; #pragma unroll
;       for (int q = 0; q < 4; ++q) {
;         u32x4 pk;
; #pragma unroll
;         for (int e2 = 0; e2 < 4; ++e2) {
;           int e = q * 8 + e2 * 2;
;           pk[e2] = pack2(O[e >> 4][e & 3][(e >> 2) & 3], O[(e + 1) >> 4][(e + 1) & 3][((e + 1) >> 2) & 3]);
;         }
;         ypriv[q] = pk;
;       }
;     ...
;     ret_load_vt(vp, VT + ((long)(h * 128 + nchunk) * 512 + sl * 128) * 128, tid);
; #pragma unroll
;     for (int mb = 0; mb < 2; ++mb)
; #pragma unroll
;       for (int ks = 0; ks < 8; ++ks) qa[mb][ks] = *(const bf16x8*)(qnext + (mb * 16 * 2048 + ks * 32) * 2 + qofs2);
	v_mfma_f32_16x16x32_bf16 v[104:107], v[68:71], v[100:103], v[120:123]
	v_mfma_f32_16x16x32_bf16 v[68:71], v[72:75], v[100:103], v[116:119]
	v_lshlrev_b32_e32 v0, 7, v3
	v_and_b32_e32 v0, 0xffffe000, v0
	v_lshlrev_b32_e32 v72, 8, v181
	s_add_u32 s52, s48, s12
	v_or3_b32 v0, v0, v72, v182
	s_addc_u32 s53, s49, s13
	v_lshl_add_u64 v[72:73], s[52:53], 0, v[0:1]
	s_mov_b32 s17, 0x148f0000
	v_add_co_u32_e32 v74, vcc, s17, v72
	s_mov_b32 s17, 0x148f1000
	s_nop 0
	v_addc_co_u32_e32 v75, vcc, 0, v73, vcc
	v_add_co_u32_e32 v72, vcc, s17, v72
	s_nop 1
	v_addc_co_u32_e32 v73, vcc, 0, v73, vcc
	global_load_dwordx4 v[164:167], v[74:75], off offset:64
	global_load_dwordx4 v[156:159], v[74:75], off offset:128
	global_load_dwordx4 v[172:175], v[72:73], off offset:-4096
	global_load_dwordx4 v[148:151], v[74:75], off offset:192
	global_load_dwordx4 v[176:179], v[72:73], off
	global_load_dwordx4 v[168:171], v[72:73], off offset:64
	global_load_dwordx4 v[160:163], v[72:73], off offset:128
	global_load_dwordx4 v[152:155], v[72:73], off offset:192
	v_lshl_or_b32 v108, v185, 2, v186
	v_mov_b32_e32 v72, v88
	v_sub_u32_e32 v0, 0xff, v108
	v_cvt_f32_i32_e32 v0, v0
	v_mov_b32_e32 v73, v92
	v_mov_b32_e32 v74, v96
	v_mov_b32_e32 v75, v104
	v_mul_f32_e32 v0, v180, v0
	v_exp_f32_e32 v0, v0
	v_mov_b32_e32 v92, v89
	v_mov_b32_e32 v104, v97
	v_mov_b32_e32 v96, v90
	v_pk_mul_f32 v[72:73], v[72:73], v[0:1] op_sel_hi:[1,0]
	v_pk_mul_f32 v[74:75], v[74:75], v[0:1] op_sel_hi:[1,0]
	v_sub_u32_e32 v0, 0xfe, v108
	v_cvt_f32_i32_e32 v0, v0
	v_mov_b32_e32 v97, v94
	v_mov_b32_e32 v100, v98
	v_mov_b32_e32 v101, v106
	v_mul_f32_e32 v0, v180, v0
	v_exp_f32_e32 v0, v0
	v_mov_b32_e32 v94, v91
	v_mov_b32_e32 v106, v99
	v_mov_b32_e32 v98, v76
	v_pk_mul_f32 v[88:89], v[92:93], v[0:1] op_sel_hi:[1,0]
	v_pk_mul_f32 v[92:93], v[104:105], v[0:1] op_sel_hi:[1,0]
	v_sub_u32_e32 v0, 0xfd, v108
	v_cvt_f32_i32_e32 v0, v0
	v_mov_b32_e32 v99, v80
	v_mov_b32_e32 v102, v84
	v_mov_b32_e32 v103, v68
	v_mul_f32_e32 v0, v180, v0
	v_exp_f32_e32 v0, v0
	v_mov_b32_e32 v80, v77
	v_mov_b32_e32 v68, v85
	v_pk_mul_f32 v[96:97], v[96:97], v[0:1] op_sel_hi:[1,0]
	v_pk_mul_f32 v[100:101], v[100:101], v[0:1] op_sel_hi:[1,0]
	v_sub_u32_e32 v0, 0xfc, v108
	v_cvt_f32_i32_e32 v0, v0
	v_mul_f32_e32 v0, v180, v0
	v_exp_f32_e32 v0, v0
	s_nop 0
	v_pk_mul_f32 v[90:91], v[94:95], v[0:1] op_sel_hi:[1,0]
	v_pk_mul_f32 v[94:95], v[106:107], v[0:1] op_sel_hi:[1,0]
	v_sub_u32_e32 v0, 0xef, v108
	v_cvt_f32_i32_e32 v0, v0
	v_mul_f32_e32 v0, v180, v0
	v_exp_f32_e32 v0, v0
	s_nop 0
	v_pk_mul_f32 v[98:99], v[98:99], v[0:1] op_sel_hi:[1,0]
	v_pk_mul_f32 v[102:103], v[102:103], v[0:1] op_sel_hi:[1,0]
	v_sub_u32_e32 v0, 0xee, v108
	v_cvt_f32_i32_e32 v0, v0
	v_mul_f32_e32 v0, v180, v0
	v_exp_f32_e32 v0, v0
	s_nop 0
	v_pk_mul_f32 v[76:77], v[80:81], v[0:1] op_sel_hi:[1,0]
	v_pk_mul_f32 v[80:81], v[68:69], v[0:1] op_sel_hi:[1,0]
	v_sub_u32_e32 v0, 0xed, v108
	v_cvt_f32_i32_e32 v0, v0
	v_mov_b32_e32 v68, v78
	v_mov_b32_e32 v69, v82
	v_mov_b32_e32 v82, v79
	v_mul_f32_e32 v0, v180, v0
	v_exp_f32_e32 v0, v0
	s_nop 0
	v_pk_mul_f32 v[84:85], v[68:69], v[0:1] op_sel_hi:[1,0]
	v_mov_b32_e32 v68, v86
	v_mov_b32_e32 v69, v70
	v_pk_mul_f32 v[104:105], v[68:69], v[0:1] op_sel_hi:[1,0]
	v_sub_u32_e32 v0, 0xec, v108
	v_cvt_f32_i32_e32 v0, v0
	v_mov_b32_e32 v70, v87
	v_and_b32_e32 v68, 3, v183
	v_mul_f32_e32 v0, v180, v0
	v_exp_f32_e32 v0, v0
	s_nop 0
	v_pk_mul_f32 v[78:79], v[82:83], v[0:1] op_sel_hi:[1,0]
	v_pk_mul_f32 v[82:83], v[70:71], v[0:1] op_sel_hi:[1,0]
	v_mul_lo_u32 v0, v184, s58
	v_lshl_or_b32 v0, v68, 6, v0
	v_cvt_pk_bf16_f32 v68, v72, v73
	v_cvt_pk_bf16_f32 v69, v74, v75
	v_cvt_pk_bf16_f32 v70, v88, v89
	v_cvt_pk_bf16_f32 v71, v92, v93
	global_store_dwordx4 v0, v[68:71], s[4:5] offset:-32
	s_nop 1
	v_cvt_pk_bf16_f32 v68, v96, v97
	v_cvt_pk_bf16_f32 v69, v100, v101
	v_cvt_pk_bf16_f32 v70, v90, v91
	v_cvt_pk_bf16_f32 v71, v94, v95
	global_store_dwordx4 v0, v[68:71], s[4:5] offset:-16
	s_nop 1
	v_cvt_pk_bf16_f32 v68, v98, v99
	v_cvt_pk_bf16_f32 v69, v102, v103
	v_cvt_pk_bf16_f32 v70, v76, v77
	v_cvt_pk_bf16_f32 v71, v80, v81
	global_store_dwordx4 v0, v[68:71], s[4:5]
	s_nop 1
	v_cvt_pk_bf16_f32 v68, v84, v85
	v_cvt_pk_bf16_f32 v69, v104, v105
	v_cvt_pk_bf16_f32 v70, v78, v79
	v_cvt_pk_bf16_f32 v71, v82, v83
	global_store_dwordx4 v0, v[68:71], s[4:5] offset:16
	s_add_i32 s16, s16, s27
	s_ashr_i32 s17, s16, 31
	s_lshl_b64 s[16:17], s[16:17], 17
	s_add_u32 s16, s30, s16
	s_addc_u32 s17, s31, s17
	v_lshlrev_b32_e32 v0, 4, v3
	v_lshl_add_u64 v[68:69], s[16:17], 0, v[0:1]
	v_add_co_u32_e32 v70, vcc, s51, v68
	v_mov_b32_e32 v3, v1
	s_nop 0
	v_addc_co_u32_e32 v71, vcc, 0, v69, vcc
	global_load_dwordx4 v[128:131], v[70:71], off
	v_add_co_u32_e32 v70, vcc, s55, v68
	v_lshl_add_u64 v[72:73], s[18:19], 0, v[2:3]
	s_nop 0
	v_addc_co_u32_e32 v71, vcc, 0, v69, vcc
	v_add_co_u32_e32 v68, vcc, s56, v68
	global_load_dwordx4 v[124:127], v0, s[16:17]
	s_nop 0
	v_addc_co_u32_e32 v69, vcc, 0, v69, vcc
	global_load_dwordx4 v[132:135], v[70:71], off
	global_load_dwordx4 v[144:147], v[68:69], off
	global_load_dwordx4 v[136:139], v2, s[18:19]
	global_load_dwordx4 v[112:115], v2, s[18:19] offset:64
	global_load_dwordx4 v[108:111], v2, s[18:19] offset:128
	global_load_dwordx4 v[96:99], v2, s[18:19] offset:192
	global_load_dwordx4 v[92:95], v2, s[18:19] offset:256
	global_load_dwordx4 v[80:83], v2, s[18:19] offset:320
	global_load_dwordx4 v[76:79], v2, s[18:19] offset:384
	global_load_dwordx4 v[68:71], v2, s[18:19] offset:448
	v_add_co_u32_e32 v2, vcc, s54, v72
	s_nop 1
	v_addc_co_u32_e32 v3, vcc, 0, v73, vcc
	global_load_dwordx4 v[140:143], v[2:3], off
	global_load_dwordx4 v[120:123], v[2:3], off offset:64
	global_load_dwordx4 v[116:119], v[2:3], off offset:128
	global_load_dwordx4 v[104:107], v[2:3], off offset:192
	global_load_dwordx4 v[100:103], v[2:3], off offset:256
	global_load_dwordx4 v[88:91], v[2:3], off offset:320
	global_load_dwordx4 v[84:87], v[2:3], off offset:384
	global_load_dwordx4 v[72:75], v[2:3], off offset:448
	v_mul_u32_u24_e32 v0, 0x110, v181
	v_add3_u32 v0, s93, v182, v0
	ds_read_b128 v[182:185], v0
	v_pk_mul_f32 v[26:27], s[2:3], v[26:27]
	v_pk_mul_f32 v[24:25], s[0:1], v[24:25]
	v_pk_mul_f32 v[6:7], s[2:3], v[6:7]
	v_pk_mul_f32 v[4:5], s[0:1], v[4:5]
	s_waitcnt vmcnt(29) lgkmcnt(0)
; __device__ __forceinline__ void ret_state_mma(f32x4 (&T)[2][8], const bf16x8 (&kt)[2][4], const u16* VTs, float cd,
;                                               int fr, int fq) {
; #pragma unroll
;   for (int mb = 0; mb < 2; ++mb)
; #pragma unroll
;     for (int nb = 0; nb < 8; ++nb) T[mb][nb] *= cd;
; #pragma unroll
;   for (int ks = 0; ks < 4; ++ks)
; #pragma unroll
;     for (int nb = 0; nb < 8; ++nb) {
;       bf16x8 b = *(const bf16x8*)(VTs + (nb * 16 + fr) * 136 + ks * 32 + fq * 8);
; #pragma unroll
;       for (int mb = 0; mb < 2; ++mb) T[mb][nb] = mfma16(kt[mb][ks], b, T[mb][nb]);
;     }
; }
	v_mfma_f32_16x16x32_bf16 v[24:27], v[172:175], v[182:185], v[24:27]
	v_mul_f32_e64 v30, s2, v30
	v_mul_f32_e64 v31, s3, v31
	v_pk_mul_f32 v[28:29], s[0:1], v[28:29]
	v_pk_mul_f32 v[10:11], s[2:3], v[10:11]
	s_waitcnt vmcnt(27)
	v_mfma_f32_16x16x32_bf16 v[182:185], v[176:179], v[182:185], v[4:7]
	v_mul_f32_e64 v8, s0, v8
	v_mul_f32_e64 v9, s1, v9
	v_pk_mul_f32 v[38:39], s[2:3], v[38:39]
	v_pk_mul_f32 v[36:37], s[0:1], v[36:37]
	ds_read_b128 v[2:5], v0 offset:4352
	s_waitcnt lgkmcnt(0)
	v_mfma_f32_16x16x32_bf16 v[28:31], v[172:175], v[2:5], v[28:31]
	v_mul_f32_e64 v14, s2, v14
	v_mul_f32_e64 v15, s3, v15
	v_pk_mul_f32 v[12:13], s[0:1], v[12:13]
	v_pk_mul_f32 v[50:51], s[2:3], v[50:51]
	v_mfma_f32_16x16x32_bf16 v[186:189], v[176:179], v[2:5], v[8:11]
	ds_read_b128 v[2:5], v0 offset:8704
	v_pk_mul_f32 v[48:49], s[0:1], v[48:49]
	v_pk_mul_f32 v[18:19], s[2:3], v[18:19]
	ds_read_b128 v[6:9], v0 offset:30464
	s_waitcnt lgkmcnt(1)
	v_mfma_f32_16x16x32_bf16 v[36:39], v[172:175], v[2:5], v[36:39]
	v_mul_f32_e64 v16, s0, v16
	v_mul_f32_e64 v17, s1, v17
	v_pk_mul_f32 v[54:55], s[2:3], v[54:55]
	v_pk_mul_f32 v[52:53], s[0:1], v[52:53]
	v_mfma_f32_16x16x32_bf16 v[190:193], v[176:179], v[2:5], v[12:15]
	ds_read_b128 v[2:5], v0 offset:13056
	v_pk_mul_f32 v[22:23], s[2:3], v[22:23]
	v_pk_mul_f32 v[20:21], s[0:1], v[20:21]
	s_waitcnt lgkmcnt(0)
	v_mfma_f32_16x16x32_bf16 v[48:51], v[172:175], v[2:5], v[48:51]
	v_mul_f32_e64 v58, s2, v58
	v_mul_f32_e64 v59, s3, v59
	v_pk_mul_f32 v[56:57], s[0:1], v[56:57]
	v_pk_mul_f32 v[34:35], s[2:3], v[34:35]
	v_mfma_f32_16x16x32_bf16 v[194:197], v[176:179], v[2:5], v[16:19]
	ds_read_b128 v[2:5], v0 offset:17408
	v_pk_mul_f32 v[32:33], s[0:1], v[32:33]
	v_pk_mul_f32 v[62:63], s[2:3], v[62:63]
	s_waitcnt lgkmcnt(0)
	v_mfma_f32_16x16x32_bf16 v[52:55], v[172:175], v[2:5], v[52:55]
	v_mul_f32_e64 v60, s0, v60
	v_mul_f32_e64 v61, s1, v61
	v_pk_mul_f32 v[66:67], s[2:3], v[66:67]
	v_pk_mul_f32 v[64:65], s[0:1], v[64:65]
	v_mfma_f32_16x16x32_bf16 v[18:21], v[176:179], v[2:5], v[20:23]
	ds_read_b128 v[2:5], v0 offset:21760
	v_pk_mul_f32 v[42:43], s[2:3], v[42:43]
	v_pk_mul_f32 v[40:41], s[0:1], v[40:41]
	s_waitcnt lgkmcnt(0)
	v_mfma_f32_16x16x32_bf16 v[56:59], v[172:175], v[2:5], v[56:59]
	v_mul_f32_e64 v46, s2, v46
	v_mul_f32_e64 v47, s3, v47
	v_pk_mul_f32 v[44:45], s[0:1], v[44:45]
	s_add_i32 s50, s50, -1
	v_mfma_f32_16x16x32_bf16 v[32:35], v[176:179], v[2:5], v[32:35]
	ds_read_b128 v[2:5], v0 offset:26112
	s_add_u32 s12, s12, 0xffff0000
	s_addc_u32 s13, s13, -1
	s_waitcnt lgkmcnt(0)
	v_mfma_f32_16x16x32_bf16 v[10:13], v[172:175], v[2:5], v[60:63]
	s_add_u32 s4, s4, 0xffef8000
	s_nop 1
	ds_read_b128 v[60:63], v0 offset:8768
	s_addc_u32 s5, s5, -1
	v_mfma_f32_16x16x32_bf16 v[14:17], v[176:179], v[2:5], v[40:43]
	s_cmp_lg_u32 s50, -2
	v_mfma_f32_16x16x32_bf16 v[2:5], v[172:175], v[6:9], v[64:67]
	ds_read_b128 v[172:175], v0 offset:17472
	ds_read_b128 v[40:43], v0 offset:64
	v_mfma_f32_16x16x32_bf16 v[6:9], v[176:179], v[6:9], v[44:47]
	ds_read_b128 v[64:67], v0 offset:13120
	s_nop 1
	ds_read_b128 v[44:47], v0 offset:4416
	s_waitcnt lgkmcnt(3)
	v_mfma_f32_16x16x32_bf16 v[52:55], v[164:167], v[172:175], v[52:55]
	s_waitcnt vmcnt(26)
	v_mfma_f32_16x16x32_bf16 v[18:21], v[168:171], v[172:175], v[18:21]
	ds_read_b128 v[172:175], v0 offset:21824
	s_waitcnt lgkmcnt(3)
	v_mfma_f32_16x16x32_bf16 v[22:25], v[164:167], v[40:43], v[24:27]
	s_waitcnt lgkmcnt(1)
	v_mfma_f32_16x16x32_bf16 v[26:29], v[164:167], v[44:47], v[28:31]
	s_waitcnt lgkmcnt(0)
	v_mfma_f32_16x16x32_bf16 v[56:59], v[164:167], v[172:175], v[56:59]
	v_mfma_f32_16x16x32_bf16 v[30:33], v[168:171], v[172:175], v[32:35]
	ds_read_b128 v[172:175], v0 offset:26176
	s_waitcnt lgkmcnt(0)
	v_mfma_f32_16x16x32_bf16 v[10:13], v[164:167], v[172:175], v[10:13]
	v_mfma_f32_16x16x32_bf16 v[14:17], v[168:171], v[172:175], v[14:17]
	ds_read_b128 v[172:175], v0 offset:30528
	v_mfma_f32_16x16x32_bf16 v[36:39], v[164:167], v[60:63], v[36:39]
	v_mfma_f32_16x16x32_bf16 v[48:51], v[164:167], v[64:67], v[48:51]
	s_waitcnt lgkmcnt(0)
	v_mfma_f32_16x16x32_bf16 v[2:5], v[164:167], v[172:175], v[2:5]
	ds_read_b128 v[164:167], v0 offset:128
	v_mfma_f32_16x16x32_bf16 v[40:43], v[168:171], v[40:43], v[182:185]
	s_waitcnt lgkmcnt(0)
	v_mfma_f32_16x16x32_bf16 v[22:25], v[156:159], v[164:167], v[22:25]
	s_waitcnt vmcnt(25)
	v_mfma_f32_16x16x32_bf16 v[40:43], v[160:163], v[164:167], v[40:43]
	ds_read_b128 v[164:167], v0 offset:4480
	v_mfma_f32_16x16x32_bf16 v[44:47], v[168:171], v[44:47], v[186:189]
	v_mfma_f32_16x16x32_bf16 v[60:63], v[168:171], v[60:63], v[190:193]
	v_mfma_f32_16x16x32_bf16 v[64:67], v[168:171], v[64:67], v[194:197]
	v_mfma_f32_16x16x32_bf16 v[6:9], v[168:171], v[172:175], v[6:9]
	s_waitcnt lgkmcnt(0)
	v_mfma_f32_16x16x32_bf16 v[168:171], v[156:159], v[164:167], v[26:29]
	s_nop 2
	ds_read_b128 v[26:29], v0 offset:8832
	s_waitcnt lgkmcnt(0)
	v_mfma_f32_16x16x32_bf16 v[34:37], v[156:159], v[26:29], v[36:39]
	v_mfma_f32_16x16x32_bf16 v[60:63], v[160:163], v[26:29], v[60:63]
	ds_read_b128 v[26:29], v0 offset:13184
	s_waitcnt lgkmcnt(0)
	v_mfma_f32_16x16x32_bf16 v[48:51], v[156:159], v[26:29], v[48:51]
	v_mfma_f32_16x16x32_bf16 v[64:67], v[160:163], v[26:29], v[64:67]
	ds_read_b128 v[26:29], v0 offset:17536
	v_mfma_f32_16x16x32_bf16 v[44:47], v[160:163], v[164:167], v[44:47]
	s_waitcnt lgkmcnt(0)
	v_mfma_f32_16x16x32_bf16 v[164:167], v[160:163], v[26:29], v[18:21]
	s_nop 2
	ds_read_b128 v[18:21], v0 offset:21888
	s_waitcnt lgkmcnt(0)
	v_mfma_f32_16x16x32_bf16 v[56:59], v[156:159], v[18:21], v[56:59]
	v_mfma_f32_16x16x32_bf16 v[172:175], v[160:163], v[18:21], v[30:33]
	ds_read_b128 v[18:21], v0 offset:26240
	s_waitcnt lgkmcnt(0)
	v_mfma_f32_16x16x32_bf16 v[176:179], v[156:159], v[18:21], v[10:13]
	s_nop 2
	ds_read_b128 v[10:13], v0 offset:30592
	v_mfma_f32_16x16x32_bf16 v[52:55], v[156:159], v[26:29], v[52:55]
	v_mfma_f32_16x16x32_bf16 v[182:185], v[160:163], v[18:21], v[14:17]
	s_waitcnt lgkmcnt(0)
	v_mfma_f32_16x16x32_bf16 v[156:159], v[156:159], v[10:13], v[2:5]
	s_nop 0
	ds_read_b128 v[16:19], v0 offset:13248
	v_mfma_f32_16x16x32_bf16 v[160:163], v[160:163], v[10:13], v[6:9]
	ds_read_b128 v[2:5], v0 offset:192
	ds_read_b128 v[12:15], v0 offset:8896
	s_nop 0
	ds_read_b128 v[8:11], v0 offset:4544
	s_waitcnt lgkmcnt(2)
	v_mfma_f32_16x16x32_bf16 v[24:27], v[148:151], v[2:5], v[22:25]
	s_nop 2
	ds_read_b128 v[20:23], v0 offset:17600
	s_waitcnt vmcnt(24)
	v_mfma_f32_16x16x32_bf16 v[4:7], v[152:155], v[2:5], v[40:43]
	s_waitcnt lgkmcnt(1)
	v_mfma_f32_16x16x32_bf16 v[28:31], v[148:151], v[8:11], v[168:171]
	s_nop 0
	ds_read_b128 v[40:43], v0 offset:26304
	v_mfma_f32_16x16x32_bf16 v[8:11], v[152:155], v[8:11], v[44:47]
	v_mfma_f32_16x16x32_bf16 v[36:39], v[148:151], v[12:15], v[34:37]
	s_nop 1
	ds_read_b128 v[44:47], v0 offset:30656
	ds_read_b128 v[32:35], v0 offset:21952
	v_mfma_f32_16x16x32_bf16 v[12:15], v[152:155], v[12:15], v[60:63]
	s_waitcnt lgkmcnt(0)
	s_barrier
; __device__ __forceinline__ float ex2(float x) { return __builtin_amdgcn_exp2f(x); }
; __device__ __forceinline__ float uni(float x) { return __int_as_float(__builtin_amdgcn_readfirstlane(__float_as_int(x))); }
; template <bool FWD>
; __device__ __forceinline__ void ret_sweep(const Params& p, int gs, int s, int g, int h, int sl, int nsegps, float lf, float lb) {
;     ...
;   const float lg = FWD ? lf : lb;
;   const float cd = uni(ex2(lg * 128.f));
;   f32x4 T[2][8];
; #pragma unroll
;   for (int mb = 0; mb < 2; ++mb)
; #pragma unroll
;     for (int nb = 0; nb < 8; ++nb) T[mb][nb] = f32x4{0.f, 0.f, 0.f, 0.f};
;   {
;     constexpr int dir = FWD ? 0 : 1;
;     float cdS = uni(ex2(lg * (128.f * SEG)));
;     int gp = dir ? nsegps - 1 : 0;
;     int cnt = dir ? nsegps - 1 - g : g;
; #pragma unroll 1
;     for (int q = 0; q < cnt; ++q) {
;       int tq = get_tid(p.wid);
;       const f32x4* src = (const f32x4*)((const char*)(ST + (long)(((((s * nsegps + gp) * 8 + h) * 2 + dir) * 4) + sl) * 32768) + (unsigned)(tq * 256));
; #pragma unroll
;       for (int mb = 0; mb < 2; ++mb)
; #pragma unroll
;         for (int nb = 0; nb < 8; ++nb) T[mb][nb] = T[mb][nb] * cdS + src[mb * 8 + nb];
	v_mfma_f32_16x16x32_bf16 v[48:51], v[148:151], v[16:19], v[48:51]
	v_mfma_f32_16x16x32_bf16 v[16:19], v[152:155], v[16:19], v[64:67]
	v_mfma_f32_16x16x32_bf16 v[52:55], v[148:151], v[20:23], v[52:55]
	v_mfma_f32_16x16x32_bf16 v[20:23], v[152:155], v[20:23], v[164:167]
	v_mfma_f32_16x16x32_bf16 v[56:59], v[148:151], v[32:35], v[56:59]
	v_mfma_f32_16x16x32_bf16 v[32:35], v[152:155], v[32:35], v[172:175]
	v_mfma_f32_16x16x32_bf16 v[60:63], v[148:151], v[40:43], v[176:179]
	v_mfma_f32_16x16x32_bf16 v[40:43], v[152:155], v[40:43], v[182:185]
	v_mfma_f32_16x16x32_bf16 v[64:67], v[148:151], v[44:47], v[156:159]
	v_mfma_f32_16x16x32_bf16 v[44:47], v[152:155], v[44:47], v[160:163]
	s_cbranch_scc1 .LBB0_126
	v_mov_b32_e32 v0, 0x3fb8aa3b
	v_mul_f32_e32 v251, s44, v0
	v_mul_f32_e32 v0, 0x43000000, v251
	v_exp_f32_e32 v0, v0
	s_movk_i32 s49, 0xffc0
	s_movk_i32 s48, 0x6000
	s_cmp_lt_i32 s15, 1
	v_readfirstlane_b32 s12, v0
	v_mul_f32_e32 v0, 0x45000000, v251
	v_exp_f32_e32 v0, v0
	s_nop 0
	v_readfirstlane_b32 s0, v0
	s_cbranch_scc1 .LBB0_130
	s_lshl_b32 s4, s43, s22
	s_lshl_b32 s4, s4, 6
	s_or_b32 s4, s4, s40
	v_mov_b32_e32 v60, 0
	v_readlane_b32 s18, v253, 3
	s_mov_b32 s1, s0
	s_mov_b32 s2, s0
	s_mov_b32 s3, s0
	s_add_i32 s4, s4, s41
	v_mov_b32_e32 v61, v60
	v_mov_b32_e32 v62, v60
	v_mov_b32_e32 v63, v60
	v_mov_b32_e32 v40, v60
	v_mov_b32_e32 v41, v60
	v_mov_b32_e32 v42, v60
	v_mov_b32_e32 v43, v60
	v_mov_b32_e32 v32, v60
	v_mov_b32_e32 v33, v60
	v_mov_b32_e32 v34, v60
	v_mov_b32_e32 v35, v60
	v_mov_b32_e32 v24, v60
	v_mov_b32_e32 v25, v60
	v_mov_b32_e32 v26, v60
	v_mov_b32_e32 v27, v60
	v_mov_b32_e32 v16, v60
	v_mov_b32_e32 v17, v60
	v_mov_b32_e32 v18, v60
	v_mov_b32_e32 v19, v60
	v_mov_b32_e32 v12, v60
	v_mov_b32_e32 v13, v60
	v_mov_b32_e32 v14, v60
	v_mov_b32_e32 v15, v60
	v_mov_b32_e32 v8, v60
	v_mov_b32_e32 v9, v60
	v_mov_b32_e32 v10, v60
	v_mov_b32_e32 v11, v60
	v_mov_b32_e32 v4, v60
	v_mov_b32_e32 v5, v60
	v_mov_b32_e32 v6, v60
	v_mov_b32_e32 v7, v60
	v_mov_b32_e32 v64, v60
	v_mov_b32_e32 v65, v60
	v_mov_b32_e32 v66, v60
	v_mov_b32_e32 v67, v60
	v_mov_b32_e32 v56, v60
	v_mov_b32_e32 v57, v60
	v_mov_b32_e32 v58, v60
	v_mov_b32_e32 v59, v60
	v_mov_b32_e32 v52, v60
	v_mov_b32_e32 v53, v60
	v_mov_b32_e32 v54, v60
	v_mov_b32_e32 v55, v60
	v_mov_b32_e32 v48, v60
	v_mov_b32_e32 v49, v60
	v_mov_b32_e32 v50, v60
	v_mov_b32_e32 v51, v60
	v_mov_b32_e32 v44, v60
	v_mov_b32_e32 v45, v60
	v_mov_b32_e32 v46, v60
	v_mov_b32_e32 v47, v60
	v_mov_b32_e32 v36, v60
	v_mov_b32_e32 v37, v60
	v_mov_b32_e32 v38, v60
	v_mov_b32_e32 v39, v60
	v_mov_b32_e32 v28, v60
	v_mov_b32_e32 v29, v60
	v_mov_b32_e32 v30, v60
	v_mov_b32_e32 v31, v60
	v_mov_b32_e32 v20, v60
	v_mov_b32_e32 v21, v60
	v_mov_b32_e32 v22, v60
	v_mov_b32_e32 v23, v60
	v_readlane_b32 s19, v253, 4
	v_readlane_b32 s13, v253, 8
	v_readlane_b32 s40, v254, 52

; #define WAIT_L(n) asm volatile("s_waitcnt lgkmcnt(" #n ")" ::: "memory")
; #define BAR __builtin_amdgcn_s_barrier()
; #define SCHED __builtin_amdgcn_sched_barrier(0)
; __device__ __forceinline__ void mainloop_8phase(const u16* __restrict__ A, const u16* __restrict__ Bt, int K,
;                                                 f32x4 (&acc)[2][2][4][2], int wid_s, int ld) {
;     ...
;   for (int t = 0; t < nt - 2; t += 2) {
;     LDB(B0, 0, 0); SCHED; LDA(At, 0, 0); STAGE(SA(1, 1), A, brow + G_HALF, t + 1);
;     WAIT_L(8); BAR; WAIT_L(0); MMA(0, 0, At, B0); BAR; SCHED;
;     LDB(B1, 0, 1); STAGE(SB(0, 0), Bt, bcol, t + 2);
;     BAR; WAIT_L(0); MMA(0, 1, At, B1); BAR;
;     LDA(At, 0, 1); STAGE(SA(0, 0), A, brow, t + 2);
;     BAR; WAIT_L(0); MMA(1, 0, At, B0); BAR; SCHED;
.LBB0_162:
	ds_read_b128 v[156:159], v148
	ds_read_b128 v[160:163], v148 offset:1024
	ds_read_b128 v[164:167], v148 offset:2048
	ds_read_b128 v[168:171], v148 offset:3072
	v_readfirstlane_b32 s7, v150
	s_add_i32 s6, s3, 0xffffff00
	s_mov_b32 m0, s7
	v_readfirstlane_b32 s7, v149
	ds_read_b128 v[172:175], v133
	ds_read_b128 v[176:179], v133 offset:1024
	ds_read_b128 v[180:183], v132
	ds_read_b128 v[184:187], v132 offset:1024
	ds_read_b128 v[188:191], v131
	ds_read_b128 v[192:195], v131 offset:1024
	ds_read_b128 v[196:199], v130
	ds_read_b128 v[200:203], v130 offset:1024
	buffer_load_dwordx4 v137, s[88:91], s6 offen lds
	s_mov_b32 m0, s7
	s_nop 0
	buffer_load_dwordx4 v136, s[88:91], s6 offen lds
	s_waitcnt lgkmcnt(8)
	s_barrier
	s_waitcnt lgkmcnt(0)
	s_waitcnt lgkmcnt(7)
	v_mfma_f32_16x16x32_bf16 v[126:129], v[172:175], v[156:159], v[126:129]
	v_mfma_f32_16x16x32_bf16 v[122:125], v[172:175], v[164:167], v[122:125]
	s_waitcnt lgkmcnt(5)
	v_mfma_f32_16x16x32_bf16 v[118:121], v[180:183], v[156:159], v[118:121]
	v_mfma_f32_16x16x32_bf16 v[114:117], v[180:183], v[164:167], v[114:117]
	s_waitcnt lgkmcnt(3)
	v_mfma_f32_16x16x32_bf16 v[110:113], v[188:191], v[156:159], v[110:113]
	v_mfma_f32_16x16x32_bf16 v[106:109], v[188:191], v[164:167], v[106:109]
	s_waitcnt lgkmcnt(1)
	v_mfma_f32_16x16x32_bf16 v[102:105], v[196:199], v[156:159], v[102:105]
	v_mfma_f32_16x16x32_bf16 v[98:101], v[196:199], v[164:167], v[98:101]
	v_mfma_f32_16x16x32_bf16 v[126:129], v[176:179], v[160:163], v[126:129]
	v_mfma_f32_16x16x32_bf16 v[122:125], v[176:179], v[168:171], v[122:125]
	v_mfma_f32_16x16x32_bf16 v[118:121], v[184:187], v[160:163], v[118:121]
	v_mfma_f32_16x16x32_bf16 v[114:117], v[184:187], v[168:171], v[114:117]
	v_mfma_f32_16x16x32_bf16 v[110:113], v[192:195], v[160:163], v[110:113]
	v_mfma_f32_16x16x32_bf16 v[106:109], v[192:195], v[168:171], v[106:109]
	s_waitcnt lgkmcnt(0)
	v_mfma_f32_16x16x32_bf16 v[102:105], v[200:203], v[160:163], v[102:105]
	v_mfma_f32_16x16x32_bf16 v[98:101], v[200:203], v[168:171], v[98:101]
	s_barrier
	v_readfirstlane_b32 s16, v146
	s_add_i32 s15, s3, 0xfff7ff80
	s_mov_b32 s6, s90
	s_mov_b32 s7, s91
	s_mov_b32 m0, s16
	v_readfirstlane_b32 s16, v151
	ds_read_b128 v[204:207], v145
	ds_read_b128 v[208:211], v145 offset:1024
	ds_read_b128 v[212:215], v145 offset:2048
	ds_read_b128 v[216:219], v145 offset:3072
	buffer_load_dwordx4 v137, s[4:7], s15 offen lds
	s_mov_b32 m0, s16
	s_nop 0
	buffer_load_dwordx4 v136, s[4:7], s15 offen lds
	s_barrier
	s_waitcnt lgkmcnt(0)
	s_waitcnt lgkmcnt(3)
	v_mfma_f32_16x16x32_bf16 v[94:97], v[172:175], v[204:207], v[94:97]
	s_waitcnt lgkmcnt(1)
	v_mfma_f32_16x16x32_bf16 v[90:93], v[172:175], v[212:215], v[90:93]
	v_mfma_f32_16x16x32_bf16 v[86:89], v[180:183], v[204:207], v[86:89]
	v_mfma_f32_16x16x32_bf16 v[82:85], v[180:183], v[212:215], v[82:85]
	v_mfma_f32_16x16x32_bf16 v[78:81], v[188:191], v[204:207], v[78:81]
	v_mfma_f32_16x16x32_bf16 v[74:77], v[188:191], v[212:215], v[74:77]
	v_mfma_f32_16x16x32_bf16 v[70:73], v[196:199], v[204:207], v[70:73]
	v_mfma_f32_16x16x32_bf16 v[66:69], v[196:199], v[212:215], v[66:69]
	v_mfma_f32_16x16x32_bf16 v[94:97], v[176:179], v[208:211], v[94:97]
	s_waitcnt lgkmcnt(0)
	v_mfma_f32_16x16x32_bf16 v[90:93], v[176:179], v[216:219], v[90:93]
	v_mfma_f32_16x16x32_bf16 v[86:89], v[184:187], v[208:211], v[86:89]
	v_mfma_f32_16x16x32_bf16 v[82:85], v[184:187], v[216:219], v[82:85]
	v_mfma_f32_16x16x32_bf16 v[78:81], v[192:195], v[208:211], v[78:81]
	v_mfma_f32_16x16x32_bf16 v[74:77], v[192:195], v[216:219], v[74:77]
	v_mfma_f32_16x16x32_bf16 v[70:73], v[200:203], v[208:211], v[70:73]
	v_mfma_f32_16x16x32_bf16 v[66:69], v[200:203], v[216:219], v[66:69]
	v_readfirstlane_b32 s16, v140
	s_mov_b32 m0, s16
	v_readfirstlane_b32 s16, v152
	s_barrier
	ds_read_b128 v[172:175], v133 offset:16384
	ds_read_b128 v[176:179], v133 offset:17408
	ds_read_b128 v[180:183], v132 offset:16384
	ds_read_b128 v[184:187], v132 offset:17408
	ds_read_b128 v[188:191], v131 offset:16384
	ds_read_b128 v[192:195], v131 offset:17408
	ds_read_b128 v[196:199], v130 offset:16384
	ds_read_b128 v[200:203], v130 offset:17408
	buffer_load_dwordx4 v137, s[88:91], s15 offen lds
	s_mov_b32 m0, s16
	s_nop 0
	buffer_load_dwordx4 v136, s[88:91], s15 offen lds
	s_barrier
	s_waitcnt lgkmcnt(0)
	s_waitcnt lgkmcnt(7)
	v_mfma_f32_16x16x32_bf16 v[62:65], v[172:175], v[156:159], v[62:65]
	v_mfma_f32_16x16x32_bf16 v[58:61], v[172:175], v[164:167], v[58:61]
	s_waitcnt lgkmcnt(5)
	v_mfma_f32_16x16x32_bf16 v[54:57], v[180:183], v[156:159], v[54:57]
	v_mfma_f32_16x16x32_bf16 v[50:53], v[180:183], v[164:167], v[50:53]
	s_waitcnt lgkmcnt(3)
	v_mfma_f32_16x16x32_bf16 v[46:49], v[188:191], v[156:159], v[46:49]
	v_mfma_f32_16x16x32_bf16 v[42:45], v[188:191], v[164:167], v[42:45]
	s_waitcnt lgkmcnt(1)
	v_mfma_f32_16x16x32_bf16 v[38:41], v[196:199], v[156:159], v[38:41]
	v_mfma_f32_16x16x32_bf16 v[34:37], v[196:199], v[164:167], v[34:37]
	v_mfma_f32_16x16x32_bf16 v[62:65], v[176:179], v[160:163], v[62:65]
	v_mfma_f32_16x16x32_bf16 v[58:61], v[176:179], v[168:171], v[58:61]
	v_mfma_f32_16x16x32_bf16 v[54:57], v[184:187], v[160:163], v[54:57]
	v_mfma_f32_16x16x32_bf16 v[50:53], v[184:187], v[168:171], v[50:53]
	v_mfma_f32_16x16x32_bf16 v[46:49], v[192:195], v[160:163], v[46:49]
	v_mfma_f32_16x16x32_bf16 v[42:45], v[192:195], v[168:171], v[42:45]
	s_waitcnt lgkmcnt(0)
	v_mfma_f32_16x16x32_bf16 v[38:41], v[200:203], v[160:163], v[38:41]
	v_mfma_f32_16x16x32_bf16 v[34:37], v[200:203], v[168:171], v[34:37]
	s_barrier
; #define WAIT_V(n) asm volatile("s_waitcnt vmcnt(" #n ")" ::: "memory")
; #define WAIT_L(n) asm volatile("s_waitcnt lgkmcnt(" #n ")" ::: "memory")
; #define BAR __builtin_amdgcn_s_barrier()
; #define SCHED __builtin_amdgcn_sched_barrier(0)
; __device__ __forceinline__ void mainloop_8phase(const u16* __restrict__ A, const u16* __restrict__ Bt, int K,
;                                                 f32x4 (&acc)[2][2][4][2], int wid_s, int ld) {
;     ...
;     STAGE(SB(0, 1), Bt, bcol + G_HALF, t + 2);
;     WAIT_V(6); BAR; MMA(1, 1, At, B1); BAR;
;     LDB(B0, 1, 0); SCHED; LDA(At, 1, 0); STAGE(SA(0, 1), A, brow + G_HALF, t + 2);
;     WAIT_L(8); BAR; WAIT_L(0); MMA(0, 0, At, B0); BAR; SCHED;
;     LDB(B1, 1, 1); STAGE(SB(1, 0), Bt, bcol, t + 3);
;     BAR; WAIT_L(0); MMA(0, 1, At, B1); BAR;
;     LDA(At, 1, 1); STAGE(SA(1, 0), A, brow, t + 3);
	v_readfirstlane_b32 s16, v147
	s_add_i32 s15, s3, 0xffffff80
	s_mov_b32 m0, s16
	v_readfirstlane_b32 s16, v153
	buffer_load_dwordx4 v137, s[4:7], s15 offen lds
	s_mov_b32 m0, s16
	s_nop 0
	buffer_load_dwordx4 v136, s[4:7], s15 offen lds
	s_waitcnt vmcnt(6)
	s_barrier
	v_mfma_f32_16x16x32_bf16 v[30:33], v[172:175], v[204:207], v[30:33]
	v_mfma_f32_16x16x32_bf16 v[26:29], v[172:175], v[212:215], v[26:29]
	v_mfma_f32_16x16x32_bf16 v[22:25], v[180:183], v[204:207], v[22:25]
	v_mfma_f32_16x16x32_bf16 v[18:21], v[180:183], v[212:215], v[18:21]
	v_mfma_f32_16x16x32_bf16 v[14:17], v[188:191], v[204:207], v[14:17]
	v_mfma_f32_16x16x32_bf16 v[10:13], v[188:191], v[212:215], v[10:13]
	v_mfma_f32_16x16x32_bf16 v[6:9], v[196:199], v[204:207], v[6:9]
	v_mfma_f32_16x16x32_bf16 v[2:5], v[196:199], v[212:215], v[2:5]
	v_mfma_f32_16x16x32_bf16 v[30:33], v[176:179], v[208:211], v[30:33]
	v_mfma_f32_16x16x32_bf16 v[26:29], v[176:179], v[216:219], v[26:29]
	v_mfma_f32_16x16x32_bf16 v[22:25], v[184:187], v[208:211], v[22:25]
	v_mfma_f32_16x16x32_bf16 v[18:21], v[184:187], v[216:219], v[18:21]
	v_mfma_f32_16x16x32_bf16 v[14:17], v[192:195], v[208:211], v[14:17]
	v_mfma_f32_16x16x32_bf16 v[10:13], v[192:195], v[216:219], v[10:13]
	v_mfma_f32_16x16x32_bf16 v[6:9], v[200:203], v[208:211], v[6:9]
	v_mfma_f32_16x16x32_bf16 v[2:5], v[200:203], v[216:219], v[2:5]
	s_barrier
	ds_read_b128 v[156:159], v135
	ds_read_b128 v[160:163], v135 offset:1024
	ds_read_b128 v[164:167], v135 offset:2048
	ds_read_b128 v[168:171], v135 offset:3072
	v_readfirstlane_b32 s16, v154
	s_mov_b32 m0, s16
	v_readfirstlane_b32 s16, v155
	ds_read_b128 v[172:175], v133 offset:32768
	ds_read_b128 v[176:179], v133 offset:33792
	ds_read_b128 v[180:183], v132 offset:32768
	ds_read_b128 v[184:187], v132 offset:33792
	ds_read_b128 v[188:191], v131 offset:32768
	ds_read_b128 v[192:195], v131 offset:33792
	ds_read_b128 v[196:199], v130 offset:32768
	ds_read_b128 v[200:203], v130 offset:33792
	buffer_load_dwordx4 v137, s[88:91], s15 offen lds
	s_mov_b32 m0, s16
	s_nop 0
	buffer_load_dwordx4 v136, s[88:91], s15 offen lds
	s_waitcnt lgkmcnt(8)
	s_barrier
	s_waitcnt lgkmcnt(0)
	s_waitcnt lgkmcnt(7)
	v_mfma_f32_16x16x32_bf16 v[126:129], v[172:175], v[156:159], v[126:129]
	v_mfma_f32_16x16x32_bf16 v[122:125], v[172:175], v[164:167], v[122:125]
	s_waitcnt lgkmcnt(5)
	v_mfma_f32_16x16x32_bf16 v[118:121], v[180:183], v[156:159], v[118:121]
	v_mfma_f32_16x16x32_bf16 v[114:117], v[180:183], v[164:167], v[114:117]
	s_waitcnt lgkmcnt(3)
	v_mfma_f32_16x16x32_bf16 v[110:113], v[188:191], v[156:159], v[110:113]
	v_mfma_f32_16x16x32_bf16 v[106:109], v[188:191], v[164:167], v[106:109]
	s_waitcnt lgkmcnt(1)
	v_mfma_f32_16x16x32_bf16 v[102:105], v[196:199], v[156:159], v[102:105]
	v_mfma_f32_16x16x32_bf16 v[98:101], v[196:199], v[164:167], v[98:101]
	v_mfma_f32_16x16x32_bf16 v[126:129], v[176:179], v[160:163], v[126:129]
	v_mfma_f32_16x16x32_bf16 v[122:125], v[176:179], v[168:171], v[122:125]
	v_mfma_f32_16x16x32_bf16 v[118:121], v[184:187], v[160:163], v[118:121]
	v_mfma_f32_16x16x32_bf16 v[114:117], v[184:187], v[168:171], v[114:117]
	v_mfma_f32_16x16x32_bf16 v[110:113], v[192:195], v[160:163], v[110:113]
	v_mfma_f32_16x16x32_bf16 v[106:109], v[192:195], v[168:171], v[106:109]
	s_waitcnt lgkmcnt(0)
	v_mfma_f32_16x16x32_bf16 v[102:105], v[200:203], v[160:163], v[102:105]
	v_mfma_f32_16x16x32_bf16 v[98:101], v[200:203], v[168:171], v[98:101]
	s_barrier
	v_readfirstlane_b32 s16, v138
	s_add_i32 s15, s3, 0xfff80000
	s_mov_b32 m0, s16
	v_readfirstlane_b32 s16, v139
	ds_read_b128 v[204:207], v134
	ds_read_b128 v[208:211], v134 offset:1024
	ds_read_b128 v[212:215], v134 offset:2048
	ds_read_b128 v[216:219], v134 offset:3072
	buffer_load_dwordx4 v137, s[4:7], s15 offen lds
	s_mov_b32 m0, s16
	s_nop 0
	buffer_load_dwordx4 v136, s[4:7], s15 offen lds
	s_barrier
	s_waitcnt lgkmcnt(0)
	s_waitcnt lgkmcnt(3)
	v_mfma_f32_16x16x32_bf16 v[94:97], v[172:175], v[204:207], v[94:97]
	s_waitcnt lgkmcnt(1)
	v_mfma_f32_16x16x32_bf16 v[90:93], v[172:175], v[212:215], v[90:93]
	v_mfma_f32_16x16x32_bf16 v[86:89], v[180:183], v[204:207], v[86:89]
	v_mfma_f32_16x16x32_bf16 v[82:85], v[180:183], v[212:215], v[82:85]
	v_mfma_f32_16x16x32_bf16 v[78:81], v[188:191], v[204:207], v[78:81]
	v_mfma_f32_16x16x32_bf16 v[74:77], v[188:191], v[212:215], v[74:77]
	v_mfma_f32_16x16x32_bf16 v[70:73], v[196:199], v[204:207], v[70:73]
	v_mfma_f32_16x16x32_bf16 v[66:69], v[196:199], v[212:215], v[66:69]
	v_mfma_f32_16x16x32_bf16 v[94:97], v[176:179], v[208:211], v[94:97]
	s_waitcnt lgkmcnt(0)
	v_mfma_f32_16x16x32_bf16 v[90:93], v[176:179], v[216:219], v[90:93]
	v_mfma_f32_16x16x32_bf16 v[86:89], v[184:187], v[208:211], v[86:89]
	v_mfma_f32_16x16x32_bf16 v[82:85], v[184:187], v[216:219], v[82:85]
	v_mfma_f32_16x16x32_bf16 v[78:81], v[192:195], v[208:211], v[78:81]
	v_mfma_f32_16x16x32_bf16 v[74:77], v[192:195], v[216:219], v[74:77]
	v_mfma_f32_16x16x32_bf16 v[70:73], v[200:203], v[208:211], v[70:73]
	v_mfma_f32_16x16x32_bf16 v[66:69], v[200:203], v[216:219], v[66:69]
	v_readfirstlane_b32 s16, v141
	s_mov_b32 m0, s16
	v_readfirstlane_b32 s16, v142
	s_barrier
	ds_read_b128 v[172:175], v133 offset:49152
	ds_read_b128 v[176:179], v133 offset:50176
	ds_read_b128 v[180:183], v132 offset:49152
	ds_read_b128 v[184:187], v132 offset:50176
	ds_read_b128 v[188:191], v131 offset:49152
	ds_read_b128 v[192:195], v131 offset:50176
	ds_read_b128 v[196:199], v130 offset:49152
	ds_read_b128 v[200:203], v130 offset:50176
	buffer_load_dwordx4 v137, s[88:91], s15 offen lds
	s_mov_b32 m0, s16
	s_nop 0
	buffer_load_dwordx4 v136, s[88:91], s15 offen lds
	s_barrier
; #define WAIT_V(n) asm volatile("s_waitcnt vmcnt(" #n ")" ::: "memory")
; #define WAIT_L(n) asm volatile("s_waitcnt lgkmcnt(" #n ")" ::: "memory")
; #define BAR __builtin_amdgcn_s_barrier()
; #define SCHED __builtin_amdgcn_sched_barrier(0)
; __device__ __forceinline__ void mainloop_8phase(const u16* __restrict__ A, const u16* __restrict__ Bt, int K,
;                                                 f32x4 (&acc)[2][2][4][2], int wid_s, int ld) {
;     ...
;     BAR; WAIT_L(0); MMA(1, 0, At, B0); BAR; SCHED;
;     STAGE(SB(1, 1), Bt, bcol + G_HALF, t + 3);
;     WAIT_V(6); BAR; MMA(1, 1, At, B1); BAR;
;   }
;   { LDB(B0, 0, 0); LDA(At, 0, 0); STAGE(SA(1, 1), A, brow + G_HALF, nt - 1);
;     BAR; WAIT_L(0); MMA(0, 0, At, B0); BAR;
;     LDB(B1, 0, 1); BAR; WAIT_L(0); MMA(0, 1, At, B1); BAR;
	s_waitcnt lgkmcnt(0)
	s_waitcnt lgkmcnt(7)
	v_mfma_f32_16x16x32_bf16 v[62:65], v[172:175], v[156:159], v[62:65]
	v_mfma_f32_16x16x32_bf16 v[58:61], v[172:175], v[164:167], v[58:61]
	s_waitcnt lgkmcnt(5)
	v_mfma_f32_16x16x32_bf16 v[54:57], v[180:183], v[156:159], v[54:57]
	v_mfma_f32_16x16x32_bf16 v[50:53], v[180:183], v[164:167], v[50:53]
	s_waitcnt lgkmcnt(3)
	v_mfma_f32_16x16x32_bf16 v[46:49], v[188:191], v[156:159], v[46:49]
	v_mfma_f32_16x16x32_bf16 v[42:45], v[188:191], v[164:167], v[42:45]
	s_waitcnt lgkmcnt(1)
	v_mfma_f32_16x16x32_bf16 v[38:41], v[196:199], v[156:159], v[38:41]
	v_mfma_f32_16x16x32_bf16 v[34:37], v[196:199], v[164:167], v[34:37]
	v_mfma_f32_16x16x32_bf16 v[62:65], v[176:179], v[160:163], v[62:65]
	v_mfma_f32_16x16x32_bf16 v[58:61], v[176:179], v[168:171], v[58:61]
	v_mfma_f32_16x16x32_bf16 v[54:57], v[184:187], v[160:163], v[54:57]
	v_mfma_f32_16x16x32_bf16 v[50:53], v[184:187], v[168:171], v[50:53]
	v_mfma_f32_16x16x32_bf16 v[46:49], v[192:195], v[160:163], v[46:49]
	v_mfma_f32_16x16x32_bf16 v[42:45], v[192:195], v[168:171], v[42:45]
	s_waitcnt lgkmcnt(0)
	v_mfma_f32_16x16x32_bf16 v[38:41], v[200:203], v[160:163], v[38:41]
	v_mfma_f32_16x16x32_bf16 v[34:37], v[200:203], v[168:171], v[34:37]
	s_barrier
	v_readfirstlane_b32 s15, v143
	s_mov_b32 m0, s15
	v_readfirstlane_b32 s15, v144
	buffer_load_dwordx4 v137, s[4:7], s3 offen lds
	s_mov_b32 m0, s15
	s_nop 0
	buffer_load_dwordx4 v136, s[4:7], s3 offen lds
	s_waitcnt vmcnt(6)
	s_barrier
	v_mfma_f32_16x16x32_bf16 v[30:33], v[172:175], v[204:207], v[30:33]
	v_mfma_f32_16x16x32_bf16 v[26:29], v[172:175], v[212:215], v[26:29]
	v_mfma_f32_16x16x32_bf16 v[22:25], v[180:183], v[204:207], v[22:25]
	v_mfma_f32_16x16x32_bf16 v[18:21], v[180:183], v[212:215], v[18:21]
	v_mfma_f32_16x16x32_bf16 v[14:17], v[188:191], v[204:207], v[14:17]
	v_mfma_f32_16x16x32_bf16 v[10:13], v[188:191], v[212:215], v[10:13]
	v_mfma_f32_16x16x32_bf16 v[6:9], v[196:199], v[204:207], v[6:9]
	v_mfma_f32_16x16x32_bf16 v[2:5], v[196:199], v[212:215], v[2:5]
	v_mfma_f32_16x16x32_bf16 v[30:33], v[176:179], v[208:211], v[30:33]
	v_mfma_f32_16x16x32_bf16 v[26:29], v[176:179], v[216:219], v[26:29]
	v_mfma_f32_16x16x32_bf16 v[22:25], v[184:187], v[208:211], v[22:25]
	v_mfma_f32_16x16x32_bf16 v[18:21], v[184:187], v[216:219], v[18:21]
	v_mfma_f32_16x16x32_bf16 v[14:17], v[192:195], v[208:211], v[14:17]
	v_mfma_f32_16x16x32_bf16 v[10:13], v[192:195], v[216:219], v[10:13]
	v_mfma_f32_16x16x32_bf16 v[6:9], v[200:203], v[208:211], v[6:9]
	v_mfma_f32_16x16x32_bf16 v[2:5], v[200:203], v[216:219], v[2:5]
	s_add_i32 s2, s2, 2
	s_addk_i32 s3, 0x100
	s_cmp_lt_u32 s2, 28
	s_barrier
	s_cbranch_scc1 .LBB0_162
	v_readfirstlane_b32 s2, v150
	s_mov_b32 m0, s2
	s_mov_b32 s3, 0x80f80
	v_readfirstlane_b32 s2, v149
	ds_read_b128 v[138:141], v148
	ds_read_b128 v[152:155], v148 offset:1024
	ds_read_b128 v[156:159], v148 offset:2048
	ds_read_b128 v[160:163], v148 offset:3072
	ds_read_b128 v[164:167], v133
	ds_read_b128 v[168:171], v133 offset:1024
	ds_read_b128 v[172:175], v132
	ds_read_b128 v[176:179], v132 offset:1024
	ds_read_b128 v[180:183], v131
	ds_read_b128 v[184:187], v131 offset:1024
	ds_read_b128 v[188:191], v130
	ds_read_b128 v[192:195], v130 offset:1024
	buffer_load_dwordx4 v137, s[88:91], s3 offen lds
	s_mov_b32 m0, s2
	s_nop 0
	buffer_load_dwordx4 v136, s[88:91], s3 offen lds
	s_barrier
	s_waitcnt lgkmcnt(0)
	s_waitcnt lgkmcnt(7)
	v_mfma_f32_16x16x32_bf16 v[126:129], v[164:167], v[138:141], v[126:129]
	s_waitcnt lgkmcnt(5)
	v_mfma_f32_16x16x32_bf16 v[118:121], v[172:175], v[138:141], v[118:121]
	s_waitcnt lgkmcnt(3)
	v_mfma_f32_16x16x32_bf16 v[110:113], v[180:183], v[138:141], v[110:113]
	s_waitcnt lgkmcnt(1)
	v_mfma_f32_16x16x32_bf16 v[102:105], v[188:191], v[138:141], v[102:105]
	v_mfma_f32_16x16x32_bf16 v[126:129], v[168:171], v[152:155], v[126:129]
	v_mfma_f32_16x16x32_bf16 v[122:125], v[164:167], v[156:159], v[122:125]
	v_mfma_f32_16x16x32_bf16 v[118:121], v[176:179], v[152:155], v[118:121]
	v_mfma_f32_16x16x32_bf16 v[114:117], v[172:175], v[156:159], v[114:117]
	v_mfma_f32_16x16x32_bf16 v[110:113], v[184:187], v[152:155], v[110:113]
	v_mfma_f32_16x16x32_bf16 v[106:109], v[180:183], v[156:159], v[106:109]
	s_waitcnt lgkmcnt(0)
	v_mfma_f32_16x16x32_bf16 v[102:105], v[192:195], v[152:155], v[102:105]
	v_mfma_f32_16x16x32_bf16 v[98:101], v[188:191], v[156:159], v[98:101]
	v_mfma_f32_16x16x32_bf16 v[146:149], v[168:171], v[160:163], v[122:125]
	v_mfma_f32_16x16x32_bf16 v[196:199], v[176:179], v[160:163], v[114:117]
	v_mfma_f32_16x16x32_bf16 v[200:203], v[184:187], v[160:163], v[106:109]
	v_mfma_f32_16x16x32_bf16 v[204:207], v[192:195], v[160:163], v[98:101]
	s_barrier
	s_nop 1
	ds_read_b128 v[98:101], v145
	ds_read_b128 v[106:109], v145 offset:1024
	ds_read_b128 v[114:117], v145 offset:2048
	ds_read_b128 v[122:125], v145 offset:3072
	s_barrier
	s_waitcnt lgkmcnt(0)
	s_waitcnt lgkmcnt(3)
	v_mfma_f32_16x16x32_bf16 v[94:97], v[164:167], v[98:101], v[94:97]
	s_waitcnt lgkmcnt(1)
	v_mfma_f32_16x16x32_bf16 v[90:93], v[164:167], v[114:117], v[90:93]
	v_mfma_f32_16x16x32_bf16 v[86:89], v[172:175], v[98:101], v[86:89]
	v_mfma_f32_16x16x32_bf16 v[82:85], v[172:175], v[114:117], v[82:85]
	v_mfma_f32_16x16x32_bf16 v[78:81], v[180:183], v[98:101], v[78:81]
	v_mfma_f32_16x16x32_bf16 v[74:77], v[180:183], v[114:117], v[74:77]
	v_mfma_f32_16x16x32_bf16 v[70:73], v[188:191], v[98:101], v[70:73]
	v_mfma_f32_16x16x32_bf16 v[66:69], v[188:191], v[114:117], v[66:69]
	v_mfma_f32_16x16x32_bf16 v[94:97], v[168:171], v[106:109], v[94:97]
	s_waitcnt lgkmcnt(0)
	v_mfma_f32_16x16x32_bf16 v[90:93], v[168:171], v[122:125], v[90:93]
	v_mfma_f32_16x16x32_bf16 v[86:89], v[176:179], v[106:109], v[86:89]
	v_mfma_f32_16x16x32_bf16 v[82:85], v[176:179], v[122:125], v[82:85]
	v_mfma_f32_16x16x32_bf16 v[78:81], v[184:187], v[106:109], v[78:81]
	v_mfma_f32_16x16x32_bf16 v[74:77], v[184:187], v[122:125], v[74:77]
	v_mfma_f32_16x16x32_bf16 v[70:73], v[192:195], v[106:109], v[70:73]
	v_mfma_f32_16x16x32_bf16 v[66:69], v[192:195], v[122:125], v[66:69]
	s_barrier
; #define WAIT_V(n) asm volatile("s_waitcnt vmcnt(" #n ")" ::: "memory")
; #define WAIT_L(n) asm volatile("s_waitcnt lgkmcnt(" #n ")" ::: "memory")
; #define BAR __builtin_amdgcn_s_barrier()
; __device__ __forceinline__ void mainloop_8phase(const u16* __restrict__ A, const u16* __restrict__ Bt, int K,
;                                                 f32x4 (&acc)[2][2][4][2], int wid_s, int ld) {
;     ...
;     LDA(At, 0, 1); WAIT_V(4); BAR; WAIT_L(0); MMA(1, 0, At, B0); MMA(1, 1, At, B1); BAR; }
;   { LDB(B0, 1, 0); LDA(At, 1, 0); WAIT_V(2); BAR; WAIT_L(0); MMA(0, 0, At, B0); BAR;
	ds_read_b128 v[142:145], v133 offset:16384
	ds_read_b128 v[164:167], v133 offset:17408
	ds_read_b128 v[168:171], v132 offset:16384
	ds_read_b128 v[172:175], v132 offset:17408
	ds_read_b128 v[176:179], v131 offset:16384
	ds_read_b128 v[180:183], v131 offset:17408
	ds_read_b128 v[184:187], v130 offset:16384
	ds_read_b128 v[188:191], v130 offset:17408
	s_waitcnt vmcnt(4)
	s_barrier
	s_waitcnt lgkmcnt(0)
	s_waitcnt lgkmcnt(7)
	v_mfma_f32_16x16x32_bf16 v[62:65], v[142:145], v[138:141], v[62:65]
	v_mfma_f32_16x16x32_bf16 v[58:61], v[142:145], v[156:159], v[58:61]
	s_waitcnt lgkmcnt(5)
	v_mfma_f32_16x16x32_bf16 v[54:57], v[168:171], v[138:141], v[54:57]
	v_mfma_f32_16x16x32_bf16 v[50:53], v[168:171], v[156:159], v[50:53]
	s_waitcnt lgkmcnt(3)
	v_mfma_f32_16x16x32_bf16 v[46:49], v[176:179], v[138:141], v[46:49]
	v_mfma_f32_16x16x32_bf16 v[42:45], v[176:179], v[156:159], v[42:45]
	s_waitcnt lgkmcnt(1)
	v_mfma_f32_16x16x32_bf16 v[38:41], v[184:187], v[138:141], v[38:41]
	v_mfma_f32_16x16x32_bf16 v[34:37], v[184:187], v[156:159], v[34:37]
	v_mfma_f32_16x16x32_bf16 v[192:195], v[164:167], v[152:155], v[62:65]
	v_mfma_f32_16x16x32_bf16 v[208:211], v[164:167], v[160:163], v[58:61]
	v_mfma_f32_16x16x32_bf16 v[212:215], v[172:175], v[152:155], v[54:57]
	v_mfma_f32_16x16x32_bf16 v[216:219], v[172:175], v[160:163], v[50:53]
	v_mfma_f32_16x16x32_bf16 v[220:223], v[180:183], v[152:155], v[46:49]
	v_mfma_f32_16x16x32_bf16 v[224:227], v[180:183], v[160:163], v[42:45]
	s_waitcnt lgkmcnt(0)
	v_mfma_f32_16x16x32_bf16 v[136:139], v[188:191], v[152:155], v[38:41]
	v_mfma_f32_16x16x32_bf16 v[150:153], v[188:191], v[160:163], v[34:37]
	v_mfma_f32_16x16x32_bf16 v[30:33], v[142:145], v[98:101], v[30:33]
	v_mfma_f32_16x16x32_bf16 v[22:25], v[168:171], v[98:101], v[22:25]
	v_mfma_f32_16x16x32_bf16 v[14:17], v[176:179], v[98:101], v[14:17]
	v_mfma_f32_16x16x32_bf16 v[6:9], v[184:187], v[98:101], v[6:9]
	v_mfma_f32_16x16x32_bf16 v[30:33], v[164:167], v[106:109], v[30:33]
	v_mfma_f32_16x16x32_bf16 v[26:29], v[142:145], v[114:117], v[26:29]
	v_mfma_f32_16x16x32_bf16 v[22:25], v[172:175], v[106:109], v[22:25]
	v_mfma_f32_16x16x32_bf16 v[18:21], v[168:171], v[114:117], v[18:21]
	v_mfma_f32_16x16x32_bf16 v[14:17], v[180:183], v[106:109], v[14:17]
	v_mfma_f32_16x16x32_bf16 v[10:13], v[176:179], v[114:117], v[10:13]
	v_mfma_f32_16x16x32_bf16 v[6:9], v[188:191], v[106:109], v[6:9]
	v_mfma_f32_16x16x32_bf16 v[2:5], v[184:187], v[114:117], v[2:5]
	v_mfma_f32_16x16x32_bf16 v[140:143], v[164:167], v[122:125], v[26:29]
	v_mfma_f32_16x16x32_bf16 v[154:157], v[172:175], v[122:125], v[18:21]
	v_mfma_f32_16x16x32_bf16 v[158:161], v[180:183], v[122:125], v[10:13]
	v_mfma_f32_16x16x32_bf16 v[162:165], v[188:191], v[122:125], v[2:5]
	s_barrier
	s_nop 1
	ds_read_b128 v[2:5], v135
	ds_read_b128 v[166:169], v135 offset:1024
	ds_read_b128 v[170:173], v135 offset:2048
	ds_read_b128 v[174:177], v135 offset:3072
	ds_read_b128 v[10:13], v133 offset:32768
	ds_read_b128 v[18:21], v133 offset:33792
	ds_read_b128 v[26:29], v132 offset:32768
	ds_read_b128 v[38:41], v132 offset:33792
	ds_read_b128 v[46:49], v131 offset:32768
	ds_read_b128 v[178:181], v131 offset:33792
	ds_read_b128 v[182:185], v130 offset:32768
	ds_read_b128 v[186:189], v130 offset:33792
	s_waitcnt vmcnt(2)
	s_barrier
	s_waitcnt lgkmcnt(0)
	s_waitcnt lgkmcnt(7)
	v_mfma_f32_16x16x32_bf16 v[34:37], v[10:13], v[2:5], v[126:129]
	s_waitcnt lgkmcnt(6)
	v_mfma_f32_16x16x32_bf16 v[122:125], v[18:21], v[166:169], v[34:37]
	v_mfma_f32_16x16x32_bf16 v[34:37], v[10:13], v[170:173], v[146:149]
	v_mfma_f32_16x16x32_bf16 v[58:61], v[18:21], v[174:177], v[34:37]
	s_waitcnt lgkmcnt(5)
	v_mfma_f32_16x16x32_bf16 v[34:37], v[26:29], v[2:5], v[118:121]
	s_waitcnt lgkmcnt(4)
	v_mfma_f32_16x16x32_bf16 v[114:117], v[38:41], v[166:169], v[34:37]
	v_mfma_f32_16x16x32_bf16 v[34:37], v[26:29], v[170:173], v[196:199]
	v_mfma_f32_16x16x32_bf16 v[50:53], v[38:41], v[174:177], v[34:37]
	s_waitcnt lgkmcnt(3)
	v_mfma_f32_16x16x32_bf16 v[34:37], v[46:49], v[2:5], v[110:113]
	s_waitcnt lgkmcnt(2)
	v_mfma_f32_16x16x32_bf16 v[106:109], v[178:181], v[166:169], v[34:37]
	v_mfma_f32_16x16x32_bf16 v[34:37], v[46:49], v[170:173], v[200:203]
	v_mfma_f32_16x16x32_bf16 v[42:45], v[178:181], v[174:177], v[34:37]
	s_waitcnt lgkmcnt(1)
	v_mfma_f32_16x16x32_bf16 v[34:37], v[182:185], v[2:5], v[102:105]
	s_waitcnt lgkmcnt(0)
	v_mfma_f32_16x16x32_bf16 v[98:101], v[186:189], v[166:169], v[34:37]
	v_mfma_f32_16x16x32_bf16 v[34:37], v[182:185], v[170:173], v[204:207]
	v_mfma_f32_16x16x32_bf16 v[34:37], v[186:189], v[174:177], v[34:37]
	s_barrier
; #define WAIT_V(n) asm volatile("s_waitcnt vmcnt(" #n ")" ::: "memory")
; #define WAIT_L(n) asm volatile("s_waitcnt lgkmcnt(" #n ")" ::: "memory")
; #define BAR __builtin_amdgcn_s_barrier()
; __device__ __forceinline__ void mainloop_8phase(const u16* __restrict__ A, const u16* __restrict__ Bt, int K,
;                                                 f32x4 (&acc)[2][2][4][2], int wid_s, int ld) {
;     ...
;   { LDB(B0, 1, 0); LDA(At, 1, 0); WAIT_V(2); BAR; WAIT_L(0); MMA(0, 0, At, B0); BAR;
;     LDB(B1, 1, 1); WAIT_V(0); BAR; WAIT_L(0); MMA(0, 1, At, B1); BAR;
;     LDA(At, 1, 1); BAR; WAIT_L(0); MMA(1, 0, At, B0); MMA(1, 1, At, B1); BAR; }
;   if (wr == 0) BAR;
	ds_read_b128 v[144:147], v134
	ds_read_b128 v[196:199], v134 offset:1024
	ds_read_b128 v[200:203], v134 offset:2048
	ds_read_b128 v[204:207], v134 offset:3072
	s_waitcnt vmcnt(0)
	s_barrier
	s_waitcnt lgkmcnt(0)
	s_waitcnt lgkmcnt(3)
	v_mfma_f32_16x16x32_bf16 v[54:57], v[10:13], v[144:147], v[94:97]
	s_waitcnt lgkmcnt(1)
	v_mfma_f32_16x16x32_bf16 v[10:13], v[10:13], v[200:203], v[90:93]
	s_waitcnt lgkmcnt(0)
	v_mfma_f32_16x16x32_bf16 v[62:65], v[18:21], v[204:207], v[10:13]
	v_mfma_f32_16x16x32_bf16 v[10:13], v[26:29], v[144:147], v[86:89]
	v_mfma_f32_16x16x32_bf16 v[118:121], v[38:41], v[196:199], v[10:13]
	v_mfma_f32_16x16x32_bf16 v[10:13], v[26:29], v[200:203], v[82:85]
	v_mfma_f32_16x16x32_bf16 v[126:129], v[18:21], v[196:199], v[54:57]
	v_mfma_f32_16x16x32_bf16 v[54:57], v[38:41], v[204:207], v[10:13]
	v_mfma_f32_16x16x32_bf16 v[10:13], v[46:49], v[144:147], v[78:81]
	v_mfma_f32_16x16x32_bf16 v[110:113], v[178:181], v[196:199], v[10:13]
	v_mfma_f32_16x16x32_bf16 v[10:13], v[46:49], v[200:203], v[74:77]
	v_mfma_f32_16x16x32_bf16 v[46:49], v[178:181], v[204:207], v[10:13]
	v_mfma_f32_16x16x32_bf16 v[10:13], v[182:185], v[144:147], v[70:73]
	v_mfma_f32_16x16x32_bf16 v[102:105], v[186:189], v[196:199], v[10:13]
	v_mfma_f32_16x16x32_bf16 v[10:13], v[182:185], v[200:203], v[66:69]
	v_mfma_f32_16x16x32_bf16 v[38:41], v[186:189], v[204:207], v[10:13]
	s_barrier
	ds_read_b128 v[70:73], v133 offset:49152
	ds_read_b128 v[78:81], v133 offset:50176
	ds_read_b128 v[178:181], v132 offset:49152
	ds_read_b128 v[132:135], v132 offset:50176
	ds_read_b128 v[182:185], v131 offset:49152
	ds_read_b128 v[186:189], v131 offset:50176
	ds_read_b128 v[228:231], v130 offset:49152
	ds_read_b128 v[232:235], v130 offset:50176
	s_barrier
	s_waitcnt lgkmcnt(0)
	s_waitcnt lgkmcnt(7)
	v_mfma_f32_16x16x32_bf16 v[10:13], v[70:73], v[2:5], v[192:195]
	s_waitcnt lgkmcnt(6)
	v_mfma_f32_16x16x32_bf16 v[90:93], v[78:81], v[166:169], v[10:13]
	v_mfma_f32_16x16x32_bf16 v[10:13], v[70:73], v[170:173], v[208:211]
	v_mfma_f32_16x16x32_bf16 v[26:29], v[78:81], v[174:177], v[10:13]
	s_waitcnt lgkmcnt(5)
	v_mfma_f32_16x16x32_bf16 v[10:13], v[178:181], v[2:5], v[212:215]
	s_waitcnt lgkmcnt(4)
	v_mfma_f32_16x16x32_bf16 v[82:85], v[132:135], v[166:169], v[10:13]
	v_mfma_f32_16x16x32_bf16 v[10:13], v[178:181], v[170:173], v[216:219]
	v_mfma_f32_16x16x32_bf16 v[18:21], v[132:135], v[174:177], v[10:13]
	s_waitcnt lgkmcnt(3)
	v_mfma_f32_16x16x32_bf16 v[10:13], v[182:185], v[2:5], v[220:223]
	s_waitcnt lgkmcnt(1)
	v_mfma_f32_16x16x32_bf16 v[2:5], v[228:231], v[2:5], v[136:139]
	v_mfma_f32_16x16x32_bf16 v[74:77], v[186:189], v[166:169], v[10:13]
	v_mfma_f32_16x16x32_bf16 v[10:13], v[182:185], v[170:173], v[224:227]
	s_waitcnt lgkmcnt(0)
	v_mfma_f32_16x16x32_bf16 v[66:69], v[232:235], v[166:169], v[2:5]
	v_mfma_f32_16x16x32_bf16 v[2:5], v[228:231], v[170:173], v[150:153]
	v_mfma_f32_16x16x32_bf16 v[10:13], v[186:189], v[174:177], v[10:13]
	v_mfma_f32_16x16x32_bf16 v[2:5], v[232:235], v[174:177], v[2:5]
	v_mfma_f32_16x16x32_bf16 v[30:33], v[70:73], v[144:147], v[30:33]
	v_mfma_f32_16x16x32_bf16 v[94:97], v[78:81], v[196:199], v[30:33]
	v_mfma_f32_16x16x32_bf16 v[30:33], v[70:73], v[200:203], v[140:143]
	v_mfma_f32_16x16x32_bf16 v[22:25], v[178:181], v[144:147], v[22:25]
	v_mfma_f32_16x16x32_bf16 v[14:17], v[182:185], v[144:147], v[14:17]
	v_mfma_f32_16x16x32_bf16 v[6:9], v[228:231], v[144:147], v[6:9]
	v_mfma_f32_16x16x32_bf16 v[30:33], v[78:81], v[204:207], v[30:33]
	v_mfma_f32_16x16x32_bf16 v[86:89], v[132:135], v[196:199], v[22:25]
	v_mfma_f32_16x16x32_bf16 v[22:25], v[178:181], v[200:203], v[154:157]
	v_mfma_f32_16x16x32_bf16 v[78:81], v[186:189], v[196:199], v[14:17]
	v_mfma_f32_16x16x32_bf16 v[14:17], v[182:185], v[200:203], v[158:161]
	v_mfma_f32_16x16x32_bf16 v[70:73], v[232:235], v[196:199], v[6:9]
	v_mfma_f32_16x16x32_bf16 v[6:9], v[228:231], v[200:203], v[162:165]
	v_mfma_f32_16x16x32_bf16 v[22:25], v[132:135], v[204:207], v[22:25]
	v_mfma_f32_16x16x32_bf16 v[14:17], v[186:189], v[204:207], v[14:17]
	v_mfma_f32_16x16x32_bf16 v[6:9], v[232:235], v[204:207], v[6:9]
	s_movk_i32 s2, 0x100
	v_cmp_gt_u32_e32 vcc, s2, v0
	s_barrier
	s_and_saveexec_b64 s[2:3], vcc
	s_cbranch_execz .LBB0_165
	s_barrier

; #define WAIT_L(n) asm volatile("s_waitcnt lgkmcnt(" #n ")" ::: "memory")
; #define BAR __builtin_amdgcn_s_barrier()
; #define SCHED __builtin_amdgcn_sched_barrier(0)
; __device__ __forceinline__ void mainloop_8phase(const u16* __restrict__ A, const u16* __restrict__ Bt, int K,
;                                                 f32x4 (&acc)[2][2][4][2], int wid_s, int ld) {
;     ...
;   for (int t = 0; t < nt - 2; t += 2) {
;     LDB(B0, 0, 0); SCHED; LDA(At, 0, 0); STAGE(SA(1, 1), A, brow + G_HALF, t + 1);
;     WAIT_L(8); BAR; WAIT_L(0); MMA(0, 0, At, B0); BAR; SCHED;
;     LDB(B1, 0, 1); STAGE(SB(0, 0), Bt, bcol, t + 2);
;     BAR; WAIT_L(0); MMA(0, 1, At, B1); BAR;
;     LDA(At, 0, 1); STAGE(SA(0, 0), A, brow, t + 2);
;     BAR; WAIT_L(0); MMA(1, 0, At, B0); BAR; SCHED;
.LBB0_247:
	ds_read_b128 v[156:159], v155
	ds_read_b128 v[160:163], v155 offset:1024
	ds_read_b128 v[164:167], v155 offset:2048
	ds_read_b128 v[168:171], v155 offset:3072
	v_readfirstlane_b32 s6, v145
	s_add_i32 s3, s1, 0xffffff00
	s_mov_b32 m0, s6
	v_readfirstlane_b32 s6, v144
	ds_read_b128 v[172:175], v133
	ds_read_b128 v[176:179], v133 offset:1024
	ds_read_b128 v[180:183], v132
	ds_read_b128 v[184:187], v132 offset:1024
	ds_read_b128 v[188:191], v131
	ds_read_b128 v[192:195], v131 offset:1024
	ds_read_b128 v[196:199], v130
	ds_read_b128 v[200:203], v130 offset:1024
	buffer_load_dwordx4 v137, s[88:91], s3 offen lds
	s_mov_b32 m0, s6
	s_nop 0
	buffer_load_dwordx4 v136, s[88:91], s3 offen lds
	s_waitcnt lgkmcnt(8)
	s_barrier
	s_waitcnt lgkmcnt(0)
	s_waitcnt lgkmcnt(7)
	v_mfma_f32_16x16x32_bf16 v[126:129], v[172:175], v[156:159], v[126:129]
	v_mfma_f32_16x16x32_bf16 v[122:125], v[172:175], v[164:167], v[122:125]
	s_waitcnt lgkmcnt(5)
	v_mfma_f32_16x16x32_bf16 v[118:121], v[180:183], v[156:159], v[118:121]
	v_mfma_f32_16x16x32_bf16 v[114:117], v[180:183], v[164:167], v[114:117]
	s_waitcnt lgkmcnt(3)
	v_mfma_f32_16x16x32_bf16 v[110:113], v[188:191], v[156:159], v[110:113]
	v_mfma_f32_16x16x32_bf16 v[106:109], v[188:191], v[164:167], v[106:109]
	s_waitcnt lgkmcnt(1)
	v_mfma_f32_16x16x32_bf16 v[102:105], v[196:199], v[156:159], v[102:105]
	v_mfma_f32_16x16x32_bf16 v[98:101], v[196:199], v[164:167], v[98:101]
	v_mfma_f32_16x16x32_bf16 v[126:129], v[176:179], v[160:163], v[126:129]
	v_mfma_f32_16x16x32_bf16 v[122:125], v[176:179], v[168:171], v[122:125]
	v_mfma_f32_16x16x32_bf16 v[118:121], v[184:187], v[160:163], v[118:121]
	v_mfma_f32_16x16x32_bf16 v[114:117], v[184:187], v[168:171], v[114:117]
	v_mfma_f32_16x16x32_bf16 v[110:113], v[192:195], v[160:163], v[110:113]
	v_mfma_f32_16x16x32_bf16 v[106:109], v[192:195], v[168:171], v[106:109]
	s_waitcnt lgkmcnt(0)
	v_mfma_f32_16x16x32_bf16 v[102:105], v[200:203], v[160:163], v[102:105]
	v_mfma_f32_16x16x32_bf16 v[98:101], v[200:203], v[168:171], v[98:101]
	s_barrier
	v_readfirstlane_b32 s14, v148
	s_add_i32 s3, s1, 0xfff7ff80
	s_mov_b32 s6, s90
	s_mov_b32 s7, s91
	s_mov_b32 m0, s14
	v_readfirstlane_b32 s14, v149
	ds_read_b128 v[204:207], v147
	ds_read_b128 v[208:211], v147 offset:1024
	ds_read_b128 v[212:215], v147 offset:2048
	ds_read_b128 v[216:219], v147 offset:3072
	buffer_load_dwordx4 v137, s[4:7], s3 offen lds
	s_mov_b32 m0, s14
	s_nop 0
	buffer_load_dwordx4 v136, s[4:7], s3 offen lds
	s_barrier
	s_waitcnt lgkmcnt(0)
	s_waitcnt lgkmcnt(3)
	v_mfma_f32_16x16x32_bf16 v[94:97], v[172:175], v[204:207], v[94:97]
	s_waitcnt lgkmcnt(1)
	v_mfma_f32_16x16x32_bf16 v[90:93], v[172:175], v[212:215], v[90:93]
	v_mfma_f32_16x16x32_bf16 v[86:89], v[180:183], v[204:207], v[86:89]
	v_mfma_f32_16x16x32_bf16 v[82:85], v[180:183], v[212:215], v[82:85]
	v_mfma_f32_16x16x32_bf16 v[78:81], v[188:191], v[204:207], v[78:81]
	v_mfma_f32_16x16x32_bf16 v[74:77], v[188:191], v[212:215], v[74:77]
	v_mfma_f32_16x16x32_bf16 v[70:73], v[196:199], v[204:207], v[70:73]
	v_mfma_f32_16x16x32_bf16 v[66:69], v[196:199], v[212:215], v[66:69]
	v_mfma_f32_16x16x32_bf16 v[94:97], v[176:179], v[208:211], v[94:97]
	s_waitcnt lgkmcnt(0)
	v_mfma_f32_16x16x32_bf16 v[90:93], v[176:179], v[216:219], v[90:93]
	v_mfma_f32_16x16x32_bf16 v[86:89], v[184:187], v[208:211], v[86:89]
	v_mfma_f32_16x16x32_bf16 v[82:85], v[184:187], v[216:219], v[82:85]
	v_mfma_f32_16x16x32_bf16 v[78:81], v[192:195], v[208:211], v[78:81]
	v_mfma_f32_16x16x32_bf16 v[74:77], v[192:195], v[216:219], v[74:77]
	v_mfma_f32_16x16x32_bf16 v[70:73], v[200:203], v[208:211], v[70:73]
	v_mfma_f32_16x16x32_bf16 v[66:69], v[200:203], v[216:219], v[66:69]
	v_readfirstlane_b32 s14, v140
	s_mov_b32 m0, s14
	v_readfirstlane_b32 s14, v150
	s_barrier
	ds_read_b128 v[172:175], v133 offset:16384
	ds_read_b128 v[176:179], v133 offset:17408
	ds_read_b128 v[180:183], v132 offset:16384
	ds_read_b128 v[184:187], v132 offset:17408
	ds_read_b128 v[188:191], v131 offset:16384
	ds_read_b128 v[192:195], v131 offset:17408
	ds_read_b128 v[196:199], v130 offset:16384
	ds_read_b128 v[200:203], v130 offset:17408
	buffer_load_dwordx4 v137, s[88:91], s3 offen lds
	s_mov_b32 m0, s14
	s_nop 0
	buffer_load_dwordx4 v136, s[88:91], s3 offen lds
	s_barrier
	s_waitcnt lgkmcnt(0)
	s_waitcnt lgkmcnt(7)
	v_mfma_f32_16x16x32_bf16 v[62:65], v[172:175], v[156:159], v[62:65]
	v_mfma_f32_16x16x32_bf16 v[58:61], v[172:175], v[164:167], v[58:61]
	s_waitcnt lgkmcnt(5)
	v_mfma_f32_16x16x32_bf16 v[54:57], v[180:183], v[156:159], v[54:57]
	v_mfma_f32_16x16x32_bf16 v[50:53], v[180:183], v[164:167], v[50:53]
	s_waitcnt lgkmcnt(3)
	v_mfma_f32_16x16x32_bf16 v[46:49], v[188:191], v[156:159], v[46:49]
	v_mfma_f32_16x16x32_bf16 v[42:45], v[188:191], v[164:167], v[42:45]
	s_waitcnt lgkmcnt(1)
	v_mfma_f32_16x16x32_bf16 v[38:41], v[196:199], v[156:159], v[38:41]
	v_mfma_f32_16x16x32_bf16 v[34:37], v[196:199], v[164:167], v[34:37]
	v_mfma_f32_16x16x32_bf16 v[62:65], v[176:179], v[160:163], v[62:65]
	v_mfma_f32_16x16x32_bf16 v[58:61], v[176:179], v[168:171], v[58:61]
	v_mfma_f32_16x16x32_bf16 v[54:57], v[184:187], v[160:163], v[54:57]
	v_mfma_f32_16x16x32_bf16 v[50:53], v[184:187], v[168:171], v[50:53]
	v_mfma_f32_16x16x32_bf16 v[46:49], v[192:195], v[160:163], v[46:49]
	v_mfma_f32_16x16x32_bf16 v[42:45], v[192:195], v[168:171], v[42:45]
	s_waitcnt lgkmcnt(0)
	v_mfma_f32_16x16x32_bf16 v[38:41], v[200:203], v[160:163], v[38:41]
	v_mfma_f32_16x16x32_bf16 v[34:37], v[200:203], v[168:171], v[34:37]
	s_barrier
; #define WAIT_V(n) asm volatile("s_waitcnt vmcnt(" #n ")" ::: "memory")
; #define WAIT_L(n) asm volatile("s_waitcnt lgkmcnt(" #n ")" ::: "memory")
; #define BAR __builtin_amdgcn_s_barrier()
; #define SCHED __builtin_amdgcn_sched_barrier(0)
; __device__ __forceinline__ void mainloop_8phase(const u16* __restrict__ A, const u16* __restrict__ Bt, int K,
;                                                 f32x4 (&acc)[2][2][4][2], int wid_s, int ld) {
;     ...
;     STAGE(SB(0, 1), Bt, bcol + G_HALF, t + 2);
;     WAIT_V(6); BAR; MMA(1, 1, At, B1); BAR;
;     LDB(B0, 1, 0); SCHED; LDA(At, 1, 0); STAGE(SA(0, 1), A, brow + G_HALF, t + 2);
;     WAIT_L(8); BAR; WAIT_L(0); MMA(0, 0, At, B0); BAR; SCHED;
;     LDB(B1, 1, 1); STAGE(SB(1, 0), Bt, bcol, t + 3);
;     BAR; WAIT_L(0); MMA(0, 1, At, B1); BAR;
;     LDA(At, 1, 1); STAGE(SA(1, 0), A, brow, t + 3);
	v_readfirstlane_b32 s14, v151
	s_add_i32 s3, s1, 0xffffff80
	s_mov_b32 m0, s14
	v_readfirstlane_b32 s14, v152
	buffer_load_dwordx4 v137, s[4:7], s3 offen lds
	s_mov_b32 m0, s14
	s_nop 0
	buffer_load_dwordx4 v136, s[4:7], s3 offen lds
	s_waitcnt vmcnt(6)
	s_barrier
	v_mfma_f32_16x16x32_bf16 v[30:33], v[172:175], v[204:207], v[30:33]
	v_mfma_f32_16x16x32_bf16 v[26:29], v[172:175], v[212:215], v[26:29]
	v_mfma_f32_16x16x32_bf16 v[22:25], v[180:183], v[204:207], v[22:25]
	v_mfma_f32_16x16x32_bf16 v[18:21], v[180:183], v[212:215], v[18:21]
	v_mfma_f32_16x16x32_bf16 v[14:17], v[188:191], v[204:207], v[14:17]
	v_mfma_f32_16x16x32_bf16 v[10:13], v[188:191], v[212:215], v[10:13]
	v_mfma_f32_16x16x32_bf16 v[6:9], v[196:199], v[204:207], v[6:9]
	v_mfma_f32_16x16x32_bf16 v[2:5], v[196:199], v[212:215], v[2:5]
	v_mfma_f32_16x16x32_bf16 v[30:33], v[176:179], v[208:211], v[30:33]
	v_mfma_f32_16x16x32_bf16 v[26:29], v[176:179], v[216:219], v[26:29]
	v_mfma_f32_16x16x32_bf16 v[22:25], v[184:187], v[208:211], v[22:25]
	v_mfma_f32_16x16x32_bf16 v[18:21], v[184:187], v[216:219], v[18:21]
	v_mfma_f32_16x16x32_bf16 v[14:17], v[192:195], v[208:211], v[14:17]
	v_mfma_f32_16x16x32_bf16 v[10:13], v[192:195], v[216:219], v[10:13]
	v_mfma_f32_16x16x32_bf16 v[6:9], v[200:203], v[208:211], v[6:9]
	v_mfma_f32_16x16x32_bf16 v[2:5], v[200:203], v[216:219], v[2:5]
	s_barrier
	ds_read_b128 v[156:159], v135
	ds_read_b128 v[160:163], v135 offset:1024
	ds_read_b128 v[164:167], v135 offset:2048
	ds_read_b128 v[168:171], v135 offset:3072
	v_readfirstlane_b32 s14, v153
	s_mov_b32 m0, s14
	v_readfirstlane_b32 s14, v154
	ds_read_b128 v[172:175], v133 offset:32768
	ds_read_b128 v[176:179], v133 offset:33792
	ds_read_b128 v[180:183], v132 offset:32768
	ds_read_b128 v[184:187], v132 offset:33792
	ds_read_b128 v[188:191], v131 offset:32768
	ds_read_b128 v[192:195], v131 offset:33792
	ds_read_b128 v[196:199], v130 offset:32768
	ds_read_b128 v[200:203], v130 offset:33792
	buffer_load_dwordx4 v137, s[88:91], s3 offen lds
	s_mov_b32 m0, s14
	s_nop 0
	buffer_load_dwordx4 v136, s[88:91], s3 offen lds
	s_waitcnt lgkmcnt(8)
	s_barrier
	s_waitcnt lgkmcnt(0)
	s_waitcnt lgkmcnt(7)
	v_mfma_f32_16x16x32_bf16 v[126:129], v[172:175], v[156:159], v[126:129]
	v_mfma_f32_16x16x32_bf16 v[122:125], v[172:175], v[164:167], v[122:125]
	s_waitcnt lgkmcnt(5)
	v_mfma_f32_16x16x32_bf16 v[118:121], v[180:183], v[156:159], v[118:121]
	v_mfma_f32_16x16x32_bf16 v[114:117], v[180:183], v[164:167], v[114:117]
	s_waitcnt lgkmcnt(3)
	v_mfma_f32_16x16x32_bf16 v[110:113], v[188:191], v[156:159], v[110:113]
	v_mfma_f32_16x16x32_bf16 v[106:109], v[188:191], v[164:167], v[106:109]
	s_waitcnt lgkmcnt(1)
	v_mfma_f32_16x16x32_bf16 v[102:105], v[196:199], v[156:159], v[102:105]
	v_mfma_f32_16x16x32_bf16 v[98:101], v[196:199], v[164:167], v[98:101]
	v_mfma_f32_16x16x32_bf16 v[126:129], v[176:179], v[160:163], v[126:129]
	v_mfma_f32_16x16x32_bf16 v[122:125], v[176:179], v[168:171], v[122:125]
	v_mfma_f32_16x16x32_bf16 v[118:121], v[184:187], v[160:163], v[118:121]
	v_mfma_f32_16x16x32_bf16 v[114:117], v[184:187], v[168:171], v[114:117]
	v_mfma_f32_16x16x32_bf16 v[110:113], v[192:195], v[160:163], v[110:113]
	v_mfma_f32_16x16x32_bf16 v[106:109], v[192:195], v[168:171], v[106:109]
	s_waitcnt lgkmcnt(0)
	v_mfma_f32_16x16x32_bf16 v[102:105], v[200:203], v[160:163], v[102:105]
	v_mfma_f32_16x16x32_bf16 v[98:101], v[200:203], v[168:171], v[98:101]
	s_barrier
	v_readfirstlane_b32 s14, v138
	s_add_i32 s3, s1, 0xfff80000
	s_mov_b32 m0, s14
	v_readfirstlane_b32 s14, v139
	ds_read_b128 v[204:207], v134
	ds_read_b128 v[208:211], v134 offset:1024
	ds_read_b128 v[212:215], v134 offset:2048
	ds_read_b128 v[216:219], v134 offset:3072
	buffer_load_dwordx4 v137, s[4:7], s3 offen lds
	s_mov_b32 m0, s14
	s_nop 0
	buffer_load_dwordx4 v136, s[4:7], s3 offen lds
	s_barrier
	s_waitcnt lgkmcnt(0)
	s_waitcnt lgkmcnt(3)
	v_mfma_f32_16x16x32_bf16 v[94:97], v[172:175], v[204:207], v[94:97]
	s_waitcnt lgkmcnt(1)
	v_mfma_f32_16x16x32_bf16 v[90:93], v[172:175], v[212:215], v[90:93]
	v_mfma_f32_16x16x32_bf16 v[86:89], v[180:183], v[204:207], v[86:89]
	v_mfma_f32_16x16x32_bf16 v[82:85], v[180:183], v[212:215], v[82:85]
	v_mfma_f32_16x16x32_bf16 v[78:81], v[188:191], v[204:207], v[78:81]
	v_mfma_f32_16x16x32_bf16 v[74:77], v[188:191], v[212:215], v[74:77]
	v_mfma_f32_16x16x32_bf16 v[70:73], v[196:199], v[204:207], v[70:73]
	v_mfma_f32_16x16x32_bf16 v[66:69], v[196:199], v[212:215], v[66:69]
	v_mfma_f32_16x16x32_bf16 v[94:97], v[176:179], v[208:211], v[94:97]
	s_waitcnt lgkmcnt(0)
	v_mfma_f32_16x16x32_bf16 v[90:93], v[176:179], v[216:219], v[90:93]
	v_mfma_f32_16x16x32_bf16 v[86:89], v[184:187], v[208:211], v[86:89]
	v_mfma_f32_16x16x32_bf16 v[82:85], v[184:187], v[216:219], v[82:85]
	v_mfma_f32_16x16x32_bf16 v[78:81], v[192:195], v[208:211], v[78:81]
	v_mfma_f32_16x16x32_bf16 v[74:77], v[192:195], v[216:219], v[74:77]
	v_mfma_f32_16x16x32_bf16 v[70:73], v[200:203], v[208:211], v[70:73]
	v_mfma_f32_16x16x32_bf16 v[66:69], v[200:203], v[216:219], v[66:69]
	v_readfirstlane_b32 s14, v141
	s_mov_b32 m0, s14
	v_readfirstlane_b32 s14, v142
	s_barrier
	ds_read_b128 v[172:175], v133 offset:49152
	ds_read_b128 v[176:179], v133 offset:50176
	ds_read_b128 v[180:183], v132 offset:49152
	ds_read_b128 v[184:187], v132 offset:50176
	ds_read_b128 v[188:191], v131 offset:49152
	ds_read_b128 v[192:195], v131 offset:50176
	ds_read_b128 v[196:199], v130 offset:49152
	ds_read_b128 v[200:203], v130 offset:50176
	buffer_load_dwordx4 v137, s[88:91], s3 offen lds
	s_mov_b32 m0, s14
	s_nop 0
	buffer_load_dwordx4 v136, s[88:91], s3 offen lds
	s_barrier
; #define WAIT_V(n) asm volatile("s_waitcnt vmcnt(" #n ")" ::: "memory")
; #define WAIT_L(n) asm volatile("s_waitcnt lgkmcnt(" #n ")" ::: "memory")
; #define BAR __builtin_amdgcn_s_barrier()
; #define SCHED __builtin_amdgcn_sched_barrier(0)
; __device__ __forceinline__ void mainloop_8phase(const u16* __restrict__ A, const u16* __restrict__ Bt, int K,
;                                                 f32x4 (&acc)[2][2][4][2], int wid_s, int ld) {
;     ...
;     BAR; WAIT_L(0); MMA(1, 0, At, B0); BAR; SCHED;
;     STAGE(SB(1, 1), Bt, bcol + G_HALF, t + 3);
;     WAIT_V(6); BAR; MMA(1, 1, At, B1); BAR;
;   }
;   { LDB(B0, 0, 0); LDA(At, 0, 0); STAGE(SA(1, 1), A, brow + G_HALF, nt - 1);
;     BAR; WAIT_L(0); MMA(0, 0, At, B0); BAR;
;     LDB(B1, 0, 1); BAR; WAIT_L(0); MMA(0, 1, At, B1); BAR;
	s_waitcnt lgkmcnt(0)
	s_waitcnt lgkmcnt(7)
	v_mfma_f32_16x16x32_bf16 v[62:65], v[172:175], v[156:159], v[62:65]
	v_mfma_f32_16x16x32_bf16 v[58:61], v[172:175], v[164:167], v[58:61]
	s_waitcnt lgkmcnt(5)
	v_mfma_f32_16x16x32_bf16 v[54:57], v[180:183], v[156:159], v[54:57]
	v_mfma_f32_16x16x32_bf16 v[50:53], v[180:183], v[164:167], v[50:53]
	s_waitcnt lgkmcnt(3)
	v_mfma_f32_16x16x32_bf16 v[46:49], v[188:191], v[156:159], v[46:49]
	v_mfma_f32_16x16x32_bf16 v[42:45], v[188:191], v[164:167], v[42:45]
	s_waitcnt lgkmcnt(1)
	v_mfma_f32_16x16x32_bf16 v[38:41], v[196:199], v[156:159], v[38:41]
	v_mfma_f32_16x16x32_bf16 v[34:37], v[196:199], v[164:167], v[34:37]
	v_mfma_f32_16x16x32_bf16 v[62:65], v[176:179], v[160:163], v[62:65]
	v_mfma_f32_16x16x32_bf16 v[58:61], v[176:179], v[168:171], v[58:61]
	v_mfma_f32_16x16x32_bf16 v[54:57], v[184:187], v[160:163], v[54:57]
	v_mfma_f32_16x16x32_bf16 v[50:53], v[184:187], v[168:171], v[50:53]
	v_mfma_f32_16x16x32_bf16 v[46:49], v[192:195], v[160:163], v[46:49]
	v_mfma_f32_16x16x32_bf16 v[42:45], v[192:195], v[168:171], v[42:45]
	s_waitcnt lgkmcnt(0)
	v_mfma_f32_16x16x32_bf16 v[38:41], v[200:203], v[160:163], v[38:41]
	v_mfma_f32_16x16x32_bf16 v[34:37], v[200:203], v[168:171], v[34:37]
	s_barrier
	v_readfirstlane_b32 s3, v143
	s_mov_b32 m0, s3
	v_readfirstlane_b32 s3, v146
	buffer_load_dwordx4 v137, s[4:7], s1 offen lds
	s_mov_b32 m0, s3
	s_nop 0
	buffer_load_dwordx4 v136, s[4:7], s1 offen lds
	s_waitcnt vmcnt(6)
	s_barrier
	v_mfma_f32_16x16x32_bf16 v[30:33], v[172:175], v[204:207], v[30:33]
	v_mfma_f32_16x16x32_bf16 v[26:29], v[172:175], v[212:215], v[26:29]
	v_mfma_f32_16x16x32_bf16 v[22:25], v[180:183], v[204:207], v[22:25]
	v_mfma_f32_16x16x32_bf16 v[18:21], v[180:183], v[212:215], v[18:21]
	v_mfma_f32_16x16x32_bf16 v[14:17], v[188:191], v[204:207], v[14:17]
	v_mfma_f32_16x16x32_bf16 v[10:13], v[188:191], v[212:215], v[10:13]
	v_mfma_f32_16x16x32_bf16 v[6:9], v[196:199], v[204:207], v[6:9]
	v_mfma_f32_16x16x32_bf16 v[2:5], v[196:199], v[212:215], v[2:5]
	v_mfma_f32_16x16x32_bf16 v[30:33], v[176:179], v[208:211], v[30:33]
	v_mfma_f32_16x16x32_bf16 v[26:29], v[176:179], v[216:219], v[26:29]
	v_mfma_f32_16x16x32_bf16 v[22:25], v[184:187], v[208:211], v[22:25]
	v_mfma_f32_16x16x32_bf16 v[18:21], v[184:187], v[216:219], v[18:21]
	v_mfma_f32_16x16x32_bf16 v[14:17], v[192:195], v[208:211], v[14:17]
	v_mfma_f32_16x16x32_bf16 v[10:13], v[192:195], v[216:219], v[10:13]
	v_mfma_f32_16x16x32_bf16 v[6:9], v[200:203], v[208:211], v[6:9]
	v_mfma_f32_16x16x32_bf16 v[2:5], v[200:203], v[216:219], v[2:5]
	s_add_i32 s0, s0, 2
	s_addk_i32 s1, 0x100
	s_cmp_lt_u32 s0, 28
	s_barrier
	s_cbranch_scc1 .LBB0_247
	v_readfirstlane_b32 s0, v145
	s_mov_b32 m0, s0
	s_mov_b32 s1, 0x80f80
	v_readfirstlane_b32 s0, v144
	ds_read_b128 v[138:141], v155
	ds_read_b128 v[148:151], v155 offset:1024
	ds_read_b128 v[156:159], v155 offset:2048
	ds_read_b128 v[152:155], v155 offset:3072
	ds_read_b128 v[160:163], v133
	ds_read_b128 v[164:167], v133 offset:1024
	ds_read_b128 v[168:171], v132
	ds_read_b128 v[172:175], v132 offset:1024
	ds_read_b128 v[176:179], v131
	ds_read_b128 v[180:183], v131 offset:1024
	ds_read_b128 v[184:187], v130
	ds_read_b128 v[188:191], v130 offset:1024
	buffer_load_dwordx4 v137, s[88:91], s1 offen lds
	s_mov_b32 m0, s0
	s_nop 0
	buffer_load_dwordx4 v136, s[88:91], s1 offen lds
	s_barrier
	s_waitcnt lgkmcnt(0)
	s_waitcnt lgkmcnt(7)
	v_mfma_f32_16x16x32_bf16 v[126:129], v[160:163], v[138:141], v[126:129]
	s_waitcnt lgkmcnt(5)
	v_mfma_f32_16x16x32_bf16 v[118:121], v[168:171], v[138:141], v[118:121]
	s_waitcnt lgkmcnt(3)
	v_mfma_f32_16x16x32_bf16 v[110:113], v[176:179], v[138:141], v[110:113]
	s_waitcnt lgkmcnt(1)
	v_mfma_f32_16x16x32_bf16 v[102:105], v[184:187], v[138:141], v[102:105]
	v_mfma_f32_16x16x32_bf16 v[126:129], v[164:167], v[148:151], v[126:129]
	v_mfma_f32_16x16x32_bf16 v[122:125], v[160:163], v[156:159], v[122:125]
	v_mfma_f32_16x16x32_bf16 v[118:121], v[172:175], v[148:151], v[118:121]
	v_mfma_f32_16x16x32_bf16 v[114:117], v[168:171], v[156:159], v[114:117]
	v_mfma_f32_16x16x32_bf16 v[110:113], v[180:183], v[148:151], v[110:113]
	v_mfma_f32_16x16x32_bf16 v[106:109], v[176:179], v[156:159], v[106:109]
	s_waitcnt lgkmcnt(0)
	v_mfma_f32_16x16x32_bf16 v[102:105], v[188:191], v[148:151], v[102:105]
	v_mfma_f32_16x16x32_bf16 v[98:101], v[184:187], v[156:159], v[98:101]
	v_mfma_f32_16x16x32_bf16 v[142:145], v[164:167], v[152:155], v[122:125]
	v_mfma_f32_16x16x32_bf16 v[192:195], v[172:175], v[152:155], v[114:117]
	v_mfma_f32_16x16x32_bf16 v[196:199], v[180:183], v[152:155], v[106:109]
	v_mfma_f32_16x16x32_bf16 v[200:203], v[188:191], v[152:155], v[98:101]
	s_barrier
	s_nop 1
	ds_read_b128 v[98:101], v147
	ds_read_b128 v[106:109], v147 offset:1024
	ds_read_b128 v[114:117], v147 offset:2048
	ds_read_b128 v[122:125], v147 offset:3072
	s_barrier
	s_waitcnt lgkmcnt(0)
	s_waitcnt lgkmcnt(3)
	v_mfma_f32_16x16x32_bf16 v[94:97], v[160:163], v[98:101], v[94:97]
	s_waitcnt lgkmcnt(1)
	v_mfma_f32_16x16x32_bf16 v[90:93], v[160:163], v[114:117], v[90:93]
	v_mfma_f32_16x16x32_bf16 v[86:89], v[168:171], v[98:101], v[86:89]
	v_mfma_f32_16x16x32_bf16 v[82:85], v[168:171], v[114:117], v[82:85]
	v_mfma_f32_16x16x32_bf16 v[78:81], v[176:179], v[98:101], v[78:81]
	v_mfma_f32_16x16x32_bf16 v[74:77], v[176:179], v[114:117], v[74:77]
	v_mfma_f32_16x16x32_bf16 v[70:73], v[184:187], v[98:101], v[70:73]
	v_mfma_f32_16x16x32_bf16 v[66:69], v[184:187], v[114:117], v[66:69]
	v_mfma_f32_16x16x32_bf16 v[94:97], v[164:167], v[106:109], v[94:97]
	s_waitcnt lgkmcnt(0)
	v_mfma_f32_16x16x32_bf16 v[90:93], v[164:167], v[122:125], v[90:93]
	v_mfma_f32_16x16x32_bf16 v[86:89], v[172:175], v[106:109], v[86:89]
	v_mfma_f32_16x16x32_bf16 v[82:85], v[172:175], v[122:125], v[82:85]
	v_mfma_f32_16x16x32_bf16 v[78:81], v[180:183], v[106:109], v[78:81]
	v_mfma_f32_16x16x32_bf16 v[74:77], v[180:183], v[122:125], v[74:77]
	v_mfma_f32_16x16x32_bf16 v[70:73], v[188:191], v[106:109], v[70:73]
	v_mfma_f32_16x16x32_bf16 v[66:69], v[188:191], v[122:125], v[66:69]
	s_barrier
; #define WAIT_V(n) asm volatile("s_waitcnt vmcnt(" #n ")" ::: "memory")
; #define WAIT_L(n) asm volatile("s_waitcnt lgkmcnt(" #n ")" ::: "memory")
; #define BAR __builtin_amdgcn_s_barrier()
; __device__ __forceinline__ void mainloop_8phase(const u16* __restrict__ A, const u16* __restrict__ Bt, int K,
;                                                 f32x4 (&acc)[2][2][4][2], int wid_s, int ld) {
;     ...
;     LDA(At, 0, 1); WAIT_V(4); BAR; WAIT_L(0); MMA(1, 0, At, B0); MMA(1, 1, At, B1); BAR; }
;   { LDB(B0, 1, 0); LDA(At, 1, 0); WAIT_V(2); BAR; WAIT_L(0); MMA(0, 0, At, B0); BAR;
	ds_read_b128 v[160:163], v133 offset:16384
	ds_read_b128 v[164:167], v133 offset:17408
	ds_read_b128 v[168:171], v132 offset:16384
	ds_read_b128 v[172:175], v132 offset:17408
	ds_read_b128 v[176:179], v131 offset:16384
	ds_read_b128 v[180:183], v131 offset:17408
	ds_read_b128 v[184:187], v130 offset:16384
	ds_read_b128 v[188:191], v130 offset:17408
	s_waitcnt vmcnt(4)
	s_barrier
	s_waitcnt lgkmcnt(0)
	s_waitcnt lgkmcnt(7)
	v_mfma_f32_16x16x32_bf16 v[62:65], v[160:163], v[138:141], v[62:65]
	v_mfma_f32_16x16x32_bf16 v[58:61], v[160:163], v[156:159], v[58:61]
	s_waitcnt lgkmcnt(5)
	v_mfma_f32_16x16x32_bf16 v[54:57], v[168:171], v[138:141], v[54:57]
	v_mfma_f32_16x16x32_bf16 v[50:53], v[168:171], v[156:159], v[50:53]
	s_waitcnt lgkmcnt(3)
	v_mfma_f32_16x16x32_bf16 v[46:49], v[176:179], v[138:141], v[46:49]
	v_mfma_f32_16x16x32_bf16 v[42:45], v[176:179], v[156:159], v[42:45]
	s_waitcnt lgkmcnt(1)
	v_mfma_f32_16x16x32_bf16 v[38:41], v[184:187], v[138:141], v[38:41]
	v_mfma_f32_16x16x32_bf16 v[34:37], v[184:187], v[156:159], v[34:37]
	v_mfma_f32_16x16x32_bf16 v[204:207], v[164:167], v[148:151], v[62:65]
	v_mfma_f32_16x16x32_bf16 v[208:211], v[164:167], v[152:155], v[58:61]
	v_mfma_f32_16x16x32_bf16 v[212:215], v[172:175], v[148:151], v[54:57]
	v_mfma_f32_16x16x32_bf16 v[216:219], v[172:175], v[152:155], v[50:53]
	v_mfma_f32_16x16x32_bf16 v[220:223], v[180:183], v[148:151], v[46:49]
	v_mfma_f32_16x16x32_bf16 v[224:227], v[180:183], v[152:155], v[42:45]
	s_waitcnt lgkmcnt(0)
	v_mfma_f32_16x16x32_bf16 v[136:139], v[188:191], v[148:151], v[38:41]
	v_mfma_f32_16x16x32_bf16 v[146:149], v[188:191], v[152:155], v[34:37]
	v_mfma_f32_16x16x32_bf16 v[30:33], v[160:163], v[98:101], v[30:33]
	v_mfma_f32_16x16x32_bf16 v[22:25], v[168:171], v[98:101], v[22:25]
	v_mfma_f32_16x16x32_bf16 v[14:17], v[176:179], v[98:101], v[14:17]
	v_mfma_f32_16x16x32_bf16 v[6:9], v[184:187], v[98:101], v[6:9]
	v_mfma_f32_16x16x32_bf16 v[30:33], v[164:167], v[106:109], v[30:33]
	v_mfma_f32_16x16x32_bf16 v[26:29], v[160:163], v[114:117], v[26:29]
	v_mfma_f32_16x16x32_bf16 v[22:25], v[172:175], v[106:109], v[22:25]
	v_mfma_f32_16x16x32_bf16 v[18:21], v[168:171], v[114:117], v[18:21]
	v_mfma_f32_16x16x32_bf16 v[14:17], v[180:183], v[106:109], v[14:17]
	v_mfma_f32_16x16x32_bf16 v[10:13], v[176:179], v[114:117], v[10:13]
	v_mfma_f32_16x16x32_bf16 v[6:9], v[188:191], v[106:109], v[6:9]
	v_mfma_f32_16x16x32_bf16 v[2:5], v[184:187], v[114:117], v[2:5]
	v_mfma_f32_16x16x32_bf16 v[150:153], v[164:167], v[122:125], v[26:29]
	v_mfma_f32_16x16x32_bf16 v[154:157], v[172:175], v[122:125], v[18:21]
	v_mfma_f32_16x16x32_bf16 v[158:161], v[180:183], v[122:125], v[10:13]
	v_mfma_f32_16x16x32_bf16 v[162:165], v[188:191], v[122:125], v[2:5]
	s_barrier
	s_nop 1
	ds_read_b128 v[2:5], v135
	ds_read_b128 v[10:13], v135 offset:1024
	ds_read_b128 v[18:21], v135 offset:2048
	ds_read_b128 v[26:29], v135 offset:3072
	ds_read_b128 v[34:37], v133 offset:32768
	ds_read_b128 v[38:41], v133 offset:33792
	ds_read_b128 v[42:45], v132 offset:32768
	ds_read_b128 v[46:49], v132 offset:33792
	ds_read_b128 v[166:169], v131 offset:32768
	ds_read_b128 v[170:173], v131 offset:33792
	ds_read_b128 v[174:177], v130 offset:32768
	ds_read_b128 v[178:181], v130 offset:33792
	s_waitcnt vmcnt(2)
	s_barrier
	s_waitcnt lgkmcnt(0)
	s_waitcnt lgkmcnt(7)
	v_mfma_f32_16x16x32_bf16 v[50:53], v[34:37], v[2:5], v[126:129]
	s_waitcnt lgkmcnt(6)
	v_mfma_f32_16x16x32_bf16 v[122:125], v[38:41], v[10:13], v[50:53]
	v_mfma_f32_16x16x32_bf16 v[50:53], v[34:37], v[18:21], v[142:145]
	v_mfma_f32_16x16x32_bf16 v[126:129], v[38:41], v[26:29], v[50:53]
	s_waitcnt lgkmcnt(5)
	v_mfma_f32_16x16x32_bf16 v[50:53], v[42:45], v[2:5], v[118:121]
	s_waitcnt lgkmcnt(4)
	v_mfma_f32_16x16x32_bf16 v[114:117], v[46:49], v[10:13], v[50:53]
	v_mfma_f32_16x16x32_bf16 v[50:53], v[42:45], v[18:21], v[192:195]
	v_mfma_f32_16x16x32_bf16 v[118:121], v[46:49], v[26:29], v[50:53]
	s_waitcnt lgkmcnt(3)
	v_mfma_f32_16x16x32_bf16 v[50:53], v[166:169], v[2:5], v[110:113]
	s_waitcnt lgkmcnt(2)
	v_mfma_f32_16x16x32_bf16 v[106:109], v[170:173], v[10:13], v[50:53]
	v_mfma_f32_16x16x32_bf16 v[50:53], v[166:169], v[18:21], v[196:199]
	v_mfma_f32_16x16x32_bf16 v[110:113], v[170:173], v[26:29], v[50:53]
	s_waitcnt lgkmcnt(1)
	v_mfma_f32_16x16x32_bf16 v[50:53], v[174:177], v[2:5], v[102:105]
	s_waitcnt lgkmcnt(0)
	v_mfma_f32_16x16x32_bf16 v[98:101], v[178:181], v[10:13], v[50:53]
	v_mfma_f32_16x16x32_bf16 v[50:53], v[174:177], v[18:21], v[200:203]
	v_mfma_f32_16x16x32_bf16 v[102:105], v[178:181], v[26:29], v[50:53]
	s_barrier
; #define WAIT_V(n) asm volatile("s_waitcnt vmcnt(" #n ")" ::: "memory")
; #define WAIT_L(n) asm volatile("s_waitcnt lgkmcnt(" #n ")" ::: "memory")
; #define BAR __builtin_amdgcn_s_barrier()
; __device__ __forceinline__ void mainloop_8phase(const u16* __restrict__ A, const u16* __restrict__ Bt, int K,
;                                                 f32x4 (&acc)[2][2][4][2], int wid_s, int ld) {
;     ...
;   { LDB(B0, 1, 0); LDA(At, 1, 0); WAIT_V(2); BAR; WAIT_L(0); MMA(0, 0, At, B0); BAR;
;     LDB(B1, 1, 1); WAIT_V(0); BAR; WAIT_L(0); MMA(0, 1, At, B1); BAR;
;     LDA(At, 1, 1); BAR; WAIT_L(0); MMA(1, 0, At, B0); MMA(1, 1, At, B1); BAR; }
;   if (wr == 0) BAR;
	ds_read_b128 v[140:143], v134
	ds_read_b128 v[182:185], v134 offset:1024
	ds_read_b128 v[186:189], v134 offset:2048
	ds_read_b128 v[190:193], v134 offset:3072
	s_waitcnt vmcnt(0)
	s_barrier
	s_waitcnt lgkmcnt(0)
	s_waitcnt lgkmcnt(3)
	v_mfma_f32_16x16x32_bf16 v[50:53], v[34:37], v[140:143], v[94:97]
	s_waitcnt lgkmcnt(1)
	v_mfma_f32_16x16x32_bf16 v[34:37], v[34:37], v[186:189], v[90:93]
	s_waitcnt lgkmcnt(0)
	v_mfma_f32_16x16x32_bf16 v[62:65], v[38:41], v[190:193], v[34:37]
	v_mfma_f32_16x16x32_bf16 v[34:37], v[42:45], v[140:143], v[86:89]
	v_mfma_f32_16x16x32_bf16 v[58:61], v[38:41], v[182:185], v[50:53]
	v_mfma_f32_16x16x32_bf16 v[50:53], v[46:49], v[182:185], v[34:37]
	v_mfma_f32_16x16x32_bf16 v[34:37], v[42:45], v[186:189], v[82:85]
	v_mfma_f32_16x16x32_bf16 v[54:57], v[46:49], v[190:193], v[34:37]
	v_mfma_f32_16x16x32_bf16 v[34:37], v[166:169], v[140:143], v[78:81]
	v_mfma_f32_16x16x32_bf16 v[42:45], v[170:173], v[182:185], v[34:37]
	v_mfma_f32_16x16x32_bf16 v[34:37], v[166:169], v[186:189], v[74:77]
	v_mfma_f32_16x16x32_bf16 v[46:49], v[170:173], v[190:193], v[34:37]
	v_mfma_f32_16x16x32_bf16 v[34:37], v[174:177], v[140:143], v[70:73]
	v_mfma_f32_16x16x32_bf16 v[38:41], v[174:177], v[186:189], v[66:69]
	v_mfma_f32_16x16x32_bf16 v[34:37], v[178:181], v[182:185], v[34:37]
	v_mfma_f32_16x16x32_bf16 v[38:41], v[178:181], v[190:193], v[38:41]
	s_barrier
	ds_read_b128 v[166:169], v133 offset:49152
	ds_read_b128 v[170:173], v133 offset:50176
	ds_read_b128 v[174:177], v132 offset:49152
	ds_read_b128 v[132:135], v132 offset:50176
	ds_read_b128 v[178:181], v131 offset:49152
	ds_read_b128 v[194:197], v131 offset:50176
	ds_read_b128 v[198:201], v130 offset:49152
	ds_read_b128 v[228:231], v130 offset:50176
	s_barrier
	s_waitcnt lgkmcnt(0)
	s_waitcnt lgkmcnt(7)
	v_mfma_f32_16x16x32_bf16 v[66:69], v[166:169], v[2:5], v[204:207]
	s_waitcnt lgkmcnt(6)
	v_mfma_f32_16x16x32_bf16 v[90:93], v[170:173], v[10:13], v[66:69]
	v_mfma_f32_16x16x32_bf16 v[66:69], v[166:169], v[18:21], v[208:211]
	v_mfma_f32_16x16x32_bf16 v[94:97], v[170:173], v[26:29], v[66:69]
	s_waitcnt lgkmcnt(5)
	v_mfma_f32_16x16x32_bf16 v[66:69], v[174:177], v[2:5], v[212:215]
	s_waitcnt lgkmcnt(4)
	v_mfma_f32_16x16x32_bf16 v[82:85], v[132:135], v[10:13], v[66:69]
	v_mfma_f32_16x16x32_bf16 v[66:69], v[174:177], v[18:21], v[216:219]
	v_mfma_f32_16x16x32_bf16 v[86:89], v[132:135], v[26:29], v[66:69]
	s_waitcnt lgkmcnt(3)
	v_mfma_f32_16x16x32_bf16 v[66:69], v[178:181], v[2:5], v[220:223]
	s_waitcnt lgkmcnt(2)
	v_mfma_f32_16x16x32_bf16 v[74:77], v[194:197], v[10:13], v[66:69]
	v_mfma_f32_16x16x32_bf16 v[66:69], v[178:181], v[18:21], v[224:227]
	s_waitcnt lgkmcnt(1)
	v_mfma_f32_16x16x32_bf16 v[2:5], v[198:201], v[2:5], v[136:139]
	v_mfma_f32_16x16x32_bf16 v[78:81], v[194:197], v[26:29], v[66:69]
	s_waitcnt lgkmcnt(0)
	v_mfma_f32_16x16x32_bf16 v[66:69], v[228:231], v[10:13], v[2:5]
	v_mfma_f32_16x16x32_bf16 v[2:5], v[198:201], v[18:21], v[146:149]
	v_mfma_f32_16x16x32_bf16 v[70:73], v[228:231], v[26:29], v[2:5]
	v_mfma_f32_16x16x32_bf16 v[2:5], v[166:169], v[140:143], v[30:33]
	v_mfma_f32_16x16x32_bf16 v[26:29], v[170:173], v[182:185], v[2:5]
	v_mfma_f32_16x16x32_bf16 v[2:5], v[166:169], v[186:189], v[150:153]
	v_mfma_f32_16x16x32_bf16 v[30:33], v[170:173], v[190:193], v[2:5]
	v_mfma_f32_16x16x32_bf16 v[2:5], v[174:177], v[140:143], v[22:25]
	v_mfma_f32_16x16x32_bf16 v[18:21], v[132:135], v[182:185], v[2:5]
	v_mfma_f32_16x16x32_bf16 v[2:5], v[174:177], v[186:189], v[154:157]
	v_mfma_f32_16x16x32_bf16 v[22:25], v[132:135], v[190:193], v[2:5]
	v_mfma_f32_16x16x32_bf16 v[2:5], v[178:181], v[140:143], v[14:17]
	v_mfma_f32_16x16x32_bf16 v[10:13], v[194:197], v[182:185], v[2:5]
	v_mfma_f32_16x16x32_bf16 v[2:5], v[178:181], v[186:189], v[158:161]
	v_mfma_f32_16x16x32_bf16 v[14:17], v[194:197], v[190:193], v[2:5]
	v_mfma_f32_16x16x32_bf16 v[2:5], v[198:201], v[140:143], v[6:9]
	v_mfma_f32_16x16x32_bf16 v[6:9], v[198:201], v[186:189], v[162:165]
	v_mfma_f32_16x16x32_bf16 v[2:5], v[228:231], v[182:185], v[2:5]
	v_mfma_f32_16x16x32_bf16 v[6:9], v[228:231], v[190:193], v[6:9]
	s_movk_i32 s0, 0x100
	v_cmp_gt_u32_e32 vcc, s0, v0
	s_barrier
	s_and_saveexec_b64 s[0:1], vcc
	s_cbranch_execz .LBB0_250
	s_barrier

; #define WAIT_V(n) asm volatile("s_waitcnt vmcnt(" #n ")" ::: "memory")
; #define WAIT_L(n) asm volatile("s_waitcnt lgkmcnt(" #n ")" ::: "memory")
; #define BAR __builtin_amdgcn_s_barrier()
; #define SCHED __builtin_amdgcn_sched_barrier(0)
; __device__ __forceinline__ void mainloop_8phase(const u16* __restrict__ A, const u16* __restrict__ Bt, int K,
;                                                 f32x4 (&acc)[2][2][4][2], int wid_s, int ld) {
;     ...
;   for (int t = 0; t < nt - 2; t += 2) {
;     LDB(B0, 0, 0); SCHED; LDA(At, 0, 0); STAGE(SA(1, 1), A, brow + G_HALF, t + 1);
;     WAIT_L(8); BAR; WAIT_L(0); MMA(0, 0, At, B0); BAR; SCHED;
;     LDB(B1, 0, 1); STAGE(SB(0, 0), Bt, bcol, t + 2);
;     BAR; WAIT_L(0); MMA(0, 1, At, B1); BAR;
;     LDA(At, 0, 1); STAGE(SA(0, 0), A, brow, t + 2);
;     BAR; WAIT_L(0); MMA(1, 0, At, B0); BAR; SCHED;
;     STAGE(SB(0, 1), Bt, bcol + G_HALF, t + 2);
;     WAIT_V(6); BAR; MMA(1, 1, At, B1); BAR;
.LBB0_342:
	ds_read_b128 v[156:159], v155
	ds_read_b128 v[160:163], v155 offset:1024
	ds_read_b128 v[164:167], v155 offset:2048
	ds_read_b128 v[168:171], v155 offset:3072
	v_readfirstlane_b32 s6, v145
	s_add_i32 s3, s2, 0xffffff00
	s_mov_b32 m0, s6
	v_readfirstlane_b32 s6, v144
	ds_read_b128 v[172:175], v133
	ds_read_b128 v[176:179], v133 offset:1024
	ds_read_b128 v[180:183], v132
	ds_read_b128 v[184:187], v132 offset:1024
	ds_read_b128 v[188:191], v131
	ds_read_b128 v[192:195], v131 offset:1024
	ds_read_b128 v[196:199], v130
	ds_read_b128 v[200:203], v130 offset:1024
	buffer_load_dwordx4 v136, s[88:91], s3 offen lds
	s_mov_b32 m0, s6
	s_nop 0
	buffer_load_dwordx4 v135, s[88:91], s3 offen lds
	s_waitcnt lgkmcnt(8)
	s_barrier
	s_waitcnt lgkmcnt(0)
	s_waitcnt lgkmcnt(7)
	v_mfma_f32_16x16x32_bf16 v[126:129], v[172:175], v[156:159], v[126:129]
	v_mfma_f32_16x16x32_bf16 v[122:125], v[172:175], v[164:167], v[122:125]
	s_waitcnt lgkmcnt(5)
	v_mfma_f32_16x16x32_bf16 v[118:121], v[180:183], v[156:159], v[118:121]
	v_mfma_f32_16x16x32_bf16 v[114:117], v[180:183], v[164:167], v[114:117]
	s_waitcnt lgkmcnt(3)
	v_mfma_f32_16x16x32_bf16 v[110:113], v[188:191], v[156:159], v[110:113]
	v_mfma_f32_16x16x32_bf16 v[106:109], v[188:191], v[164:167], v[106:109]
	s_waitcnt lgkmcnt(1)
	v_mfma_f32_16x16x32_bf16 v[102:105], v[196:199], v[156:159], v[102:105]
	v_mfma_f32_16x16x32_bf16 v[98:101], v[196:199], v[164:167], v[98:101]
	v_mfma_f32_16x16x32_bf16 v[126:129], v[176:179], v[160:163], v[126:129]
	v_mfma_f32_16x16x32_bf16 v[122:125], v[176:179], v[168:171], v[122:125]
	v_mfma_f32_16x16x32_bf16 v[118:121], v[184:187], v[160:163], v[118:121]
	v_mfma_f32_16x16x32_bf16 v[114:117], v[184:187], v[168:171], v[114:117]
	v_mfma_f32_16x16x32_bf16 v[110:113], v[192:195], v[160:163], v[110:113]
	v_mfma_f32_16x16x32_bf16 v[106:109], v[192:195], v[168:171], v[106:109]
	s_waitcnt lgkmcnt(0)
	v_mfma_f32_16x16x32_bf16 v[102:105], v[200:203], v[160:163], v[102:105]
	v_mfma_f32_16x16x32_bf16 v[98:101], v[200:203], v[168:171], v[98:101]
	s_barrier
	v_readfirstlane_b32 s9, v148
	s_add_i32 s3, s2, 0xfff7ff80
	s_mov_b32 s6, s90
	s_mov_b32 s7, s91
	s_mov_b32 m0, s9
	v_readfirstlane_b32 s9, v149
	ds_read_b128 v[204:207], v147
	ds_read_b128 v[208:211], v147 offset:1024
	ds_read_b128 v[212:215], v147 offset:2048
	ds_read_b128 v[216:219], v147 offset:3072
	buffer_load_dwordx4 v136, s[4:7], s3 offen lds
	s_mov_b32 m0, s9
	s_nop 0
	buffer_load_dwordx4 v135, s[4:7], s3 offen lds
	s_barrier
	s_waitcnt lgkmcnt(0)
	s_waitcnt lgkmcnt(3)
	v_mfma_f32_16x16x32_bf16 v[94:97], v[172:175], v[204:207], v[94:97]
	s_waitcnt lgkmcnt(1)
	v_mfma_f32_16x16x32_bf16 v[90:93], v[172:175], v[212:215], v[90:93]
	v_mfma_f32_16x16x32_bf16 v[86:89], v[180:183], v[204:207], v[86:89]
	v_mfma_f32_16x16x32_bf16 v[82:85], v[180:183], v[212:215], v[82:85]
	v_mfma_f32_16x16x32_bf16 v[78:81], v[188:191], v[204:207], v[78:81]
	v_mfma_f32_16x16x32_bf16 v[74:77], v[188:191], v[212:215], v[74:77]
	v_mfma_f32_16x16x32_bf16 v[70:73], v[196:199], v[204:207], v[70:73]
	v_mfma_f32_16x16x32_bf16 v[66:69], v[196:199], v[212:215], v[66:69]
	v_mfma_f32_16x16x32_bf16 v[94:97], v[176:179], v[208:211], v[94:97]
	s_waitcnt lgkmcnt(0)
	v_mfma_f32_16x16x32_bf16 v[90:93], v[176:179], v[216:219], v[90:93]
	v_mfma_f32_16x16x32_bf16 v[86:89], v[184:187], v[208:211], v[86:89]
	v_mfma_f32_16x16x32_bf16 v[82:85], v[184:187], v[216:219], v[82:85]
	v_mfma_f32_16x16x32_bf16 v[78:81], v[192:195], v[208:211], v[78:81]
	v_mfma_f32_16x16x32_bf16 v[74:77], v[192:195], v[216:219], v[74:77]
	v_mfma_f32_16x16x32_bf16 v[70:73], v[200:203], v[208:211], v[70:73]
	v_mfma_f32_16x16x32_bf16 v[66:69], v[200:203], v[216:219], v[66:69]
	v_readfirstlane_b32 s9, v140
	s_mov_b32 m0, s9
	v_readfirstlane_b32 s9, v150
	s_barrier
	ds_read_b128 v[172:175], v133 offset:16384
	ds_read_b128 v[176:179], v133 offset:17408
	ds_read_b128 v[180:183], v132 offset:16384
	ds_read_b128 v[184:187], v132 offset:17408
	ds_read_b128 v[188:191], v131 offset:16384
	ds_read_b128 v[192:195], v131 offset:17408
	ds_read_b128 v[196:199], v130 offset:16384
	ds_read_b128 v[200:203], v130 offset:17408
	buffer_load_dwordx4 v136, s[88:91], s3 offen lds
	s_mov_b32 m0, s9
	s_nop 0
	buffer_load_dwordx4 v135, s[88:91], s3 offen lds
	s_barrier
	s_waitcnt lgkmcnt(0)
	s_waitcnt lgkmcnt(7)
	v_mfma_f32_16x16x32_bf16 v[62:65], v[172:175], v[156:159], v[62:65]
	v_mfma_f32_16x16x32_bf16 v[58:61], v[172:175], v[164:167], v[58:61]
	s_waitcnt lgkmcnt(5)
	v_mfma_f32_16x16x32_bf16 v[54:57], v[180:183], v[156:159], v[54:57]
	v_mfma_f32_16x16x32_bf16 v[50:53], v[180:183], v[164:167], v[50:53]
	s_waitcnt lgkmcnt(3)
	v_mfma_f32_16x16x32_bf16 v[46:49], v[188:191], v[156:159], v[46:49]
	v_mfma_f32_16x16x32_bf16 v[42:45], v[188:191], v[164:167], v[42:45]
	s_waitcnt lgkmcnt(1)
	v_mfma_f32_16x16x32_bf16 v[38:41], v[196:199], v[156:159], v[38:41]
	v_mfma_f32_16x16x32_bf16 v[34:37], v[196:199], v[164:167], v[34:37]
	v_mfma_f32_16x16x32_bf16 v[62:65], v[176:179], v[160:163], v[62:65]
	v_mfma_f32_16x16x32_bf16 v[58:61], v[176:179], v[168:171], v[58:61]
	v_mfma_f32_16x16x32_bf16 v[54:57], v[184:187], v[160:163], v[54:57]
	v_mfma_f32_16x16x32_bf16 v[50:53], v[184:187], v[168:171], v[50:53]
	v_mfma_f32_16x16x32_bf16 v[46:49], v[192:195], v[160:163], v[46:49]
	v_mfma_f32_16x16x32_bf16 v[42:45], v[192:195], v[168:171], v[42:45]
	s_waitcnt lgkmcnt(0)
	v_mfma_f32_16x16x32_bf16 v[38:41], v[200:203], v[160:163], v[38:41]
	v_mfma_f32_16x16x32_bf16 v[34:37], v[200:203], v[168:171], v[34:37]
	s_barrier
	v_readfirstlane_b32 s9, v151
	s_add_i32 s3, s2, 0xffffff80
	s_mov_b32 m0, s9
	v_readfirstlane_b32 s9, v152
	buffer_load_dwordx4 v136, s[4:7], s3 offen lds
	s_mov_b32 m0, s9
	s_nop 0
	buffer_load_dwordx4 v135, s[4:7], s3 offen lds
	s_waitcnt vmcnt(6)
	s_barrier
; #define WAIT_V(n) asm volatile("s_waitcnt vmcnt(" #n ")" ::: "memory")
; #define WAIT_L(n) asm volatile("s_waitcnt lgkmcnt(" #n ")" ::: "memory")
; #define BAR __builtin_amdgcn_s_barrier()
; #define SCHED __builtin_amdgcn_sched_barrier(0)
; __device__ __forceinline__ void mainloop_8phase(const u16* __restrict__ A, const u16* __restrict__ Bt, int K,
;                                                 f32x4 (&acc)[2][2][4][2], int wid_s, int ld) {
;     ...
;     WAIT_V(6); BAR; MMA(1, 1, At, B1); BAR;
;     LDB(B0, 1, 0); SCHED; LDA(At, 1, 0); STAGE(SA(0, 1), A, brow + G_HALF, t + 2);
;     WAIT_L(8); BAR; WAIT_L(0); MMA(0, 0, At, B0); BAR; SCHED;
;     LDB(B1, 1, 1); STAGE(SB(1, 0), Bt, bcol, t + 3);
;     BAR; WAIT_L(0); MMA(0, 1, At, B1); BAR;
;     LDA(At, 1, 1); STAGE(SA(1, 0), A, brow, t + 3);
	v_mfma_f32_16x16x32_bf16 v[30:33], v[172:175], v[204:207], v[30:33]
	v_mfma_f32_16x16x32_bf16 v[26:29], v[172:175], v[212:215], v[26:29]
	v_mfma_f32_16x16x32_bf16 v[22:25], v[180:183], v[204:207], v[22:25]
	v_mfma_f32_16x16x32_bf16 v[18:21], v[180:183], v[212:215], v[18:21]
	v_mfma_f32_16x16x32_bf16 v[14:17], v[188:191], v[204:207], v[14:17]
	v_mfma_f32_16x16x32_bf16 v[10:13], v[188:191], v[212:215], v[10:13]
	v_mfma_f32_16x16x32_bf16 v[6:9], v[196:199], v[204:207], v[6:9]
	v_mfma_f32_16x16x32_bf16 v[2:5], v[196:199], v[212:215], v[2:5]
	v_mfma_f32_16x16x32_bf16 v[30:33], v[176:179], v[208:211], v[30:33]
	v_mfma_f32_16x16x32_bf16 v[26:29], v[176:179], v[216:219], v[26:29]
	v_mfma_f32_16x16x32_bf16 v[22:25], v[184:187], v[208:211], v[22:25]
	v_mfma_f32_16x16x32_bf16 v[18:21], v[184:187], v[216:219], v[18:21]
	v_mfma_f32_16x16x32_bf16 v[14:17], v[192:195], v[208:211], v[14:17]
	v_mfma_f32_16x16x32_bf16 v[10:13], v[192:195], v[216:219], v[10:13]
	v_mfma_f32_16x16x32_bf16 v[6:9], v[200:203], v[208:211], v[6:9]
	v_mfma_f32_16x16x32_bf16 v[2:5], v[200:203], v[216:219], v[2:5]
	s_barrier
	ds_read_b128 v[156:159], v137
	ds_read_b128 v[160:163], v137 offset:1024
	ds_read_b128 v[164:167], v137 offset:2048
	ds_read_b128 v[168:171], v137 offset:3072
	v_readfirstlane_b32 s9, v153
	s_mov_b32 m0, s9
	v_readfirstlane_b32 s9, v154
	ds_read_b128 v[172:175], v133 offset:32768
	ds_read_b128 v[176:179], v133 offset:33792
	ds_read_b128 v[180:183], v132 offset:32768
	ds_read_b128 v[184:187], v132 offset:33792
	ds_read_b128 v[188:191], v131 offset:32768
	ds_read_b128 v[192:195], v131 offset:33792
	ds_read_b128 v[196:199], v130 offset:32768
	ds_read_b128 v[200:203], v130 offset:33792
	buffer_load_dwordx4 v136, s[88:91], s3 offen lds
	s_mov_b32 m0, s9
	s_nop 0
	buffer_load_dwordx4 v135, s[88:91], s3 offen lds
	s_waitcnt lgkmcnt(8)
	s_barrier
	s_waitcnt lgkmcnt(0)
	s_waitcnt lgkmcnt(7)
	v_mfma_f32_16x16x32_bf16 v[126:129], v[172:175], v[156:159], v[126:129]
	v_mfma_f32_16x16x32_bf16 v[122:125], v[172:175], v[164:167], v[122:125]
	s_waitcnt lgkmcnt(5)
	v_mfma_f32_16x16x32_bf16 v[118:121], v[180:183], v[156:159], v[118:121]
	v_mfma_f32_16x16x32_bf16 v[114:117], v[180:183], v[164:167], v[114:117]
	s_waitcnt lgkmcnt(3)
	v_mfma_f32_16x16x32_bf16 v[110:113], v[188:191], v[156:159], v[110:113]
	v_mfma_f32_16x16x32_bf16 v[106:109], v[188:191], v[164:167], v[106:109]
	s_waitcnt lgkmcnt(1)
	v_mfma_f32_16x16x32_bf16 v[102:105], v[196:199], v[156:159], v[102:105]
	v_mfma_f32_16x16x32_bf16 v[98:101], v[196:199], v[164:167], v[98:101]
	v_mfma_f32_16x16x32_bf16 v[126:129], v[176:179], v[160:163], v[126:129]
	v_mfma_f32_16x16x32_bf16 v[122:125], v[176:179], v[168:171], v[122:125]
	v_mfma_f32_16x16x32_bf16 v[118:121], v[184:187], v[160:163], v[118:121]
	v_mfma_f32_16x16x32_bf16 v[114:117], v[184:187], v[168:171], v[114:117]
	v_mfma_f32_16x16x32_bf16 v[110:113], v[192:195], v[160:163], v[110:113]
	v_mfma_f32_16x16x32_bf16 v[106:109], v[192:195], v[168:171], v[106:109]
	s_waitcnt lgkmcnt(0)
	v_mfma_f32_16x16x32_bf16 v[102:105], v[200:203], v[160:163], v[102:105]
	v_mfma_f32_16x16x32_bf16 v[98:101], v[200:203], v[168:171], v[98:101]
	s_barrier
	v_readfirstlane_b32 s9, v138
	s_add_i32 s3, s2, 0xfff80000
	s_mov_b32 m0, s9
	v_readfirstlane_b32 s9, v139
	ds_read_b128 v[204:207], v134
	ds_read_b128 v[208:211], v134 offset:1024
	ds_read_b128 v[212:215], v134 offset:2048
	ds_read_b128 v[216:219], v134 offset:3072
	buffer_load_dwordx4 v136, s[4:7], s3 offen lds
	s_mov_b32 m0, s9
	s_nop 0
	buffer_load_dwordx4 v135, s[4:7], s3 offen lds
	s_barrier
	s_waitcnt lgkmcnt(0)
	s_waitcnt lgkmcnt(3)
	v_mfma_f32_16x16x32_bf16 v[94:97], v[172:175], v[204:207], v[94:97]
	s_waitcnt lgkmcnt(1)
	v_mfma_f32_16x16x32_bf16 v[90:93], v[172:175], v[212:215], v[90:93]
	v_mfma_f32_16x16x32_bf16 v[86:89], v[180:183], v[204:207], v[86:89]
	v_mfma_f32_16x16x32_bf16 v[82:85], v[180:183], v[212:215], v[82:85]
	v_mfma_f32_16x16x32_bf16 v[78:81], v[188:191], v[204:207], v[78:81]
	v_mfma_f32_16x16x32_bf16 v[74:77], v[188:191], v[212:215], v[74:77]
	v_mfma_f32_16x16x32_bf16 v[70:73], v[196:199], v[204:207], v[70:73]
	v_mfma_f32_16x16x32_bf16 v[66:69], v[196:199], v[212:215], v[66:69]
	v_mfma_f32_16x16x32_bf16 v[94:97], v[176:179], v[208:211], v[94:97]
	s_waitcnt lgkmcnt(0)
	v_mfma_f32_16x16x32_bf16 v[90:93], v[176:179], v[216:219], v[90:93]
	v_mfma_f32_16x16x32_bf16 v[86:89], v[184:187], v[208:211], v[86:89]
	v_mfma_f32_16x16x32_bf16 v[82:85], v[184:187], v[216:219], v[82:85]
	v_mfma_f32_16x16x32_bf16 v[78:81], v[192:195], v[208:211], v[78:81]
	v_mfma_f32_16x16x32_bf16 v[74:77], v[192:195], v[216:219], v[74:77]
	v_mfma_f32_16x16x32_bf16 v[70:73], v[200:203], v[208:211], v[70:73]
	v_mfma_f32_16x16x32_bf16 v[66:69], v[200:203], v[216:219], v[66:69]
	v_readfirstlane_b32 s9, v141
	s_mov_b32 m0, s9
	v_readfirstlane_b32 s9, v142
	s_barrier
	ds_read_b128 v[172:175], v133 offset:49152
	ds_read_b128 v[176:179], v133 offset:50176
	ds_read_b128 v[180:183], v132 offset:49152
	ds_read_b128 v[184:187], v132 offset:50176
	ds_read_b128 v[188:191], v131 offset:49152
	ds_read_b128 v[192:195], v131 offset:50176
	ds_read_b128 v[196:199], v130 offset:49152
	ds_read_b128 v[200:203], v130 offset:50176
	buffer_load_dwordx4 v136, s[88:91], s3 offen lds
	s_mov_b32 m0, s9
	s_nop 0
	buffer_load_dwordx4 v135, s[88:91], s3 offen lds
	s_barrier
; #define WAIT_V(n) asm volatile("s_waitcnt vmcnt(" #n ")" ::: "memory")
; #define WAIT_L(n) asm volatile("s_waitcnt lgkmcnt(" #n ")" ::: "memory")
; #define BAR __builtin_amdgcn_s_barrier()
; #define SCHED __builtin_amdgcn_sched_barrier(0)
; __device__ __forceinline__ void mainloop_8phase(const u16* __restrict__ A, const u16* __restrict__ Bt, int K,
;                                                 f32x4 (&acc)[2][2][4][2], int wid_s, int ld) {
;     ...
;     BAR; WAIT_L(0); MMA(1, 0, At, B0); BAR; SCHED;
;     STAGE(SB(1, 1), Bt, bcol + G_HALF, t + 3);
;     WAIT_V(6); BAR; MMA(1, 1, At, B1); BAR;
;   }
;   { LDB(B0, 0, 0); LDA(At, 0, 0); STAGE(SA(1, 1), A, brow + G_HALF, nt - 1);
;     BAR; WAIT_L(0); MMA(0, 0, At, B0); BAR;
;     LDB(B1, 0, 1); BAR; WAIT_L(0); MMA(0, 1, At, B1); BAR;
	s_waitcnt lgkmcnt(0)
	s_waitcnt lgkmcnt(7)
	v_mfma_f32_16x16x32_bf16 v[62:65], v[172:175], v[156:159], v[62:65]
	v_mfma_f32_16x16x32_bf16 v[58:61], v[172:175], v[164:167], v[58:61]
	s_waitcnt lgkmcnt(5)
	v_mfma_f32_16x16x32_bf16 v[54:57], v[180:183], v[156:159], v[54:57]
	v_mfma_f32_16x16x32_bf16 v[50:53], v[180:183], v[164:167], v[50:53]
	s_waitcnt lgkmcnt(3)
	v_mfma_f32_16x16x32_bf16 v[46:49], v[188:191], v[156:159], v[46:49]
	v_mfma_f32_16x16x32_bf16 v[42:45], v[188:191], v[164:167], v[42:45]
	s_waitcnt lgkmcnt(1)
	v_mfma_f32_16x16x32_bf16 v[38:41], v[196:199], v[156:159], v[38:41]
	v_mfma_f32_16x16x32_bf16 v[34:37], v[196:199], v[164:167], v[34:37]
	v_mfma_f32_16x16x32_bf16 v[62:65], v[176:179], v[160:163], v[62:65]
	v_mfma_f32_16x16x32_bf16 v[58:61], v[176:179], v[168:171], v[58:61]
	v_mfma_f32_16x16x32_bf16 v[54:57], v[184:187], v[160:163], v[54:57]
	v_mfma_f32_16x16x32_bf16 v[50:53], v[184:187], v[168:171], v[50:53]
	v_mfma_f32_16x16x32_bf16 v[46:49], v[192:195], v[160:163], v[46:49]
	v_mfma_f32_16x16x32_bf16 v[42:45], v[192:195], v[168:171], v[42:45]
	s_waitcnt lgkmcnt(0)
	v_mfma_f32_16x16x32_bf16 v[38:41], v[200:203], v[160:163], v[38:41]
	v_mfma_f32_16x16x32_bf16 v[34:37], v[200:203], v[168:171], v[34:37]
	s_barrier
	v_readfirstlane_b32 s3, v143
	s_mov_b32 m0, s3
	v_readfirstlane_b32 s3, v146
	buffer_load_dwordx4 v136, s[4:7], s2 offen lds
	s_mov_b32 m0, s3
	s_nop 0
	buffer_load_dwordx4 v135, s[4:7], s2 offen lds
	s_waitcnt vmcnt(6)
	s_barrier
	v_mfma_f32_16x16x32_bf16 v[30:33], v[172:175], v[204:207], v[30:33]
	v_mfma_f32_16x16x32_bf16 v[26:29], v[172:175], v[212:215], v[26:29]
	v_mfma_f32_16x16x32_bf16 v[22:25], v[180:183], v[204:207], v[22:25]
	v_mfma_f32_16x16x32_bf16 v[18:21], v[180:183], v[212:215], v[18:21]
	v_mfma_f32_16x16x32_bf16 v[14:17], v[188:191], v[204:207], v[14:17]
	v_mfma_f32_16x16x32_bf16 v[10:13], v[188:191], v[212:215], v[10:13]
	v_mfma_f32_16x16x32_bf16 v[6:9], v[196:199], v[204:207], v[6:9]
	v_mfma_f32_16x16x32_bf16 v[2:5], v[196:199], v[212:215], v[2:5]
	v_mfma_f32_16x16x32_bf16 v[30:33], v[176:179], v[208:211], v[30:33]
	v_mfma_f32_16x16x32_bf16 v[26:29], v[176:179], v[216:219], v[26:29]
	v_mfma_f32_16x16x32_bf16 v[22:25], v[184:187], v[208:211], v[22:25]
	v_mfma_f32_16x16x32_bf16 v[18:21], v[184:187], v[216:219], v[18:21]
	v_mfma_f32_16x16x32_bf16 v[14:17], v[192:195], v[208:211], v[14:17]
	v_mfma_f32_16x16x32_bf16 v[10:13], v[192:195], v[216:219], v[10:13]
	v_mfma_f32_16x16x32_bf16 v[6:9], v[200:203], v[208:211], v[6:9]
	v_mfma_f32_16x16x32_bf16 v[2:5], v[200:203], v[216:219], v[2:5]
	s_add_i32 s1, s1, 2
	s_addk_i32 s2, 0x100
	s_cmp_lt_u32 s1, 28
	s_barrier
	s_cbranch_scc1 .LBB0_342
	v_readfirstlane_b32 s1, v145
	s_mov_b32 m0, s1
	s_mov_b32 s2, 0x80f80
	v_readfirstlane_b32 s1, v144
	ds_read_b128 v[138:141], v155
	ds_read_b128 v[148:151], v155 offset:1024
	ds_read_b128 v[156:159], v155 offset:2048
	ds_read_b128 v[152:155], v155 offset:3072
	ds_read_b128 v[160:163], v133
	ds_read_b128 v[164:167], v133 offset:1024
	ds_read_b128 v[168:171], v132
	ds_read_b128 v[172:175], v132 offset:1024
	ds_read_b128 v[176:179], v131
	ds_read_b128 v[180:183], v131 offset:1024
	ds_read_b128 v[184:187], v130
	ds_read_b128 v[188:191], v130 offset:1024
	buffer_load_dwordx4 v136, s[88:91], s2 offen lds
	s_mov_b32 m0, s1
	s_nop 0
	buffer_load_dwordx4 v135, s[88:91], s2 offen lds
	s_barrier
	s_waitcnt lgkmcnt(0)
	s_waitcnt lgkmcnt(7)
	v_mfma_f32_16x16x32_bf16 v[126:129], v[160:163], v[138:141], v[126:129]
	s_waitcnt lgkmcnt(5)
	v_mfma_f32_16x16x32_bf16 v[118:121], v[168:171], v[138:141], v[118:121]
	s_waitcnt lgkmcnt(3)
	v_mfma_f32_16x16x32_bf16 v[110:113], v[176:179], v[138:141], v[110:113]
	s_waitcnt lgkmcnt(1)
	v_mfma_f32_16x16x32_bf16 v[102:105], v[184:187], v[138:141], v[102:105]
	v_mfma_f32_16x16x32_bf16 v[126:129], v[164:167], v[148:151], v[126:129]
	v_mfma_f32_16x16x32_bf16 v[122:125], v[160:163], v[156:159], v[122:125]
	v_mfma_f32_16x16x32_bf16 v[118:121], v[172:175], v[148:151], v[118:121]
	v_mfma_f32_16x16x32_bf16 v[114:117], v[168:171], v[156:159], v[114:117]
	v_mfma_f32_16x16x32_bf16 v[110:113], v[180:183], v[148:151], v[110:113]
	v_mfma_f32_16x16x32_bf16 v[106:109], v[176:179], v[156:159], v[106:109]
	s_waitcnt lgkmcnt(0)
	v_mfma_f32_16x16x32_bf16 v[102:105], v[188:191], v[148:151], v[102:105]
	v_mfma_f32_16x16x32_bf16 v[98:101], v[184:187], v[156:159], v[98:101]
	v_mfma_f32_16x16x32_bf16 v[142:145], v[164:167], v[152:155], v[122:125]
	v_mfma_f32_16x16x32_bf16 v[192:195], v[172:175], v[152:155], v[114:117]
	v_mfma_f32_16x16x32_bf16 v[196:199], v[180:183], v[152:155], v[106:109]
	v_mfma_f32_16x16x32_bf16 v[200:203], v[188:191], v[152:155], v[98:101]
	s_barrier
	s_nop 1
	ds_read_b128 v[98:101], v147
	ds_read_b128 v[106:109], v147 offset:1024
	ds_read_b128 v[114:117], v147 offset:2048
	ds_read_b128 v[122:125], v147 offset:3072
	s_barrier
	s_waitcnt lgkmcnt(0)
	s_waitcnt lgkmcnt(3)
	v_mfma_f32_16x16x32_bf16 v[94:97], v[160:163], v[98:101], v[94:97]
	s_waitcnt lgkmcnt(1)
	v_mfma_f32_16x16x32_bf16 v[90:93], v[160:163], v[114:117], v[90:93]
	v_mfma_f32_16x16x32_bf16 v[86:89], v[168:171], v[98:101], v[86:89]
	v_mfma_f32_16x16x32_bf16 v[82:85], v[168:171], v[114:117], v[82:85]
	v_mfma_f32_16x16x32_bf16 v[78:81], v[176:179], v[98:101], v[78:81]
	v_mfma_f32_16x16x32_bf16 v[74:77], v[176:179], v[114:117], v[74:77]
	v_mfma_f32_16x16x32_bf16 v[70:73], v[184:187], v[98:101], v[70:73]
	v_mfma_f32_16x16x32_bf16 v[66:69], v[184:187], v[114:117], v[66:69]
	v_mfma_f32_16x16x32_bf16 v[94:97], v[164:167], v[106:109], v[94:97]
	s_waitcnt lgkmcnt(0)
	v_mfma_f32_16x16x32_bf16 v[90:93], v[164:167], v[122:125], v[90:93]
	v_mfma_f32_16x16x32_bf16 v[86:89], v[172:175], v[106:109], v[86:89]
	v_mfma_f32_16x16x32_bf16 v[82:85], v[172:175], v[122:125], v[82:85]
	v_mfma_f32_16x16x32_bf16 v[78:81], v[180:183], v[106:109], v[78:81]
	v_mfma_f32_16x16x32_bf16 v[74:77], v[180:183], v[122:125], v[74:77]
	v_mfma_f32_16x16x32_bf16 v[70:73], v[188:191], v[106:109], v[70:73]
	v_mfma_f32_16x16x32_bf16 v[66:69], v[188:191], v[122:125], v[66:69]
	s_barrier
; #define WAIT_V(n) asm volatile("s_waitcnt vmcnt(" #n ")" ::: "memory")
; #define WAIT_L(n) asm volatile("s_waitcnt lgkmcnt(" #n ")" ::: "memory")
; #define BAR __builtin_amdgcn_s_barrier()
; __device__ __forceinline__ void mainloop_8phase(const u16* __restrict__ A, const u16* __restrict__ Bt, int K,
;                                                 f32x4 (&acc)[2][2][4][2], int wid_s, int ld) {
;     ...
;     LDA(At, 0, 1); WAIT_V(4); BAR; WAIT_L(0); MMA(1, 0, At, B0); MMA(1, 1, At, B1); BAR; }
;   { LDB(B0, 1, 0); LDA(At, 1, 0); WAIT_V(2); BAR; WAIT_L(0); MMA(0, 0, At, B0); BAR;
	ds_read_b128 v[160:163], v133 offset:16384
	ds_read_b128 v[164:167], v133 offset:17408
	ds_read_b128 v[168:171], v132 offset:16384
	ds_read_b128 v[172:175], v132 offset:17408
	ds_read_b128 v[176:179], v131 offset:16384
	ds_read_b128 v[180:183], v131 offset:17408
	ds_read_b128 v[184:187], v130 offset:16384
	ds_read_b128 v[188:191], v130 offset:17408
	s_waitcnt vmcnt(4)
	s_barrier
	s_waitcnt lgkmcnt(0)
	s_waitcnt lgkmcnt(7)
	v_mfma_f32_16x16x32_bf16 v[62:65], v[160:163], v[138:141], v[62:65]
	v_mfma_f32_16x16x32_bf16 v[58:61], v[160:163], v[156:159], v[58:61]
	s_waitcnt lgkmcnt(5)
	v_mfma_f32_16x16x32_bf16 v[54:57], v[168:171], v[138:141], v[54:57]
	v_mfma_f32_16x16x32_bf16 v[50:53], v[168:171], v[156:159], v[50:53]
	s_waitcnt lgkmcnt(3)
	v_mfma_f32_16x16x32_bf16 v[46:49], v[176:179], v[138:141], v[46:49]
	v_mfma_f32_16x16x32_bf16 v[42:45], v[176:179], v[156:159], v[42:45]
	s_waitcnt lgkmcnt(1)
	v_mfma_f32_16x16x32_bf16 v[38:41], v[184:187], v[138:141], v[38:41]
	v_mfma_f32_16x16x32_bf16 v[34:37], v[184:187], v[156:159], v[34:37]
	v_mfma_f32_16x16x32_bf16 v[204:207], v[164:167], v[148:151], v[62:65]
	v_mfma_f32_16x16x32_bf16 v[208:211], v[164:167], v[152:155], v[58:61]
	v_mfma_f32_16x16x32_bf16 v[212:215], v[172:175], v[148:151], v[54:57]
	v_mfma_f32_16x16x32_bf16 v[216:219], v[172:175], v[152:155], v[50:53]
	v_mfma_f32_16x16x32_bf16 v[220:223], v[180:183], v[148:151], v[46:49]
	v_mfma_f32_16x16x32_bf16 v[224:227], v[180:183], v[152:155], v[42:45]
	s_waitcnt lgkmcnt(0)
	v_mfma_f32_16x16x32_bf16 v[138:141], v[188:191], v[148:151], v[38:41]
	v_mfma_f32_16x16x32_bf16 v[146:149], v[188:191], v[152:155], v[34:37]
	v_mfma_f32_16x16x32_bf16 v[30:33], v[160:163], v[98:101], v[30:33]
	v_mfma_f32_16x16x32_bf16 v[22:25], v[168:171], v[98:101], v[22:25]
	v_mfma_f32_16x16x32_bf16 v[14:17], v[176:179], v[98:101], v[14:17]
	v_mfma_f32_16x16x32_bf16 v[6:9], v[184:187], v[98:101], v[6:9]
	v_mfma_f32_16x16x32_bf16 v[30:33], v[164:167], v[106:109], v[30:33]
	v_mfma_f32_16x16x32_bf16 v[26:29], v[160:163], v[114:117], v[26:29]
	v_mfma_f32_16x16x32_bf16 v[22:25], v[172:175], v[106:109], v[22:25]
	v_mfma_f32_16x16x32_bf16 v[18:21], v[168:171], v[114:117], v[18:21]
	v_mfma_f32_16x16x32_bf16 v[14:17], v[180:183], v[106:109], v[14:17]
	v_mfma_f32_16x16x32_bf16 v[10:13], v[176:179], v[114:117], v[10:13]
	v_mfma_f32_16x16x32_bf16 v[6:9], v[188:191], v[106:109], v[6:9]
	v_mfma_f32_16x16x32_bf16 v[2:5], v[184:187], v[114:117], v[2:5]
	v_mfma_f32_16x16x32_bf16 v[150:153], v[164:167], v[122:125], v[26:29]
	v_mfma_f32_16x16x32_bf16 v[154:157], v[172:175], v[122:125], v[18:21]
	v_mfma_f32_16x16x32_bf16 v[158:161], v[180:183], v[122:125], v[10:13]
	v_mfma_f32_16x16x32_bf16 v[162:165], v[188:191], v[122:125], v[2:5]
	s_barrier
	s_nop 1
	ds_read_b128 v[2:5], v137
	ds_read_b128 v[166:169], v137 offset:1024
	ds_read_b128 v[170:173], v137 offset:2048
	ds_read_b128 v[174:177], v137 offset:3072
	ds_read_b128 v[10:13], v133 offset:32768
	ds_read_b128 v[18:21], v133 offset:33792
	ds_read_b128 v[26:29], v132 offset:32768
	ds_read_b128 v[38:41], v132 offset:33792
	ds_read_b128 v[46:49], v131 offset:32768
	ds_read_b128 v[178:181], v131 offset:33792
	ds_read_b128 v[182:185], v130 offset:32768
	ds_read_b128 v[186:189], v130 offset:33792
	s_waitcnt vmcnt(2)
	s_barrier
	s_waitcnt lgkmcnt(0)
	s_waitcnt lgkmcnt(7)
	v_mfma_f32_16x16x32_bf16 v[34:37], v[10:13], v[2:5], v[126:129]
	s_waitcnt lgkmcnt(6)
	v_mfma_f32_16x16x32_bf16 v[122:125], v[18:21], v[166:169], v[34:37]
	v_mfma_f32_16x16x32_bf16 v[34:37], v[10:13], v[170:173], v[142:145]
	v_mfma_f32_16x16x32_bf16 v[58:61], v[18:21], v[174:177], v[34:37]
	s_waitcnt lgkmcnt(5)
	v_mfma_f32_16x16x32_bf16 v[34:37], v[26:29], v[2:5], v[118:121]
	s_waitcnt lgkmcnt(4)
	v_mfma_f32_16x16x32_bf16 v[114:117], v[38:41], v[166:169], v[34:37]
	v_mfma_f32_16x16x32_bf16 v[34:37], v[26:29], v[170:173], v[192:195]
	v_mfma_f32_16x16x32_bf16 v[50:53], v[38:41], v[174:177], v[34:37]
	s_waitcnt lgkmcnt(3)
	v_mfma_f32_16x16x32_bf16 v[34:37], v[46:49], v[2:5], v[110:113]
	s_waitcnt lgkmcnt(2)
	v_mfma_f32_16x16x32_bf16 v[106:109], v[178:181], v[166:169], v[34:37]
	v_mfma_f32_16x16x32_bf16 v[34:37], v[46:49], v[170:173], v[196:199]
	v_mfma_f32_16x16x32_bf16 v[42:45], v[178:181], v[174:177], v[34:37]
	s_waitcnt lgkmcnt(1)
	v_mfma_f32_16x16x32_bf16 v[34:37], v[182:185], v[2:5], v[102:105]
	s_waitcnt lgkmcnt(0)
	v_mfma_f32_16x16x32_bf16 v[98:101], v[186:189], v[166:169], v[34:37]
	v_mfma_f32_16x16x32_bf16 v[34:37], v[182:185], v[170:173], v[200:203]
	v_mfma_f32_16x16x32_bf16 v[34:37], v[186:189], v[174:177], v[34:37]
	s_barrier
; #define WAIT_V(n) asm volatile("s_waitcnt vmcnt(" #n ")" ::: "memory")
; #define WAIT_L(n) asm volatile("s_waitcnt lgkmcnt(" #n ")" ::: "memory")
; #define BAR __builtin_amdgcn_s_barrier()
; __device__ __forceinline__ void mainloop_8phase(const u16* __restrict__ A, const u16* __restrict__ Bt, int K,
;                                                 f32x4 (&acc)[2][2][4][2], int wid_s, int ld) {
;     ...
;     LDB(B1, 1, 1); WAIT_V(0); BAR; WAIT_L(0); MMA(0, 1, At, B1); BAR;
;     LDA(At, 1, 1); BAR; WAIT_L(0); MMA(1, 0, At, B0); MMA(1, 1, At, B1); BAR; }
;   if (wr == 0) BAR;
	ds_read_b128 v[142:145], v134
	ds_read_b128 v[190:193], v134 offset:1024
	ds_read_b128 v[194:197], v134 offset:2048
	ds_read_b128 v[134:137], v134 offset:3072
	s_waitcnt vmcnt(0)
	s_barrier
	s_waitcnt lgkmcnt(0)
	s_waitcnt lgkmcnt(3)
	v_mfma_f32_16x16x32_bf16 v[54:57], v[10:13], v[142:145], v[94:97]
	s_waitcnt lgkmcnt(1)
	v_mfma_f32_16x16x32_bf16 v[10:13], v[10:13], v[194:197], v[90:93]
	s_waitcnt lgkmcnt(0)
	v_mfma_f32_16x16x32_bf16 v[62:65], v[18:21], v[134:137], v[10:13]
	v_mfma_f32_16x16x32_bf16 v[10:13], v[26:29], v[142:145], v[86:89]
	v_mfma_f32_16x16x32_bf16 v[118:121], v[38:41], v[190:193], v[10:13]
	v_mfma_f32_16x16x32_bf16 v[10:13], v[26:29], v[194:197], v[82:85]
	v_mfma_f32_16x16x32_bf16 v[126:129], v[18:21], v[190:193], v[54:57]
	v_mfma_f32_16x16x32_bf16 v[54:57], v[38:41], v[134:137], v[10:13]
	v_mfma_f32_16x16x32_bf16 v[10:13], v[46:49], v[142:145], v[78:81]
	v_mfma_f32_16x16x32_bf16 v[110:113], v[178:181], v[190:193], v[10:13]
	v_mfma_f32_16x16x32_bf16 v[10:13], v[46:49], v[194:197], v[74:77]
	v_mfma_f32_16x16x32_bf16 v[46:49], v[178:181], v[134:137], v[10:13]
	v_mfma_f32_16x16x32_bf16 v[10:13], v[182:185], v[142:145], v[70:73]
	v_mfma_f32_16x16x32_bf16 v[102:105], v[186:189], v[190:193], v[10:13]
	v_mfma_f32_16x16x32_bf16 v[10:13], v[182:185], v[194:197], v[66:69]
	v_mfma_f32_16x16x32_bf16 v[38:41], v[186:189], v[134:137], v[10:13]
	s_barrier
	ds_read_b128 v[66:69], v133 offset:49152
	ds_read_b128 v[78:81], v133 offset:50176
	ds_read_b128 v[178:181], v132 offset:49152
	ds_read_b128 v[182:185], v132 offset:50176
	ds_read_b128 v[186:189], v131 offset:49152
	ds_read_b128 v[198:201], v131 offset:50176
	ds_read_b128 v[228:231], v130 offset:49152
	ds_read_b128 v[130:133], v130 offset:50176
	s_barrier
	s_waitcnt lgkmcnt(0)
	s_waitcnt lgkmcnt(7)
	v_mfma_f32_16x16x32_bf16 v[10:13], v[66:69], v[2:5], v[204:207]
	s_waitcnt lgkmcnt(6)
	v_mfma_f32_16x16x32_bf16 v[90:93], v[78:81], v[166:169], v[10:13]
	v_mfma_f32_16x16x32_bf16 v[10:13], v[66:69], v[170:173], v[208:211]
	v_mfma_f32_16x16x32_bf16 v[26:29], v[78:81], v[174:177], v[10:13]
	s_waitcnt lgkmcnt(5)
	v_mfma_f32_16x16x32_bf16 v[10:13], v[178:181], v[2:5], v[212:215]
	s_waitcnt lgkmcnt(4)
	v_mfma_f32_16x16x32_bf16 v[82:85], v[182:185], v[166:169], v[10:13]
	v_mfma_f32_16x16x32_bf16 v[10:13], v[178:181], v[170:173], v[216:219]
	v_mfma_f32_16x16x32_bf16 v[18:21], v[182:185], v[174:177], v[10:13]
	s_waitcnt lgkmcnt(3)
	v_mfma_f32_16x16x32_bf16 v[10:13], v[186:189], v[2:5], v[220:223]
	s_waitcnt lgkmcnt(1)
	v_mfma_f32_16x16x32_bf16 v[2:5], v[228:231], v[2:5], v[138:141]
	v_mfma_f32_16x16x32_bf16 v[74:77], v[198:201], v[166:169], v[10:13]
	v_mfma_f32_16x16x32_bf16 v[10:13], v[186:189], v[170:173], v[224:227]
	s_waitcnt lgkmcnt(0)
	v_mfma_f32_16x16x32_bf16 v[70:73], v[130:133], v[166:169], v[2:5]
	v_mfma_f32_16x16x32_bf16 v[2:5], v[228:231], v[170:173], v[146:149]
	v_mfma_f32_16x16x32_bf16 v[10:13], v[198:201], v[174:177], v[10:13]
	v_mfma_f32_16x16x32_bf16 v[2:5], v[130:133], v[174:177], v[2:5]
	v_mfma_f32_16x16x32_bf16 v[30:33], v[66:69], v[142:145], v[30:33]
	v_mfma_f32_16x16x32_bf16 v[94:97], v[78:81], v[190:193], v[30:33]
	v_mfma_f32_16x16x32_bf16 v[30:33], v[66:69], v[194:197], v[150:153]
	v_mfma_f32_16x16x32_bf16 v[22:25], v[178:181], v[142:145], v[22:25]
	v_mfma_f32_16x16x32_bf16 v[14:17], v[186:189], v[142:145], v[14:17]
	v_mfma_f32_16x16x32_bf16 v[6:9], v[228:231], v[142:145], v[6:9]
	v_mfma_f32_16x16x32_bf16 v[30:33], v[78:81], v[134:137], v[30:33]
	v_mfma_f32_16x16x32_bf16 v[86:89], v[182:185], v[190:193], v[22:25]
	v_mfma_f32_16x16x32_bf16 v[22:25], v[178:181], v[194:197], v[154:157]
	v_mfma_f32_16x16x32_bf16 v[78:81], v[198:201], v[190:193], v[14:17]
	v_mfma_f32_16x16x32_bf16 v[14:17], v[186:189], v[194:197], v[158:161]
	v_mfma_f32_16x16x32_bf16 v[66:69], v[130:133], v[190:193], v[6:9]
	v_mfma_f32_16x16x32_bf16 v[6:9], v[228:231], v[194:197], v[162:165]
	v_mfma_f32_16x16x32_bf16 v[22:25], v[182:185], v[134:137], v[22:25]
	v_mfma_f32_16x16x32_bf16 v[14:17], v[198:201], v[134:137], v[14:17]
	v_mfma_f32_16x16x32_bf16 v[6:9], v[130:133], v[134:137], v[6:9]
	s_movk_i32 s1, 0x100
	v_cmp_gt_u32_e32 vcc, s1, v0
	s_barrier
	s_and_saveexec_b64 s[2:3], vcc
	s_cbranch_execz .LBB0_345
	s_barrier

; #define WAIT_L(n) asm volatile("s_waitcnt lgkmcnt(" #n ")" ::: "memory")
; #define BAR __builtin_amdgcn_s_barrier()
; #define SCHED __builtin_amdgcn_sched_barrier(0)
; __device__ __forceinline__ void mainloop_8phase(const u16* __restrict__ A, const u16* __restrict__ Bt, int K,
;                                                 f32x4 (&acc)[2][2][4][2], int wid_s, int ld) {
;     ...
;     LDB(B0, 0, 0); SCHED; LDA(At, 0, 0); STAGE(SA(1, 1), A, brow + G_HALF, t + 1);
;     WAIT_L(8); BAR; WAIT_L(0); MMA(0, 0, At, B0); BAR; SCHED;
;     LDB(B1, 0, 1); STAGE(SB(0, 0), Bt, bcol, t + 2);
;     BAR; WAIT_L(0); MMA(0, 1, At, B1); BAR;
;     LDA(At, 0, 1); STAGE(SA(0, 0), A, brow, t + 2);
;     BAR; WAIT_L(0); MMA(1, 0, At, B0); BAR; SCHED;
.LBB0_565:
	ds_read_b128 v[158:161], v156
	ds_read_b128 v[162:165], v156 offset:1024
	ds_read_b128 v[166:169], v156 offset:2048
	ds_read_b128 v[170:173], v156 offset:3072
	s_add_i32 s15, s27, s3
	v_readfirstlane_b32 s7, v146
	s_add_i32 s6, s15, 0x80
	s_mov_b32 m0, s7
	v_readfirstlane_b32 s7, v145
	ds_read_b128 v[174:177], v134
	ds_read_b128 v[178:181], v134 offset:1024
	ds_read_b128 v[182:185], v133
	ds_read_b128 v[186:189], v133 offset:1024
	ds_read_b128 v[190:193], v132
	ds_read_b128 v[194:197], v132 offset:1024
	ds_read_b128 v[198:201], v131
	ds_read_b128 v[202:205], v131 offset:1024
	buffer_load_dwordx4 v137, s[76:79], s6 offen lds
	s_mov_b32 m0, s7
	s_nop 0
	buffer_load_dwordx4 v138, s[76:79], s6 offen lds
	s_waitcnt lgkmcnt(8)
	s_barrier
	s_waitcnt lgkmcnt(0)
	s_waitcnt lgkmcnt(7)
	v_mfma_f32_16x16x32_bf16 v[126:129], v[174:177], v[158:161], v[126:129]
	v_mfma_f32_16x16x32_bf16 v[122:125], v[174:177], v[166:169], v[122:125]
	s_waitcnt lgkmcnt(5)
	v_mfma_f32_16x16x32_bf16 v[118:121], v[182:185], v[158:161], v[118:121]
	v_mfma_f32_16x16x32_bf16 v[114:117], v[182:185], v[166:169], v[114:117]
	s_waitcnt lgkmcnt(3)
	v_mfma_f32_16x16x32_bf16 v[110:113], v[190:193], v[158:161], v[110:113]
	v_mfma_f32_16x16x32_bf16 v[106:109], v[190:193], v[166:169], v[106:109]
	s_waitcnt lgkmcnt(1)
	v_mfma_f32_16x16x32_bf16 v[102:105], v[198:201], v[158:161], v[102:105]
	v_mfma_f32_16x16x32_bf16 v[98:101], v[198:201], v[166:169], v[98:101]
	v_mfma_f32_16x16x32_bf16 v[126:129], v[178:181], v[162:165], v[126:129]
	v_mfma_f32_16x16x32_bf16 v[122:125], v[178:181], v[170:173], v[122:125]
	v_mfma_f32_16x16x32_bf16 v[118:121], v[186:189], v[162:165], v[118:121]
	v_mfma_f32_16x16x32_bf16 v[114:117], v[186:189], v[170:173], v[114:117]
	v_mfma_f32_16x16x32_bf16 v[110:113], v[194:197], v[162:165], v[110:113]
	v_mfma_f32_16x16x32_bf16 v[106:109], v[194:197], v[170:173], v[106:109]
	s_waitcnt lgkmcnt(0)
	v_mfma_f32_16x16x32_bf16 v[102:105], v[202:205], v[162:165], v[102:105]
	v_mfma_f32_16x16x32_bf16 v[98:101], v[202:205], v[170:173], v[98:101]
	s_barrier
	v_readfirstlane_b32 s34, v149
	s_add_i32 s14, s3, 0x100
	s_mov_b32 s6, s78
	s_mov_b32 s7, s79
	s_mov_b32 m0, s34
	v_readfirstlane_b32 s34, v150
	ds_read_b128 v[206:209], v148
	ds_read_b128 v[210:213], v148 offset:1024
	ds_read_b128 v[214:217], v148 offset:2048
	ds_read_b128 v[218:221], v148 offset:3072
	buffer_load_dwordx4 v137, s[4:7], s14 offen lds
	s_mov_b32 m0, s34
	s_add_i32 s2, s2, 2
	buffer_load_dwordx4 v138, s[4:7], s14 offen lds
	s_barrier
	s_waitcnt lgkmcnt(0)
	s_waitcnt lgkmcnt(3)
	v_mfma_f32_16x16x32_bf16 v[94:97], v[174:177], v[206:209], v[94:97]
	s_waitcnt lgkmcnt(1)
	v_mfma_f32_16x16x32_bf16 v[90:93], v[174:177], v[214:217], v[90:93]
	v_mfma_f32_16x16x32_bf16 v[86:89], v[182:185], v[206:209], v[86:89]
	v_mfma_f32_16x16x32_bf16 v[82:85], v[182:185], v[214:217], v[82:85]
	v_mfma_f32_16x16x32_bf16 v[78:81], v[190:193], v[206:209], v[78:81]
	v_mfma_f32_16x16x32_bf16 v[74:77], v[190:193], v[214:217], v[74:77]
	v_mfma_f32_16x16x32_bf16 v[70:73], v[198:201], v[206:209], v[70:73]
	v_mfma_f32_16x16x32_bf16 v[66:69], v[198:201], v[214:217], v[66:69]
	v_mfma_f32_16x16x32_bf16 v[94:97], v[178:181], v[210:213], v[94:97]
	s_waitcnt lgkmcnt(0)
	v_mfma_f32_16x16x32_bf16 v[90:93], v[178:181], v[218:221], v[90:93]
	v_mfma_f32_16x16x32_bf16 v[86:89], v[186:189], v[210:213], v[86:89]
	v_mfma_f32_16x16x32_bf16 v[82:85], v[186:189], v[218:221], v[82:85]
	v_mfma_f32_16x16x32_bf16 v[78:81], v[194:197], v[210:213], v[78:81]
	v_mfma_f32_16x16x32_bf16 v[74:77], v[194:197], v[218:221], v[74:77]
	v_mfma_f32_16x16x32_bf16 v[70:73], v[202:205], v[210:213], v[70:73]
	v_mfma_f32_16x16x32_bf16 v[66:69], v[202:205], v[218:221], v[66:69]
	v_readfirstlane_b32 s34, v141
	s_mov_b32 m0, s34
	v_readfirstlane_b32 s34, v151
	s_barrier
	ds_read_b128 v[174:177], v134 offset:16384
	ds_read_b128 v[178:181], v134 offset:17408
	ds_read_b128 v[182:185], v133 offset:16384
	ds_read_b128 v[186:189], v133 offset:17408
	ds_read_b128 v[190:193], v132 offset:16384
	ds_read_b128 v[194:197], v132 offset:17408
	ds_read_b128 v[198:201], v131 offset:16384
	ds_read_b128 v[202:205], v131 offset:17408
	buffer_load_dwordx4 v137, s[76:79], s14 offen lds
	s_mov_b32 m0, s34
	s_nop 0
	buffer_load_dwordx4 v138, s[76:79], s14 offen lds
	s_barrier
	s_waitcnt lgkmcnt(0)
	s_waitcnt lgkmcnt(7)
	v_mfma_f32_16x16x32_bf16 v[62:65], v[174:177], v[158:161], v[62:65]
	v_mfma_f32_16x16x32_bf16 v[58:61], v[174:177], v[166:169], v[58:61]
	s_waitcnt lgkmcnt(5)
	v_mfma_f32_16x16x32_bf16 v[54:57], v[182:185], v[158:161], v[54:57]
	v_mfma_f32_16x16x32_bf16 v[50:53], v[182:185], v[166:169], v[50:53]
	s_waitcnt lgkmcnt(3)
	v_mfma_f32_16x16x32_bf16 v[46:49], v[190:193], v[158:161], v[46:49]
	v_mfma_f32_16x16x32_bf16 v[42:45], v[190:193], v[166:169], v[42:45]
	s_waitcnt lgkmcnt(1)
	v_mfma_f32_16x16x32_bf16 v[38:41], v[198:201], v[158:161], v[38:41]
	v_mfma_f32_16x16x32_bf16 v[34:37], v[198:201], v[166:169], v[34:37]
	v_mfma_f32_16x16x32_bf16 v[62:65], v[178:181], v[162:165], v[62:65]
	v_mfma_f32_16x16x32_bf16 v[58:61], v[178:181], v[170:173], v[58:61]
	v_mfma_f32_16x16x32_bf16 v[54:57], v[186:189], v[162:165], v[54:57]
	v_mfma_f32_16x16x32_bf16 v[50:53], v[186:189], v[170:173], v[50:53]
	v_mfma_f32_16x16x32_bf16 v[46:49], v[194:197], v[162:165], v[46:49]
	v_mfma_f32_16x16x32_bf16 v[42:45], v[194:197], v[170:173], v[42:45]
	s_waitcnt lgkmcnt(0)
	v_mfma_f32_16x16x32_bf16 v[38:41], v[202:205], v[162:165], v[38:41]
	v_mfma_f32_16x16x32_bf16 v[34:37], v[202:205], v[170:173], v[34:37]
	s_barrier
; #define WAIT_V(n) asm volatile("s_waitcnt vmcnt(" #n ")" ::: "memory")
; #define WAIT_L(n) asm volatile("s_waitcnt lgkmcnt(" #n ")" ::: "memory")
; #define BAR __builtin_amdgcn_s_barrier()
; #define SCHED __builtin_amdgcn_sched_barrier(0)
; __device__ __forceinline__ void mainloop_8phase(const u16* __restrict__ A, const u16* __restrict__ Bt, int K,
;                                                 f32x4 (&acc)[2][2][4][2], int wid_s, int ld) {
;     ...
;     STAGE(SB(0, 1), Bt, bcol + G_HALF, t + 2);
;     WAIT_V(6); BAR; MMA(1, 1, At, B1); BAR;
;     LDB(B0, 1, 0); SCHED; LDA(At, 1, 0); STAGE(SA(0, 1), A, brow + G_HALF, t + 2);
;     WAIT_L(8); BAR; WAIT_L(0); MMA(0, 0, At, B0); BAR; SCHED;
;     LDB(B1, 1, 1); STAGE(SB(1, 0), Bt, bcol, t + 3);
;     BAR; WAIT_L(0); MMA(0, 1, At, B1); BAR;
;     LDA(At, 1, 1); STAGE(SA(1, 0), A, brow, t + 3);
	v_readfirstlane_b32 s35, v152
	s_add_i32 s34, s15, 0x100
	s_mov_b32 m0, s35
	v_readfirstlane_b32 s35, v153
	buffer_load_dwordx4 v137, s[4:7], s34 offen lds
	s_mov_b32 m0, s35
	s_nop 0
	buffer_load_dwordx4 v138, s[4:7], s34 offen lds
	s_waitcnt vmcnt(6)
	s_barrier
	v_mfma_f32_16x16x32_bf16 v[30:33], v[174:177], v[206:209], v[30:33]
	v_mfma_f32_16x16x32_bf16 v[26:29], v[174:177], v[214:217], v[26:29]
	v_mfma_f32_16x16x32_bf16 v[22:25], v[182:185], v[206:209], v[22:25]
	v_mfma_f32_16x16x32_bf16 v[18:21], v[182:185], v[214:217], v[18:21]
	v_mfma_f32_16x16x32_bf16 v[14:17], v[190:193], v[206:209], v[14:17]
	v_mfma_f32_16x16x32_bf16 v[10:13], v[190:193], v[214:217], v[10:13]
	v_mfma_f32_16x16x32_bf16 v[6:9], v[198:201], v[206:209], v[6:9]
	v_mfma_f32_16x16x32_bf16 v[2:5], v[198:201], v[214:217], v[2:5]
	v_mfma_f32_16x16x32_bf16 v[30:33], v[178:181], v[210:213], v[30:33]
	v_mfma_f32_16x16x32_bf16 v[26:29], v[178:181], v[218:221], v[26:29]
	v_mfma_f32_16x16x32_bf16 v[22:25], v[186:189], v[210:213], v[22:25]
	v_mfma_f32_16x16x32_bf16 v[18:21], v[186:189], v[218:221], v[18:21]
	v_mfma_f32_16x16x32_bf16 v[14:17], v[194:197], v[210:213], v[14:17]
	v_mfma_f32_16x16x32_bf16 v[10:13], v[194:197], v[218:221], v[10:13]
	v_mfma_f32_16x16x32_bf16 v[6:9], v[202:205], v[210:213], v[6:9]
	v_mfma_f32_16x16x32_bf16 v[2:5], v[202:205], v[218:221], v[2:5]
	s_barrier
	ds_read_b128 v[158:161], v136
	ds_read_b128 v[162:165], v136 offset:1024
	ds_read_b128 v[166:169], v136 offset:2048
	ds_read_b128 v[170:173], v136 offset:3072
	v_readfirstlane_b32 s35, v154
	s_mov_b32 m0, s35
	v_readfirstlane_b32 s35, v155
	ds_read_b128 v[174:177], v134 offset:32768
	ds_read_b128 v[178:181], v134 offset:33792
	ds_read_b128 v[182:185], v133 offset:32768
	ds_read_b128 v[186:189], v133 offset:33792
	ds_read_b128 v[190:193], v132 offset:32768
	ds_read_b128 v[194:197], v132 offset:33792
	ds_read_b128 v[198:201], v131 offset:32768
	ds_read_b128 v[202:205], v131 offset:33792
	buffer_load_dwordx4 v137, s[76:79], s34 offen lds
	s_mov_b32 m0, s35
	s_nop 0
	buffer_load_dwordx4 v138, s[76:79], s34 offen lds
	s_waitcnt lgkmcnt(8)
	s_barrier
	s_waitcnt lgkmcnt(0)
	s_waitcnt lgkmcnt(7)
	v_mfma_f32_16x16x32_bf16 v[126:129], v[174:177], v[158:161], v[126:129]
	v_mfma_f32_16x16x32_bf16 v[122:125], v[174:177], v[166:169], v[122:125]
	s_waitcnt lgkmcnt(5)
	v_mfma_f32_16x16x32_bf16 v[118:121], v[182:185], v[158:161], v[118:121]
	v_mfma_f32_16x16x32_bf16 v[114:117], v[182:185], v[166:169], v[114:117]
	s_waitcnt lgkmcnt(3)
	v_mfma_f32_16x16x32_bf16 v[110:113], v[190:193], v[158:161], v[110:113]
	v_mfma_f32_16x16x32_bf16 v[106:109], v[190:193], v[166:169], v[106:109]
	s_waitcnt lgkmcnt(1)
	v_mfma_f32_16x16x32_bf16 v[102:105], v[198:201], v[158:161], v[102:105]
	v_mfma_f32_16x16x32_bf16 v[98:101], v[198:201], v[166:169], v[98:101]
	v_mfma_f32_16x16x32_bf16 v[126:129], v[178:181], v[162:165], v[126:129]
	v_mfma_f32_16x16x32_bf16 v[122:125], v[178:181], v[170:173], v[122:125]
	v_mfma_f32_16x16x32_bf16 v[118:121], v[186:189], v[162:165], v[118:121]
	v_mfma_f32_16x16x32_bf16 v[114:117], v[186:189], v[170:173], v[114:117]
	v_mfma_f32_16x16x32_bf16 v[110:113], v[194:197], v[162:165], v[110:113]
	v_mfma_f32_16x16x32_bf16 v[106:109], v[194:197], v[170:173], v[106:109]
	s_waitcnt lgkmcnt(0)
	v_mfma_f32_16x16x32_bf16 v[102:105], v[202:205], v[162:165], v[102:105]
	v_mfma_f32_16x16x32_bf16 v[98:101], v[202:205], v[170:173], v[98:101]
	s_barrier
	v_readfirstlane_b32 s34, v139
	s_addk_i32 s3, 0x180
	s_mov_b32 m0, s34
	v_readfirstlane_b32 s34, v140
	ds_read_b128 v[206:209], v135
	ds_read_b128 v[210:213], v135 offset:1024
	ds_read_b128 v[214:217], v135 offset:2048
	ds_read_b128 v[218:221], v135 offset:3072
	buffer_load_dwordx4 v137, s[4:7], s3 offen lds
	s_mov_b32 m0, s34
	s_nop 0
	buffer_load_dwordx4 v138, s[4:7], s3 offen lds
	s_barrier
	s_waitcnt lgkmcnt(0)
	s_waitcnt lgkmcnt(3)
	v_mfma_f32_16x16x32_bf16 v[94:97], v[174:177], v[206:209], v[94:97]
	s_waitcnt lgkmcnt(1)
	v_mfma_f32_16x16x32_bf16 v[90:93], v[174:177], v[214:217], v[90:93]
	v_mfma_f32_16x16x32_bf16 v[86:89], v[182:185], v[206:209], v[86:89]
	v_mfma_f32_16x16x32_bf16 v[82:85], v[182:185], v[214:217], v[82:85]
	v_mfma_f32_16x16x32_bf16 v[78:81], v[190:193], v[206:209], v[78:81]
	v_mfma_f32_16x16x32_bf16 v[74:77], v[190:193], v[214:217], v[74:77]
	v_mfma_f32_16x16x32_bf16 v[70:73], v[198:201], v[206:209], v[70:73]
	v_mfma_f32_16x16x32_bf16 v[66:69], v[198:201], v[214:217], v[66:69]
	v_mfma_f32_16x16x32_bf16 v[94:97], v[178:181], v[210:213], v[94:97]
	s_waitcnt lgkmcnt(0)
	v_mfma_f32_16x16x32_bf16 v[90:93], v[178:181], v[218:221], v[90:93]
	v_mfma_f32_16x16x32_bf16 v[86:89], v[186:189], v[210:213], v[86:89]
	v_mfma_f32_16x16x32_bf16 v[82:85], v[186:189], v[218:221], v[82:85]
	v_mfma_f32_16x16x32_bf16 v[78:81], v[194:197], v[210:213], v[78:81]
	v_mfma_f32_16x16x32_bf16 v[74:77], v[194:197], v[218:221], v[74:77]
	v_mfma_f32_16x16x32_bf16 v[70:73], v[202:205], v[210:213], v[70:73]
	v_mfma_f32_16x16x32_bf16 v[66:69], v[202:205], v[218:221], v[66:69]
	v_readfirstlane_b32 s34, v142
	s_mov_b32 m0, s34
	v_readfirstlane_b32 s34, v143
	s_barrier
	ds_read_b128 v[174:177], v134 offset:49152
	ds_read_b128 v[178:181], v134 offset:50176
	ds_read_b128 v[182:185], v133 offset:49152
	ds_read_b128 v[186:189], v133 offset:50176
	ds_read_b128 v[190:193], v132 offset:49152
	ds_read_b128 v[194:197], v132 offset:50176
	ds_read_b128 v[198:201], v131 offset:49152
	ds_read_b128 v[202:205], v131 offset:50176
	buffer_load_dwordx4 v137, s[76:79], s3 offen lds
	s_mov_b32 m0, s34
	s_nop 0
	buffer_load_dwordx4 v138, s[76:79], s3 offen lds
	s_barrier
; #define WAIT_V(n) asm volatile("s_waitcnt vmcnt(" #n ")" ::: "memory")
; #define WAIT_L(n) asm volatile("s_waitcnt lgkmcnt(" #n ")" ::: "memory")
; #define BAR __builtin_amdgcn_s_barrier()
; #define SCHED __builtin_amdgcn_sched_barrier(0)
; __device__ __forceinline__ void mainloop_8phase(const u16* __restrict__ A, const u16* __restrict__ Bt, int K,
;                                                 f32x4 (&acc)[2][2][4][2], int wid_s, int ld) {
;     ...
;     BAR; WAIT_L(0); MMA(1, 0, At, B0); BAR; SCHED;
;     STAGE(SB(1, 1), Bt, bcol + G_HALF, t + 3);
;     WAIT_V(6); BAR; MMA(1, 1, At, B1); BAR;
;   }
;   { LDB(B0, 0, 0); LDA(At, 0, 0); STAGE(SA(1, 1), A, brow + G_HALF, nt - 1);
;     BAR; WAIT_L(0); MMA(0, 0, At, B0); BAR;
;     LDB(B1, 0, 1); BAR; WAIT_L(0); MMA(0, 1, At, B1); BAR;
	s_waitcnt lgkmcnt(0)
	s_waitcnt lgkmcnt(7)
	v_mfma_f32_16x16x32_bf16 v[62:65], v[174:177], v[158:161], v[62:65]
	v_mfma_f32_16x16x32_bf16 v[58:61], v[174:177], v[166:169], v[58:61]
	s_waitcnt lgkmcnt(5)
	v_mfma_f32_16x16x32_bf16 v[54:57], v[182:185], v[158:161], v[54:57]
	v_mfma_f32_16x16x32_bf16 v[50:53], v[182:185], v[166:169], v[50:53]
	s_waitcnt lgkmcnt(3)
	v_mfma_f32_16x16x32_bf16 v[46:49], v[190:193], v[158:161], v[46:49]
	v_mfma_f32_16x16x32_bf16 v[42:45], v[190:193], v[166:169], v[42:45]
	s_waitcnt lgkmcnt(1)
	v_mfma_f32_16x16x32_bf16 v[38:41], v[198:201], v[158:161], v[38:41]
	v_mfma_f32_16x16x32_bf16 v[34:37], v[198:201], v[166:169], v[34:37]
	v_mfma_f32_16x16x32_bf16 v[62:65], v[178:181], v[162:165], v[62:65]
	v_mfma_f32_16x16x32_bf16 v[58:61], v[178:181], v[170:173], v[58:61]
	v_mfma_f32_16x16x32_bf16 v[54:57], v[186:189], v[162:165], v[54:57]
	v_mfma_f32_16x16x32_bf16 v[50:53], v[186:189], v[170:173], v[50:53]
	v_mfma_f32_16x16x32_bf16 v[46:49], v[194:197], v[162:165], v[46:49]
	v_mfma_f32_16x16x32_bf16 v[42:45], v[194:197], v[170:173], v[42:45]
	s_waitcnt lgkmcnt(0)
	v_mfma_f32_16x16x32_bf16 v[38:41], v[202:205], v[162:165], v[38:41]
	v_mfma_f32_16x16x32_bf16 v[34:37], v[202:205], v[170:173], v[34:37]
	s_barrier
	v_readfirstlane_b32 s3, v144
	s_addk_i32 s15, 0x180
	s_mov_b32 m0, s3
	v_readfirstlane_b32 s3, v147
	buffer_load_dwordx4 v137, s[4:7], s15 offen lds
	s_mov_b32 m0, s3
	s_nop 0
	buffer_load_dwordx4 v138, s[4:7], s15 offen lds
	s_waitcnt vmcnt(6)
	s_barrier
	v_mfma_f32_16x16x32_bf16 v[30:33], v[174:177], v[206:209], v[30:33]
	v_mfma_f32_16x16x32_bf16 v[26:29], v[174:177], v[214:217], v[26:29]
	v_mfma_f32_16x16x32_bf16 v[22:25], v[182:185], v[206:209], v[22:25]
	v_mfma_f32_16x16x32_bf16 v[18:21], v[182:185], v[214:217], v[18:21]
	v_mfma_f32_16x16x32_bf16 v[14:17], v[190:193], v[206:209], v[14:17]
	v_mfma_f32_16x16x32_bf16 v[10:13], v[190:193], v[214:217], v[10:13]
	v_mfma_f32_16x16x32_bf16 v[6:9], v[198:201], v[206:209], v[6:9]
	v_mfma_f32_16x16x32_bf16 v[2:5], v[198:201], v[214:217], v[2:5]
	v_mfma_f32_16x16x32_bf16 v[30:33], v[178:181], v[210:213], v[30:33]
	v_mfma_f32_16x16x32_bf16 v[26:29], v[178:181], v[218:221], v[26:29]
	v_mfma_f32_16x16x32_bf16 v[22:25], v[186:189], v[210:213], v[22:25]
	v_mfma_f32_16x16x32_bf16 v[18:21], v[186:189], v[218:221], v[18:21]
	v_mfma_f32_16x16x32_bf16 v[14:17], v[194:197], v[210:213], v[14:17]
	v_mfma_f32_16x16x32_bf16 v[10:13], v[194:197], v[218:221], v[10:13]
	v_mfma_f32_16x16x32_bf16 v[6:9], v[202:205], v[210:213], v[6:9]
	v_mfma_f32_16x16x32_bf16 v[2:5], v[202:205], v[218:221], v[2:5]
	s_cmp_lt_u32 s2, s29
	s_mov_b32 s3, s14
	s_barrier
	s_cbranch_scc1 .LBB0_565
	v_readfirstlane_b32 s2, v146
	s_mov_b32 m0, s2
	v_readfirstlane_b32 s2, v145
	ds_read_b128 v[140:143], v156
	ds_read_b128 v[150:153], v156 offset:1024
	ds_read_b128 v[158:161], v156 offset:2048
	ds_read_b128 v[154:157], v156 offset:3072
	ds_read_b128 v[162:165], v134
	ds_read_b128 v[166:169], v134 offset:1024
	ds_read_b128 v[170:173], v133
	ds_read_b128 v[174:177], v133 offset:1024
	ds_read_b128 v[178:181], v132
	ds_read_b128 v[182:185], v132 offset:1024
	ds_read_b128 v[186:189], v131
	ds_read_b128 v[190:193], v131 offset:1024
	buffer_load_dwordx4 v137, s[76:79], s30 offen lds
	s_mov_b32 m0, s2
	s_nop 0
	buffer_load_dwordx4 v138, s[76:79], s30 offen lds
	s_barrier
	s_waitcnt lgkmcnt(0)
	s_waitcnt lgkmcnt(7)
	v_mfma_f32_16x16x32_bf16 v[126:129], v[162:165], v[140:143], v[126:129]
	s_waitcnt lgkmcnt(5)
	v_mfma_f32_16x16x32_bf16 v[118:121], v[170:173], v[140:143], v[118:121]
	s_waitcnt lgkmcnt(3)
	v_mfma_f32_16x16x32_bf16 v[110:113], v[178:181], v[140:143], v[110:113]
	s_waitcnt lgkmcnt(1)
	v_mfma_f32_16x16x32_bf16 v[102:105], v[186:189], v[140:143], v[102:105]
	v_mfma_f32_16x16x32_bf16 v[126:129], v[166:169], v[150:153], v[126:129]
	v_mfma_f32_16x16x32_bf16 v[122:125], v[162:165], v[158:161], v[122:125]
	v_mfma_f32_16x16x32_bf16 v[118:121], v[174:177], v[150:153], v[118:121]
	v_mfma_f32_16x16x32_bf16 v[114:117], v[170:173], v[158:161], v[114:117]
	v_mfma_f32_16x16x32_bf16 v[110:113], v[182:185], v[150:153], v[110:113]
	v_mfma_f32_16x16x32_bf16 v[106:109], v[178:181], v[158:161], v[106:109]
	s_waitcnt lgkmcnt(0)
	v_mfma_f32_16x16x32_bf16 v[102:105], v[190:193], v[150:153], v[102:105]
	v_mfma_f32_16x16x32_bf16 v[98:101], v[186:189], v[158:161], v[98:101]
	v_mfma_f32_16x16x32_bf16 v[144:147], v[166:169], v[154:157], v[122:125]
	v_mfma_f32_16x16x32_bf16 v[194:197], v[174:177], v[154:157], v[114:117]
	v_mfma_f32_16x16x32_bf16 v[198:201], v[182:185], v[154:157], v[106:109]
	v_mfma_f32_16x16x32_bf16 v[202:205], v[190:193], v[154:157], v[98:101]
	s_barrier
	s_nop 1
	ds_read_b128 v[98:101], v148
	ds_read_b128 v[106:109], v148 offset:1024
	ds_read_b128 v[114:117], v148 offset:2048
	ds_read_b128 v[122:125], v148 offset:3072
	s_barrier
	s_waitcnt lgkmcnt(0)
	s_waitcnt lgkmcnt(3)
	v_mfma_f32_16x16x32_bf16 v[94:97], v[162:165], v[98:101], v[94:97]
	v_mfma_f32_16x16x32_bf16 v[86:89], v[170:173], v[98:101], v[86:89]
	v_mfma_f32_16x16x32_bf16 v[78:81], v[178:181], v[98:101], v[78:81]
	v_mfma_f32_16x16x32_bf16 v[70:73], v[186:189], v[98:101], v[70:73]
	s_waitcnt lgkmcnt(2)
	v_mfma_f32_16x16x32_bf16 v[94:97], v[166:169], v[106:109], v[94:97]
	s_waitcnt lgkmcnt(1)
	v_mfma_f32_16x16x32_bf16 v[90:93], v[162:165], v[114:117], v[90:93]
	v_mfma_f32_16x16x32_bf16 v[86:89], v[174:177], v[106:109], v[86:89]
	v_mfma_f32_16x16x32_bf16 v[82:85], v[170:173], v[114:117], v[82:85]
	v_mfma_f32_16x16x32_bf16 v[78:81], v[182:185], v[106:109], v[78:81]
	v_mfma_f32_16x16x32_bf16 v[74:77], v[178:181], v[114:117], v[74:77]
	v_mfma_f32_16x16x32_bf16 v[70:73], v[190:193], v[106:109], v[70:73]
	v_mfma_f32_16x16x32_bf16 v[66:69], v[186:189], v[114:117], v[66:69]
	s_waitcnt lgkmcnt(0)
	v_mfma_f32_16x16x32_bf16 v[162:165], v[166:169], v[122:125], v[90:93]
	v_mfma_f32_16x16x32_bf16 v[166:169], v[174:177], v[122:125], v[82:85]
	v_mfma_f32_16x16x32_bf16 v[170:173], v[182:185], v[122:125], v[74:77]
	v_mfma_f32_16x16x32_bf16 v[174:177], v[190:193], v[122:125], v[66:69]
	s_barrier
; #define WAIT_V(n) asm volatile("s_waitcnt vmcnt(" #n ")" ::: "memory")
; #define WAIT_L(n) asm volatile("s_waitcnt lgkmcnt(" #n ")" ::: "memory")
; #define BAR __builtin_amdgcn_s_barrier()
; __device__ __forceinline__ void mainloop_8phase(const u16* __restrict__ A, const u16* __restrict__ Bt, int K,
;                                                 f32x4 (&acc)[2][2][4][2], int wid_s, int ld) {
;     ...
;     LDA(At, 0, 1); WAIT_V(4); BAR; WAIT_L(0); MMA(1, 0, At, B0); MMA(1, 1, At, B1); BAR; }
;   { LDB(B0, 1, 0); LDA(At, 1, 0); WAIT_V(2); BAR; WAIT_L(0); MMA(0, 0, At, B0); BAR;
	s_nop 0
	ds_read_b128 v[66:69], v134 offset:16384
	ds_read_b128 v[74:77], v134 offset:17408
	ds_read_b128 v[82:85], v133 offset:16384
	ds_read_b128 v[90:93], v133 offset:17408
	ds_read_b128 v[178:181], v132 offset:16384
	ds_read_b128 v[182:185], v132 offset:17408
	ds_read_b128 v[186:189], v131 offset:16384
	ds_read_b128 v[190:193], v131 offset:17408
	s_waitcnt vmcnt(4)
	s_barrier
	s_waitcnt lgkmcnt(0)
	s_waitcnt lgkmcnt(7)
	v_mfma_f32_16x16x32_bf16 v[62:65], v[66:69], v[140:143], v[62:65]
	s_waitcnt lgkmcnt(5)
	v_mfma_f32_16x16x32_bf16 v[54:57], v[82:85], v[140:143], v[54:57]
	s_waitcnt lgkmcnt(3)
	v_mfma_f32_16x16x32_bf16 v[46:49], v[178:181], v[140:143], v[46:49]
	s_waitcnt lgkmcnt(1)
	v_mfma_f32_16x16x32_bf16 v[38:41], v[186:189], v[140:143], v[38:41]
	v_mfma_f32_16x16x32_bf16 v[62:65], v[74:77], v[150:153], v[62:65]
	v_mfma_f32_16x16x32_bf16 v[58:61], v[66:69], v[158:161], v[58:61]
	v_mfma_f32_16x16x32_bf16 v[54:57], v[90:93], v[150:153], v[54:57]
	v_mfma_f32_16x16x32_bf16 v[50:53], v[82:85], v[158:161], v[50:53]
	v_mfma_f32_16x16x32_bf16 v[46:49], v[182:185], v[150:153], v[46:49]
	v_mfma_f32_16x16x32_bf16 v[42:45], v[178:181], v[158:161], v[42:45]
	s_waitcnt lgkmcnt(0)
	v_mfma_f32_16x16x32_bf16 v[38:41], v[190:193], v[150:153], v[38:41]
	v_mfma_f32_16x16x32_bf16 v[34:37], v[186:189], v[158:161], v[34:37]
	v_mfma_f32_16x16x32_bf16 v[206:209], v[74:77], v[154:157], v[58:61]
	v_mfma_f32_16x16x32_bf16 v[210:213], v[90:93], v[154:157], v[50:53]
	v_mfma_f32_16x16x32_bf16 v[214:217], v[182:185], v[154:157], v[42:45]
	v_mfma_f32_16x16x32_bf16 v[138:141], v[190:193], v[154:157], v[34:37]
	v_mfma_f32_16x16x32_bf16 v[30:33], v[66:69], v[98:101], v[30:33]
	v_mfma_f32_16x16x32_bf16 v[22:25], v[82:85], v[98:101], v[22:25]
	v_mfma_f32_16x16x32_bf16 v[14:17], v[178:181], v[98:101], v[14:17]
	v_mfma_f32_16x16x32_bf16 v[6:9], v[186:189], v[98:101], v[6:9]
	v_mfma_f32_16x16x32_bf16 v[30:33], v[74:77], v[106:109], v[30:33]
	v_mfma_f32_16x16x32_bf16 v[26:29], v[66:69], v[114:117], v[26:29]
	v_mfma_f32_16x16x32_bf16 v[22:25], v[90:93], v[106:109], v[22:25]
	v_mfma_f32_16x16x32_bf16 v[18:21], v[82:85], v[114:117], v[18:21]
	v_mfma_f32_16x16x32_bf16 v[14:17], v[182:185], v[106:109], v[14:17]
	v_mfma_f32_16x16x32_bf16 v[10:13], v[178:181], v[114:117], v[10:13]
	v_mfma_f32_16x16x32_bf16 v[6:9], v[190:193], v[106:109], v[6:9]
	v_mfma_f32_16x16x32_bf16 v[2:5], v[186:189], v[114:117], v[2:5]
	v_mfma_f32_16x16x32_bf16 v[148:151], v[74:77], v[122:125], v[26:29]
	v_mfma_f32_16x16x32_bf16 v[152:155], v[90:93], v[122:125], v[18:21]
	v_mfma_f32_16x16x32_bf16 v[156:159], v[182:185], v[122:125], v[10:13]
	v_mfma_f32_16x16x32_bf16 v[178:181], v[190:193], v[122:125], v[2:5]
	s_barrier
	s_nop 1
	ds_read_b128 v[2:5], v136
	ds_read_b128 v[10:13], v136 offset:1024
	ds_read_b128 v[18:21], v136 offset:2048
	ds_read_b128 v[26:29], v136 offset:3072
	ds_read_b128 v[34:37], v134 offset:32768
	ds_read_b128 v[42:45], v134 offset:33792
	ds_read_b128 v[50:53], v133 offset:32768
	ds_read_b128 v[58:61], v133 offset:33792
	ds_read_b128 v[66:69], v132 offset:32768
	ds_read_b128 v[182:185], v132 offset:33792
	ds_read_b128 v[186:189], v131 offset:32768
	ds_read_b128 v[190:193], v131 offset:33792
	s_waitcnt vmcnt(2)
	s_barrier
	s_waitcnt lgkmcnt(0)
	s_waitcnt lgkmcnt(7)
	v_mfma_f32_16x16x32_bf16 v[74:77], v[34:37], v[2:5], v[126:129]
	s_waitcnt lgkmcnt(6)
	v_mfma_f32_16x16x32_bf16 v[122:125], v[42:45], v[10:13], v[74:77]
	v_mfma_f32_16x16x32_bf16 v[74:77], v[34:37], v[18:21], v[144:147]
	v_mfma_f32_16x16x32_bf16 v[126:129], v[42:45], v[26:29], v[74:77]
	s_waitcnt lgkmcnt(5)
	v_mfma_f32_16x16x32_bf16 v[74:77], v[50:53], v[2:5], v[118:121]
	s_waitcnt lgkmcnt(4)
	v_mfma_f32_16x16x32_bf16 v[114:117], v[58:61], v[10:13], v[74:77]
	v_mfma_f32_16x16x32_bf16 v[74:77], v[50:53], v[18:21], v[194:197]
	v_mfma_f32_16x16x32_bf16 v[118:121], v[58:61], v[26:29], v[74:77]
	s_waitcnt lgkmcnt(3)
	v_mfma_f32_16x16x32_bf16 v[74:77], v[66:69], v[2:5], v[110:113]
	s_waitcnt lgkmcnt(2)
	v_mfma_f32_16x16x32_bf16 v[106:109], v[182:185], v[10:13], v[74:77]
	v_mfma_f32_16x16x32_bf16 v[74:77], v[66:69], v[18:21], v[198:201]
	v_mfma_f32_16x16x32_bf16 v[110:113], v[182:185], v[26:29], v[74:77]
	s_waitcnt lgkmcnt(1)
	v_mfma_f32_16x16x32_bf16 v[74:77], v[186:189], v[2:5], v[102:105]
	s_waitcnt lgkmcnt(0)
	v_mfma_f32_16x16x32_bf16 v[98:101], v[190:193], v[10:13], v[74:77]
	v_mfma_f32_16x16x32_bf16 v[74:77], v[186:189], v[18:21], v[202:205]
	v_mfma_f32_16x16x32_bf16 v[102:105], v[190:193], v[26:29], v[74:77]
	s_barrier
; #define WAIT_V(n) asm volatile("s_waitcnt vmcnt(" #n ")" ::: "memory")
; #define WAIT_L(n) asm volatile("s_waitcnt lgkmcnt(" #n ")" ::: "memory")
; #define BAR __builtin_amdgcn_s_barrier()
; __device__ __forceinline__ void mainloop_8phase(const u16* __restrict__ A, const u16* __restrict__ Bt, int K,
;                                                 f32x4 (&acc)[2][2][4][2], int wid_s, int ld) {
;     ...
;     LDB(B1, 1, 1); WAIT_V(0); BAR; WAIT_L(0); MMA(0, 1, At, B1); BAR;
;     LDA(At, 1, 1); BAR; WAIT_L(0); MMA(1, 0, At, B0); MMA(1, 1, At, B1); BAR; }
;   if (wr == 0) BAR;
	ds_read_b128 v[142:145], v135
	ds_read_b128 v[194:197], v135 offset:1024
	ds_read_b128 v[198:201], v135 offset:2048
	ds_read_b128 v[202:205], v135 offset:3072
	s_waitcnt vmcnt(0)
	s_barrier
	s_waitcnt lgkmcnt(0)
	s_waitcnt lgkmcnt(3)
	v_mfma_f32_16x16x32_bf16 v[74:77], v[34:37], v[142:145], v[94:97]
	s_waitcnt lgkmcnt(1)
	v_mfma_f32_16x16x32_bf16 v[34:37], v[34:37], v[198:201], v[162:165]
	s_waitcnt lgkmcnt(0)
	v_mfma_f32_16x16x32_bf16 v[94:97], v[42:45], v[202:205], v[34:37]
	v_mfma_f32_16x16x32_bf16 v[34:37], v[50:53], v[142:145], v[86:89]
	v_mfma_f32_16x16x32_bf16 v[82:85], v[58:61], v[194:197], v[34:37]
	v_mfma_f32_16x16x32_bf16 v[34:37], v[50:53], v[198:201], v[166:169]
	v_mfma_f32_16x16x32_bf16 v[86:89], v[58:61], v[202:205], v[34:37]
	v_mfma_f32_16x16x32_bf16 v[34:37], v[66:69], v[142:145], v[78:81]
	v_mfma_f32_16x16x32_bf16 v[90:93], v[42:45], v[194:197], v[74:77]
	v_mfma_f32_16x16x32_bf16 v[74:77], v[182:185], v[194:197], v[34:37]
	v_mfma_f32_16x16x32_bf16 v[34:37], v[66:69], v[198:201], v[170:173]
	v_mfma_f32_16x16x32_bf16 v[78:81], v[182:185], v[202:205], v[34:37]
	v_mfma_f32_16x16x32_bf16 v[34:37], v[186:189], v[142:145], v[70:73]
	v_mfma_f32_16x16x32_bf16 v[66:69], v[190:193], v[194:197], v[34:37]
	v_mfma_f32_16x16x32_bf16 v[34:37], v[186:189], v[198:201], v[174:177]
	v_mfma_f32_16x16x32_bf16 v[70:73], v[190:193], v[202:205], v[34:37]
	s_barrier
	ds_read_b128 v[160:163], v134 offset:49152
	ds_read_b128 v[134:137], v134 offset:50176
	ds_read_b128 v[164:167], v133 offset:49152
	ds_read_b128 v[168:171], v133 offset:50176
	ds_read_b128 v[172:175], v132 offset:49152
	ds_read_b128 v[182:185], v132 offset:50176
	ds_read_b128 v[186:189], v131 offset:49152
	ds_read_b128 v[190:193], v131 offset:50176
	s_barrier
	s_waitcnt lgkmcnt(0)
	s_waitcnt lgkmcnt(7)
	v_mfma_f32_16x16x32_bf16 v[34:37], v[160:163], v[2:5], v[62:65]
	s_waitcnt lgkmcnt(6)
	v_mfma_f32_16x16x32_bf16 v[58:61], v[134:137], v[10:13], v[34:37]
	v_mfma_f32_16x16x32_bf16 v[34:37], v[160:163], v[18:21], v[206:209]
	v_mfma_f32_16x16x32_bf16 v[62:65], v[134:137], v[26:29], v[34:37]
	s_waitcnt lgkmcnt(5)
	v_mfma_f32_16x16x32_bf16 v[34:37], v[164:167], v[2:5], v[54:57]
	s_waitcnt lgkmcnt(4)
	v_mfma_f32_16x16x32_bf16 v[50:53], v[168:171], v[10:13], v[34:37]
	v_mfma_f32_16x16x32_bf16 v[34:37], v[164:167], v[18:21], v[210:213]
	v_mfma_f32_16x16x32_bf16 v[54:57], v[168:171], v[26:29], v[34:37]
	s_waitcnt lgkmcnt(3)
	v_mfma_f32_16x16x32_bf16 v[34:37], v[172:175], v[2:5], v[46:49]
	s_waitcnt lgkmcnt(2)
	v_mfma_f32_16x16x32_bf16 v[42:45], v[182:185], v[10:13], v[34:37]
	v_mfma_f32_16x16x32_bf16 v[34:37], v[172:175], v[18:21], v[214:217]
	s_waitcnt lgkmcnt(1)
	v_mfma_f32_16x16x32_bf16 v[2:5], v[186:189], v[2:5], v[38:41]
	v_mfma_f32_16x16x32_bf16 v[46:49], v[182:185], v[26:29], v[34:37]
	s_waitcnt lgkmcnt(0)
	v_mfma_f32_16x16x32_bf16 v[34:37], v[190:193], v[10:13], v[2:5]
	v_mfma_f32_16x16x32_bf16 v[2:5], v[186:189], v[18:21], v[138:141]
	v_mfma_f32_16x16x32_bf16 v[38:41], v[190:193], v[26:29], v[2:5]
	v_mfma_f32_16x16x32_bf16 v[2:5], v[160:163], v[142:145], v[30:33]
	v_mfma_f32_16x16x32_bf16 v[26:29], v[134:137], v[194:197], v[2:5]
	v_mfma_f32_16x16x32_bf16 v[2:5], v[160:163], v[198:201], v[148:151]
	v_mfma_f32_16x16x32_bf16 v[30:33], v[134:137], v[202:205], v[2:5]
	v_mfma_f32_16x16x32_bf16 v[2:5], v[164:167], v[142:145], v[22:25]
	v_mfma_f32_16x16x32_bf16 v[18:21], v[168:171], v[194:197], v[2:5]
	v_mfma_f32_16x16x32_bf16 v[2:5], v[164:167], v[198:201], v[152:155]
	v_mfma_f32_16x16x32_bf16 v[22:25], v[168:171], v[202:205], v[2:5]
	v_mfma_f32_16x16x32_bf16 v[2:5], v[172:175], v[142:145], v[14:17]
	v_mfma_f32_16x16x32_bf16 v[10:13], v[182:185], v[194:197], v[2:5]
	v_mfma_f32_16x16x32_bf16 v[2:5], v[172:175], v[198:201], v[156:159]
	v_mfma_f32_16x16x32_bf16 v[14:17], v[182:185], v[202:205], v[2:5]
	v_mfma_f32_16x16x32_bf16 v[2:5], v[186:189], v[142:145], v[6:9]
	v_mfma_f32_16x16x32_bf16 v[6:9], v[186:189], v[198:201], v[178:181]
	v_mfma_f32_16x16x32_bf16 v[2:5], v[190:193], v[194:197], v[2:5]
	v_mfma_f32_16x16x32_bf16 v[6:9], v[190:193], v[202:205], v[6:9]
	s_movk_i32 s2, 0x100
	v_cmp_gt_u32_e32 vcc, s2, v0
	s_barrier
	s_and_saveexec_b64 s[2:3], vcc
	s_cbranch_execz .LBB0_568
	s_barrier
